# attention-rpb-bias-from-per-wave-LDS-table-batched-no-serialized-global-loads
# speedup vs baseline: 1.1648x; 1.0601x over previous
.LBB0_41:
	s_nop 1
	v_accvgpr_read_b32 v191, a63
	v_or_b32_e32 v192, s4, v192
	v_cmp_lt_i32_e32 vcc, v211, v210
	v_mfma_f32_32x32x16_bf16 a[32:47], v[198:201], v[40:43], a[32:47]
	v_accvgpr_read_b32 v176, a48
	v_accvgpr_read_b32 v177, a49
	v_accvgpr_read_b32 v178, a50
	v_accvgpr_read_b32 v179, a51
	v_accvgpr_read_b32 v180, a52
	v_accvgpr_read_b32 v181, a53
	v_accvgpr_read_b32 v182, a54
	v_mfma_f32_32x32x16_bf16 a[16:31], v[198:201], v[36:39], a[16:31]
	v_accvgpr_read_b32 v183, a55
	v_accvgpr_read_b32 v184, a56
	v_accvgpr_read_b32 v185, a57
	v_accvgpr_read_b32 v186, a58
	v_accvgpr_read_b32 v187, a59
	v_accvgpr_read_b32 v188, a60
	v_accvgpr_read_b32 v189, a61
	v_mfma_f32_32x32x16_bf16 a[0:15], v[198:201], v[194:197], a[0:15]
	v_add_u32_e32 v198, v205, v192
	v_cndmask_b32_e32 v192, v209, v211, vcc
	v_lshlrev_b32_e32 v194, 2, v192
	v_cvt_pk_bf16_f32 v176, v176, v177
	v_cvt_pk_bf16_f32 v177, v178, v179
	v_cvt_pk_bf16_f32 v192, v180, v181
	v_cvt_pk_bf16_f32 v183, v182, v183
	v_cvt_pk_bf16_f32 v180, v184, v185
	v_cvt_pk_bf16_f32 v181, v186, v187
	v_cvt_pk_bf16_f32 v184, v188, v189
	v_accvgpr_read_b32 v190, a62
	v_cvt_pk_bf16_f32 v185, v190, v191
	v_and_b32_e32 v178, 63, v203
	v_cmp_gt_u32_e32 vcc, 32, v178
	v_or_b32_e32 v196, s1, v204
	v_ashrrev_i32_e32 v199, 31, v198
	v_cndmask_b32_e32 v178, v176, v180, vcc
	v_cndmask_b32_e32 v179, v177, v181, vcc
	ds_bpermute_b32 v186, v194, v178
	ds_bpermute_b32 v187, v194, v179
	v_cndmask_b32_e32 v182, v192, v184, vcc
	ds_bpermute_b32 v188, v194, v182
	v_cndmask_b32_e32 v178, v183, v185, vcc
	ds_bpermute_b32 v189, v194, v178
	v_readlane_b32 s4, v253, 43
	v_ashrrev_i32_e32 v197, 31, v196
	s_waitcnt lgkmcnt(3)
	v_cndmask_b32_e32 v178, v186, v176, vcc
	s_waitcnt lgkmcnt(2)
	v_cndmask_b32_e32 v179, v187, v177, vcc
	v_lshlrev_b64 v[176:177], 11, v[198:199]
	v_readlane_b32 s5, v253, 44
	v_cndmask_b32_e32 v180, v180, v186, vcc
	v_cndmask_b32_e32 v181, v181, v187, vcc
	v_lshl_add_u64 v[176:177], s[4:5], 0, v[176:177]
	v_lshlrev_b64 v[186:187], 1, v[196:197]
	v_accvgpr_read_b32 v175, a79
	s_waitcnt lgkmcnt(1)
	v_cndmask_b32_e32 v182, v188, v192, vcc
	v_lshl_add_u64 v[176:177], v[176:177], 0, v[186:187]
	v_and_b32_e32 v192, 32, v203
	v_accvgpr_read_b32 v160, a64
	v_lshl_add_u64 v[176:177], v[176:177], 0, v[192:193]
	v_accvgpr_read_b32 v161, a65
	s_waitcnt lgkmcnt(0)
	v_cndmask_b32_e32 v183, v189, v183, vcc
	v_cndmask_b32_e32 v184, v184, v188, vcc
	v_cndmask_b32_e32 v185, v185, v189, vcc
	global_store_dwordx4 v[176:177], v[178:181], off
	global_store_dwordx4 v[176:177], v[182:185], off offset:16
	v_accvgpr_read_b32 v162, a66
	v_cvt_pk_bf16_f32 v161, v160, v161
	v_accvgpr_read_b32 v163, a67
	v_cvt_pk_bf16_f32 v163, v162, v163
	v_accvgpr_read_b32 v164, a68
	v_accvgpr_read_b32 v165, a69
	v_cvt_pk_bf16_f32 v178, v164, v165
	v_accvgpr_read_b32 v166, a70
	v_accvgpr_read_b32 v167, a71
	v_cvt_pk_bf16_f32 v167, v166, v167
	v_accvgpr_read_b32 v168, a72
	v_accvgpr_read_b32 v169, a73
	v_cvt_pk_bf16_f32 v164, v168, v169
	v_accvgpr_read_b32 v170, a74
	v_accvgpr_read_b32 v171, a75
	v_cvt_pk_bf16_f32 v165, v170, v171
	v_accvgpr_read_b32 v172, a76
	v_accvgpr_read_b32 v173, a77
	v_cvt_pk_bf16_f32 v168, v172, v173
	v_accvgpr_read_b32 v174, a78
	v_cvt_pk_bf16_f32 v169, v174, v175
	v_cndmask_b32_e32 v162, v161, v164, vcc
	ds_bpermute_b32 v171, v194, v162
	v_cndmask_b32_e32 v166, v163, v165, vcc
	v_add_u32_e32 v160, 32, v198
	v_cndmask_b32_e32 v170, v178, v168, vcc
	ds_bpermute_b32 v166, v194, v166
	v_cndmask_b32_e32 v162, v167, v169, vcc
	ds_bpermute_b32 v170, v194, v170
	ds_bpermute_b32 v172, v194, v162
	s_waitcnt lgkmcnt(3)
	v_cndmask_b32_e32 v162, v171, v161, vcc
	v_ashrrev_i32_e32 v161, 31, v160
	v_lshlrev_b64 v[160:161], 11, v[160:161]
	v_lshl_add_u64 v[160:161], s[4:5], 0, v[160:161]
	v_accvgpr_read_b32 v159, a95
	v_lshl_add_u64 v[160:161], v[160:161], 0, v[186:187]
	v_accvgpr_read_b32 v144, a80
	s_waitcnt lgkmcnt(2)
	v_cndmask_b32_e32 v163, v166, v163, vcc
	v_cndmask_b32_e32 v164, v164, v171, vcc
	v_cndmask_b32_e32 v165, v165, v166, vcc
	v_lshl_add_u64 v[160:161], v[160:161], 0, v[192:193]
	v_accvgpr_read_b32 v145, a81
	s_waitcnt lgkmcnt(1)
	v_cndmask_b32_e32 v166, v170, v178, vcc
	s_waitcnt lgkmcnt(0)
	v_cndmask_b32_e32 v167, v172, v167, vcc
	v_cndmask_b32_e32 v168, v168, v170, vcc
	v_cndmask_b32_e32 v169, v169, v172, vcc
	global_store_dwordx4 v[160:161], v[162:165], off
	global_store_dwordx4 v[160:161], v[166:169], off offset:16
	v_accvgpr_read_b32 v146, a82
	v_cvt_pk_bf16_f32 v145, v144, v145
	v_accvgpr_read_b32 v147, a83
	v_cvt_pk_bf16_f32 v147, v146, v147
	v_accvgpr_read_b32 v148, a84
	v_accvgpr_read_b32 v149, a85
	v_cvt_pk_bf16_f32 v162, v148, v149
	v_accvgpr_read_b32 v150, a86
	v_accvgpr_read_b32 v151, a87
	v_cvt_pk_bf16_f32 v151, v150, v151
	v_accvgpr_read_b32 v152, a88
	v_accvgpr_read_b32 v153, a89
	v_cvt_pk_bf16_f32 v148, v152, v153
	v_accvgpr_read_b32 v154, a90
	v_accvgpr_read_b32 v155, a91
	v_cvt_pk_bf16_f32 v149, v154, v155
	v_accvgpr_read_b32 v156, a92
	v_accvgpr_read_b32 v157, a93
	v_cvt_pk_bf16_f32 v152, v156, v157
	v_accvgpr_read_b32 v158, a94
	v_cvt_pk_bf16_f32 v153, v158, v159
	v_cndmask_b32_e32 v146, v145, v148, vcc
	ds_bpermute_b32 v155, v194, v146
	v_cndmask_b32_e32 v150, v147, v149, vcc
	v_add_u32_e32 v144, 64, v198
	v_cndmask_b32_e32 v154, v162, v152, vcc
	ds_bpermute_b32 v150, v194, v150
	v_cndmask_b32_e32 v146, v151, v153, vcc
	ds_bpermute_b32 v154, v194, v154
	ds_bpermute_b32 v156, v194, v146
	s_waitcnt lgkmcnt(3)
	v_cndmask_b32_e32 v146, v155, v145, vcc
	v_ashrrev_i32_e32 v145, 31, v144
	v_lshlrev_b64 v[144:145], 11, v[144:145]
	v_lshl_add_u64 v[144:145], s[4:5], 0, v[144:145]
	v_accvgpr_read_b32 v143, a111
	v_lshl_add_u64 v[144:145], v[144:145], 0, v[186:187]
	v_accvgpr_read_b32 v128, a96
	s_waitcnt lgkmcnt(2)
	v_cndmask_b32_e32 v147, v150, v147, vcc
	v_cndmask_b32_e32 v148, v148, v155, vcc
	v_cndmask_b32_e32 v149, v149, v150, vcc
	v_lshl_add_u64 v[144:145], v[144:145], 0, v[192:193]
	v_accvgpr_read_b32 v129, a97
	s_waitcnt lgkmcnt(1)
	v_cndmask_b32_e32 v150, v154, v162, vcc
	s_waitcnt lgkmcnt(0)
	v_cndmask_b32_e32 v151, v156, v151, vcc
	v_cndmask_b32_e32 v152, v152, v154, vcc
	v_cndmask_b32_e32 v153, v153, v156, vcc
	global_store_dwordx4 v[144:145], v[146:149], off
	global_store_dwordx4 v[144:145], v[150:153], off offset:16
	v_accvgpr_read_b32 v130, a98
	v_cvt_pk_bf16_f32 v128, v128, v129
	v_accvgpr_read_b32 v131, a99
	v_cvt_pk_bf16_f32 v129, v130, v131
	v_accvgpr_read_b32 v132, a100
	v_accvgpr_read_b32 v133, a101
	v_cvt_pk_bf16_f32 v132, v132, v133
	v_accvgpr_read_b32 v134, a102
	v_accvgpr_read_b32 v135, a103
	v_cvt_pk_bf16_f32 v133, v134, v135
	v_accvgpr_read_b32 v136, a104
	v_accvgpr_read_b32 v137, a105
	v_cvt_pk_bf16_f32 v130, v136, v137
	v_accvgpr_read_b32 v138, a106
	v_accvgpr_read_b32 v139, a107
	v_cvt_pk_bf16_f32 v131, v138, v139
	v_accvgpr_read_b32 v140, a108
	v_accvgpr_read_b32 v141, a109
	v_cvt_pk_bf16_f32 v134, v140, v141
	v_accvgpr_read_b32 v142, a110
	v_cvt_pk_bf16_f32 v135, v142, v143
	v_cndmask_b32_e32 v136, v128, v130, vcc
	v_cndmask_b32_e32 v137, v129, v131, vcc
	v_cndmask_b32_e32 v138, v132, v134, vcc
	ds_bpermute_b32 v136, v194, v136
	ds_bpermute_b32 v137, v194, v137
	v_cndmask_b32_e32 v139, v133, v135, vcc
	ds_bpermute_b32 v138, v194, v138
	ds_bpermute_b32 v139, v194, v139
	v_accvgpr_read_b32 v112, a112
	s_waitcnt lgkmcnt(3)
	v_cndmask_b32_e32 v128, v136, v128, vcc
	s_waitcnt lgkmcnt(2)
	v_cndmask_b32_e32 v129, v137, v129, vcc
	v_cndmask_b32_e32 v130, v130, v136, vcc
	v_cndmask_b32_e32 v131, v131, v137, vcc
	v_accvgpr_read_b32 v113, a113
	s_waitcnt lgkmcnt(1)
	v_cndmask_b32_e32 v132, v138, v132, vcc
	s_waitcnt lgkmcnt(0)
	v_cndmask_b32_e32 v133, v139, v133, vcc
	v_cndmask_b32_e32 v134, v134, v138, vcc
	v_cndmask_b32_e32 v135, v135, v139, vcc
	global_store_dwordx4 v[176:177], v[128:131], off offset:64
	global_store_dwordx4 v[176:177], v[132:135], off offset:80
	v_accvgpr_read_b32 v114, a114
	v_cvt_pk_bf16_f32 v112, v112, v113
	v_accvgpr_read_b32 v115, a115
	v_cvt_pk_bf16_f32 v113, v114, v115
	v_accvgpr_read_b32 v116, a116
	v_accvgpr_read_b32 v117, a117
	v_cvt_pk_bf16_f32 v116, v116, v117
	v_accvgpr_read_b32 v118, a118
	v_accvgpr_read_b32 v119, a119
	v_cvt_pk_bf16_f32 v117, v118, v119
	v_accvgpr_read_b32 v120, a120
	v_accvgpr_read_b32 v121, a121
	v_cvt_pk_bf16_f32 v114, v120, v121
	v_accvgpr_read_b32 v122, a122
	v_accvgpr_read_b32 v123, a123
	v_cvt_pk_bf16_f32 v115, v122, v123
	v_accvgpr_read_b32 v124, a124
	v_accvgpr_read_b32 v125, a125
	v_cvt_pk_bf16_f32 v118, v124, v125
	v_accvgpr_read_b32 v126, a126
	v_accvgpr_read_b32 v127, a127
	v_cvt_pk_bf16_f32 v119, v126, v127
	v_cndmask_b32_e32 v120, v112, v114, vcc
	v_cndmask_b32_e32 v121, v113, v115, vcc
	v_cndmask_b32_e32 v122, v116, v118, vcc
	ds_bpermute_b32 v120, v194, v120
	ds_bpermute_b32 v121, v194, v121
	v_cndmask_b32_e32 v123, v117, v119, vcc
	ds_bpermute_b32 v122, v194, v122
	ds_bpermute_b32 v123, v194, v123
	v_accvgpr_read_b32 v96, a128
	s_waitcnt lgkmcnt(3)
	v_cndmask_b32_e32 v112, v120, v112, vcc
	s_waitcnt lgkmcnt(2)
	v_cndmask_b32_e32 v113, v121, v113, vcc
	v_cndmask_b32_e32 v114, v114, v120, vcc
	v_cndmask_b32_e32 v115, v115, v121, vcc
	v_accvgpr_read_b32 v97, a129
	s_waitcnt lgkmcnt(1)
	v_cndmask_b32_e32 v116, v122, v116, vcc
	s_waitcnt lgkmcnt(0)
	v_cndmask_b32_e32 v117, v123, v117, vcc
	v_cndmask_b32_e32 v118, v118, v122, vcc
	v_cndmask_b32_e32 v119, v119, v123, vcc
	global_store_dwordx4 v[160:161], v[112:115], off offset:64
	global_store_dwordx4 v[160:161], v[116:119], off offset:80
	v_accvgpr_read_b32 v98, a130
	v_cvt_pk_bf16_f32 v96, v96, v97
	v_accvgpr_read_b32 v99, a131
	v_cvt_pk_bf16_f32 v97, v98, v99
	v_accvgpr_read_b32 v100, a132
	v_accvgpr_read_b32 v101, a133
	v_cvt_pk_bf16_f32 v100, v100, v101
	v_accvgpr_read_b32 v102, a134
	v_accvgpr_read_b32 v103, a135
	v_cvt_pk_bf16_f32 v101, v102, v103
	v_accvgpr_read_b32 v104, a136
	v_accvgpr_read_b32 v105, a137
	v_cvt_pk_bf16_f32 v98, v104, v105
	v_accvgpr_read_b32 v106, a138
	v_accvgpr_read_b32 v107, a139
	v_cvt_pk_bf16_f32 v99, v106, v107
	v_accvgpr_read_b32 v108, a140
	v_accvgpr_read_b32 v109, a141
	v_cvt_pk_bf16_f32 v102, v108, v109
	v_accvgpr_read_b32 v110, a142
	v_accvgpr_read_b32 v111, a143
	v_cvt_pk_bf16_f32 v103, v110, v111
	v_cndmask_b32_e32 v104, v96, v98, vcc
	v_cndmask_b32_e32 v105, v97, v99, vcc
	v_cndmask_b32_e32 v106, v100, v102, vcc
	ds_bpermute_b32 v104, v194, v104
	ds_bpermute_b32 v105, v194, v105
	v_cndmask_b32_e32 v107, v101, v103, vcc
	ds_bpermute_b32 v106, v194, v106
	ds_bpermute_b32 v107, v194, v107
	v_accvgpr_read_b32 v80, a144
	s_waitcnt lgkmcnt(3)
	v_cndmask_b32_e32 v96, v104, v96, vcc
	s_waitcnt lgkmcnt(2)
	v_cndmask_b32_e32 v97, v105, v97, vcc
	v_cndmask_b32_e32 v98, v98, v104, vcc
	v_cndmask_b32_e32 v99, v99, v105, vcc
	v_accvgpr_read_b32 v81, a145
	s_waitcnt lgkmcnt(1)
	v_cndmask_b32_e32 v100, v106, v100, vcc
	s_waitcnt lgkmcnt(0)
	v_cndmask_b32_e32 v101, v107, v101, vcc
	v_cndmask_b32_e32 v102, v102, v106, vcc
	v_cndmask_b32_e32 v103, v103, v107, vcc
	global_store_dwordx4 v[144:145], v[96:99], off offset:64
	global_store_dwordx4 v[144:145], v[100:103], off offset:80
	v_accvgpr_read_b32 v82, a146
	v_cvt_pk_bf16_f32 v80, v80, v81
	v_accvgpr_read_b32 v83, a147
	v_cvt_pk_bf16_f32 v81, v82, v83
	v_accvgpr_read_b32 v84, a148
	v_accvgpr_read_b32 v85, a149
	v_cvt_pk_bf16_f32 v84, v84, v85
	v_accvgpr_read_b32 v86, a150
	v_accvgpr_read_b32 v87, a151
	v_cvt_pk_bf16_f32 v85, v86, v87
	v_accvgpr_read_b32 v88, a152
	v_accvgpr_read_b32 v89, a153
	v_cvt_pk_bf16_f32 v82, v88, v89
	v_accvgpr_read_b32 v90, a154
	v_accvgpr_read_b32 v91, a155
	v_cvt_pk_bf16_f32 v83, v90, v91
	v_accvgpr_read_b32 v92, a156
	v_accvgpr_read_b32 v93, a157
	v_cvt_pk_bf16_f32 v86, v92, v93
	v_accvgpr_read_b32 v94, a158
	v_accvgpr_read_b32 v95, a159
	v_cvt_pk_bf16_f32 v87, v94, v95
	v_cndmask_b32_e32 v88, v80, v82, vcc
	v_cndmask_b32_e32 v89, v81, v83, vcc
	v_cndmask_b32_e32 v90, v84, v86, vcc
	ds_bpermute_b32 v88, v194, v88
	ds_bpermute_b32 v89, v194, v89
	v_cndmask_b32_e32 v91, v85, v87, vcc
	ds_bpermute_b32 v90, v194, v90
	ds_bpermute_b32 v91, v194, v91
	v_accvgpr_read_b32 v64, a160
	s_waitcnt lgkmcnt(3)
	v_cndmask_b32_e32 v80, v88, v80, vcc
	s_waitcnt lgkmcnt(2)
	v_cndmask_b32_e32 v81, v89, v81, vcc
	v_cndmask_b32_e32 v82, v82, v88, vcc
	v_cndmask_b32_e32 v83, v83, v89, vcc
	v_accvgpr_read_b32 v65, a161
	s_waitcnt lgkmcnt(1)
	v_cndmask_b32_e32 v84, v90, v84, vcc
	s_waitcnt lgkmcnt(0)
	v_cndmask_b32_e32 v85, v91, v85, vcc
	v_cndmask_b32_e32 v86, v86, v90, vcc
	v_cndmask_b32_e32 v87, v87, v91, vcc
	global_store_dwordx4 v[176:177], v[80:83], off offset:128
	global_store_dwordx4 v[176:177], v[84:87], off offset:144
	v_accvgpr_read_b32 v66, a162
	v_cvt_pk_bf16_f32 v64, v64, v65
	v_accvgpr_read_b32 v67, a163
	v_cvt_pk_bf16_f32 v65, v66, v67
	v_accvgpr_read_b32 v68, a164
	v_accvgpr_read_b32 v69, a165
	v_cvt_pk_bf16_f32 v68, v68, v69
	v_accvgpr_read_b32 v70, a166
	v_accvgpr_read_b32 v71, a167
	v_cvt_pk_bf16_f32 v69, v70, v71
	v_accvgpr_read_b32 v72, a168
	v_accvgpr_read_b32 v73, a169
	v_cvt_pk_bf16_f32 v66, v72, v73
	v_accvgpr_read_b32 v74, a170
	v_accvgpr_read_b32 v75, a171
	v_cvt_pk_bf16_f32 v67, v74, v75
	v_accvgpr_read_b32 v76, a172
	v_accvgpr_read_b32 v77, a173
	v_cvt_pk_bf16_f32 v70, v76, v77
	v_accvgpr_read_b32 v78, a174
	v_accvgpr_read_b32 v79, a175
	v_cvt_pk_bf16_f32 v71, v78, v79
	v_cndmask_b32_e32 v72, v64, v66, vcc
	v_cndmask_b32_e32 v73, v65, v67, vcc
	v_cndmask_b32_e32 v74, v68, v70, vcc
	ds_bpermute_b32 v72, v194, v72
	ds_bpermute_b32 v73, v194, v73
	v_cndmask_b32_e32 v75, v69, v71, vcc
	ds_bpermute_b32 v74, v194, v74
	ds_bpermute_b32 v75, v194, v75
	v_accvgpr_read_b32 v48, a176
	s_waitcnt lgkmcnt(3)
	v_cndmask_b32_e32 v64, v72, v64, vcc
	s_waitcnt lgkmcnt(2)
	v_cndmask_b32_e32 v65, v73, v65, vcc
	v_cndmask_b32_e32 v66, v66, v72, vcc
	v_cndmask_b32_e32 v67, v67, v73, vcc
	v_accvgpr_read_b32 v49, a177
	s_waitcnt lgkmcnt(1)
	v_cndmask_b32_e32 v68, v74, v68, vcc
	s_waitcnt lgkmcnt(0)
	v_cndmask_b32_e32 v69, v75, v69, vcc
	v_cndmask_b32_e32 v70, v70, v74, vcc
	v_cndmask_b32_e32 v71, v71, v75, vcc
	global_store_dwordx4 v[160:161], v[64:67], off offset:128
	global_store_dwordx4 v[160:161], v[68:71], off offset:144
	v_accvgpr_read_b32 v50, a178
	v_cvt_pk_bf16_f32 v48, v48, v49
	v_accvgpr_read_b32 v51, a179
	v_cvt_pk_bf16_f32 v49, v50, v51
	v_accvgpr_read_b32 v52, a180
	v_accvgpr_read_b32 v53, a181
	v_cvt_pk_bf16_f32 v52, v52, v53
	v_accvgpr_read_b32 v54, a182
	v_accvgpr_read_b32 v55, a183
	v_cvt_pk_bf16_f32 v53, v54, v55
	v_accvgpr_read_b32 v56, a184
	v_accvgpr_read_b32 v57, a185
	v_cvt_pk_bf16_f32 v50, v56, v57
	v_accvgpr_read_b32 v58, a186
	v_accvgpr_read_b32 v59, a187
	v_cvt_pk_bf16_f32 v51, v58, v59
	v_accvgpr_read_b32 v60, a188
	v_accvgpr_read_b32 v61, a189
	v_cvt_pk_bf16_f32 v54, v60, v61
	v_accvgpr_read_b32 v62, a190
	v_accvgpr_read_b32 v63, a191
	v_cvt_pk_bf16_f32 v55, v62, v63
	v_cndmask_b32_e32 v56, v48, v50, vcc
	v_cndmask_b32_e32 v57, v49, v51, vcc
	v_cndmask_b32_e32 v58, v52, v54, vcc
	ds_bpermute_b32 v56, v194, v56
	ds_bpermute_b32 v57, v194, v57
	v_cndmask_b32_e32 v59, v53, v55, vcc
	ds_bpermute_b32 v58, v194, v58
	ds_bpermute_b32 v59, v194, v59
	v_accvgpr_read_b32 v32, a32
	s_waitcnt lgkmcnt(3)
	v_cndmask_b32_e32 v48, v56, v48, vcc
	s_waitcnt lgkmcnt(2)
	v_cndmask_b32_e32 v49, v57, v49, vcc
	v_cndmask_b32_e32 v50, v50, v56, vcc
	v_cndmask_b32_e32 v51, v51, v57, vcc
	v_accvgpr_read_b32 v33, a33
	s_waitcnt lgkmcnt(1)
	v_cndmask_b32_e32 v52, v58, v52, vcc
	s_waitcnt lgkmcnt(0)
	v_cndmask_b32_e32 v53, v59, v53, vcc
	v_cndmask_b32_e32 v54, v54, v58, vcc
	v_cndmask_b32_e32 v55, v55, v59, vcc
	global_store_dwordx4 v[144:145], v[48:51], off offset:128
	global_store_dwordx4 v[144:145], v[52:55], off offset:144
	v_accvgpr_read_b32 v34, a34
	v_cvt_pk_bf16_f32 v32, v32, v33
	v_accvgpr_read_b32 v35, a35
	v_cvt_pk_bf16_f32 v33, v34, v35
	v_accvgpr_read_b32 v36, a36
	v_accvgpr_read_b32 v37, a37
	v_cvt_pk_bf16_f32 v36, v36, v37
	v_accvgpr_read_b32 v38, a38
	v_accvgpr_read_b32 v39, a39
	v_cvt_pk_bf16_f32 v37, v38, v39
	v_accvgpr_read_b32 v40, a40
	v_accvgpr_read_b32 v41, a41
	v_cvt_pk_bf16_f32 v34, v40, v41
	v_accvgpr_read_b32 v42, a42
	v_accvgpr_read_b32 v43, a43
	v_cvt_pk_bf16_f32 v35, v42, v43
	v_accvgpr_read_b32 v44, a44
	v_accvgpr_read_b32 v45, a45
	v_cvt_pk_bf16_f32 v38, v44, v45
	v_accvgpr_read_b32 v46, a46
	v_accvgpr_read_b32 v47, a47
	v_cvt_pk_bf16_f32 v39, v46, v47
	v_cndmask_b32_e32 v40, v32, v34, vcc
	v_cndmask_b32_e32 v41, v33, v35, vcc
	v_cndmask_b32_e32 v42, v36, v38, vcc
	ds_bpermute_b32 v40, v194, v40
	ds_bpermute_b32 v41, v194, v41
	v_cndmask_b32_e32 v43, v37, v39, vcc
	ds_bpermute_b32 v42, v194, v42
	ds_bpermute_b32 v43, v194, v43
	s_waitcnt vmcnt(18)
	v_accvgpr_read_b32 v16, a16
	s_waitcnt lgkmcnt(3)
	v_cndmask_b32_e32 v32, v40, v32, vcc
	s_waitcnt lgkmcnt(2)
	v_cndmask_b32_e32 v33, v41, v33, vcc
	v_cndmask_b32_e32 v34, v34, v40, vcc
	v_cndmask_b32_e32 v35, v35, v41, vcc
	v_accvgpr_read_b32 v17, a17
	s_waitcnt lgkmcnt(1)
	v_cndmask_b32_e32 v36, v42, v36, vcc
	s_waitcnt lgkmcnt(0)
	v_cndmask_b32_e32 v37, v43, v37, vcc
	v_cndmask_b32_e32 v38, v38, v42, vcc
	v_cndmask_b32_e32 v39, v39, v43, vcc
	global_store_dwordx4 v[176:177], v[32:35], off offset:192
	global_store_dwordx4 v[176:177], v[36:39], off offset:208
	v_accvgpr_read_b32 v18, a18
	v_cvt_pk_bf16_f32 v16, v16, v17
	v_accvgpr_read_b32 v19, a19
	v_cvt_pk_bf16_f32 v17, v18, v19
	v_accvgpr_read_b32 v20, a20
	v_accvgpr_read_b32 v21, a21
	v_cvt_pk_bf16_f32 v20, v20, v21
	v_accvgpr_read_b32 v22, a22
	v_accvgpr_read_b32 v23, a23
	v_cvt_pk_bf16_f32 v21, v22, v23
	v_accvgpr_read_b32 v24, a24
	v_accvgpr_read_b32 v25, a25
	v_cvt_pk_bf16_f32 v18, v24, v25
	v_accvgpr_read_b32 v26, a26
	v_accvgpr_read_b32 v27, a27
	v_cvt_pk_bf16_f32 v19, v26, v27
	v_accvgpr_read_b32 v28, a28
	v_accvgpr_read_b32 v29, a29
	v_cvt_pk_bf16_f32 v22, v28, v29
	v_accvgpr_read_b32 v30, a30
	v_accvgpr_read_b32 v31, a31
	v_cvt_pk_bf16_f32 v23, v30, v31
	v_cndmask_b32_e32 v24, v16, v18, vcc
	v_cndmask_b32_e32 v25, v17, v19, vcc
	v_cndmask_b32_e32 v26, v20, v22, vcc
	ds_bpermute_b32 v24, v194, v24
	ds_bpermute_b32 v25, v194, v25
	v_cndmask_b32_e32 v27, v21, v23, vcc
	ds_bpermute_b32 v26, v194, v26
	ds_bpermute_b32 v27, v194, v27
	v_accvgpr_read_b32 v0, a0
	s_waitcnt lgkmcnt(3)
	v_cndmask_b32_e32 v16, v24, v16, vcc
	s_waitcnt lgkmcnt(2)
	v_cndmask_b32_e32 v17, v25, v17, vcc
	v_cndmask_b32_e32 v18, v18, v24, vcc
	v_cndmask_b32_e32 v19, v19, v25, vcc
	v_accvgpr_read_b32 v1, a1
	s_waitcnt lgkmcnt(1)
	v_cndmask_b32_e32 v20, v26, v20, vcc
	s_waitcnt lgkmcnt(0)
	v_cndmask_b32_e32 v21, v27, v21, vcc
	v_cndmask_b32_e32 v22, v22, v26, vcc
	v_cndmask_b32_e32 v23, v23, v27, vcc
	global_store_dwordx4 v[160:161], v[16:19], off offset:192
	global_store_dwordx4 v[160:161], v[20:23], off offset:208
	v_accvgpr_read_b32 v2, a2
	v_cvt_pk_bf16_f32 v0, v0, v1
	v_accvgpr_read_b32 v3, a3
	v_cvt_pk_bf16_f32 v1, v2, v3
	v_accvgpr_read_b32 v4, a4
	v_accvgpr_read_b32 v5, a5
	v_cvt_pk_bf16_f32 v4, v4, v5
	v_accvgpr_read_b32 v6, a6
	v_accvgpr_read_b32 v7, a7
	v_cvt_pk_bf16_f32 v5, v6, v7
	v_accvgpr_read_b32 v8, a8
	v_accvgpr_read_b32 v9, a9
	v_cvt_pk_bf16_f32 v2, v8, v9
	v_accvgpr_read_b32 v10, a10
	v_accvgpr_read_b32 v11, a11
	v_cvt_pk_bf16_f32 v3, v10, v11
	v_accvgpr_read_b32 v12, a12
	v_accvgpr_read_b32 v13, a13
	v_cvt_pk_bf16_f32 v6, v12, v13
	v_accvgpr_read_b32 v14, a14
	v_accvgpr_read_b32 v15, a15
	v_cvt_pk_bf16_f32 v7, v14, v15
	v_cndmask_b32_e32 v8, v0, v2, vcc
	v_cndmask_b32_e32 v9, v1, v3, vcc
	v_cndmask_b32_e32 v10, v4, v6, vcc
	v_cndmask_b32_e32 v11, v5, v7, vcc
	ds_bpermute_b32 v8, v194, v8
	ds_bpermute_b32 v9, v194, v9
	ds_bpermute_b32 v10, v194, v10
	ds_bpermute_b32 v11, v194, v11
	s_add_i32 s0, s0, s93
	s_waitcnt lgkmcnt(3)
	v_cndmask_b32_e32 v0, v8, v0, vcc
	s_waitcnt lgkmcnt(2)
	v_cndmask_b32_e32 v1, v9, v1, vcc
	v_cndmask_b32_e32 v2, v2, v8, vcc
	v_cndmask_b32_e32 v3, v3, v9, vcc
	s_waitcnt lgkmcnt(1)
	v_cndmask_b32_e32 v4, v10, v4, vcc
	s_waitcnt lgkmcnt(0)
	v_cndmask_b32_e32 v5, v11, v5, vcc
	v_cndmask_b32_e32 v6, v6, v10, vcc
	v_cndmask_b32_e32 v7, v7, v11, vcc
	s_cmpk_lt_i32 s0, 0x100
	global_store_dwordx4 v[144:145], v[0:3], off offset:192
	global_store_dwordx4 v[144:145], v[4:7], off offset:208
	s_cbranch_scc0 .LBB0_116

.LBB0_120:
	s_nop 1
	v_accvgpr_read_b32 v191, a63
	v_or_b32_e32 v192, s4, v192
	v_cmp_lt_i32_e32 vcc, v211, v210
	v_mfma_f32_32x32x16_bf16 a[32:47], v[198:201], v[40:43], a[32:47]
	v_accvgpr_read_b32 v176, a48
	v_accvgpr_read_b32 v177, a49
	v_accvgpr_read_b32 v178, a50
	v_accvgpr_read_b32 v179, a51
	v_accvgpr_read_b32 v180, a52
	v_accvgpr_read_b32 v181, a53
	v_accvgpr_read_b32 v182, a54
	v_mfma_f32_32x32x16_bf16 a[16:31], v[198:201], v[36:39], a[16:31]
	v_accvgpr_read_b32 v183, a55
	v_accvgpr_read_b32 v184, a56
	v_accvgpr_read_b32 v185, a57
	v_accvgpr_read_b32 v186, a58
	v_accvgpr_read_b32 v187, a59
	v_accvgpr_read_b32 v188, a60
	v_accvgpr_read_b32 v189, a61
	v_mfma_f32_32x32x16_bf16 a[0:15], v[198:201], v[194:197], a[0:15]
	v_add_u32_e32 v198, v205, v192
	v_cndmask_b32_e32 v192, v209, v211, vcc
	v_lshlrev_b32_e32 v194, 2, v192
	v_cvt_pk_bf16_f32 v176, v176, v177
	v_cvt_pk_bf16_f32 v177, v178, v179
	v_cvt_pk_bf16_f32 v192, v180, v181
	v_cvt_pk_bf16_f32 v183, v182, v183
	v_cvt_pk_bf16_f32 v180, v184, v185
	v_cvt_pk_bf16_f32 v181, v186, v187
	v_cvt_pk_bf16_f32 v184, v188, v189
	v_accvgpr_read_b32 v190, a62
	v_cvt_pk_bf16_f32 v185, v190, v191
	v_and_b32_e32 v178, 63, v203
	v_cmp_gt_u32_e32 vcc, 32, v178
	v_or_b32_e32 v196, s1, v204
	v_ashrrev_i32_e32 v199, 31, v198
	v_cndmask_b32_e32 v178, v176, v180, vcc
	v_cndmask_b32_e32 v179, v177, v181, vcc
	ds_bpermute_b32 v186, v194, v178
	ds_bpermute_b32 v187, v194, v179
	v_cndmask_b32_e32 v182, v192, v184, vcc
	ds_bpermute_b32 v188, v194, v182
	v_cndmask_b32_e32 v178, v183, v185, vcc
	ds_bpermute_b32 v189, v194, v178
	v_readlane_b32 s4, v253, 43
	v_ashrrev_i32_e32 v197, 31, v196
	s_waitcnt lgkmcnt(3)
	v_cndmask_b32_e32 v178, v186, v176, vcc
	s_waitcnt lgkmcnt(2)
	v_cndmask_b32_e32 v179, v187, v177, vcc
	v_lshlrev_b64 v[176:177], 11, v[198:199]
	v_readlane_b32 s5, v253, 44
	v_cndmask_b32_e32 v180, v180, v186, vcc
	v_cndmask_b32_e32 v181, v181, v187, vcc
	v_lshl_add_u64 v[176:177], s[4:5], 0, v[176:177]
	v_lshlrev_b64 v[186:187], 1, v[196:197]
	v_accvgpr_read_b32 v175, a79
	s_waitcnt lgkmcnt(1)
	v_cndmask_b32_e32 v182, v188, v192, vcc
	v_lshl_add_u64 v[176:177], v[176:177], 0, v[186:187]
	v_and_b32_e32 v192, 32, v203
	v_accvgpr_read_b32 v160, a64
	v_lshl_add_u64 v[176:177], v[176:177], 0, v[192:193]
	v_accvgpr_read_b32 v161, a65
	s_waitcnt lgkmcnt(0)
	v_cndmask_b32_e32 v183, v189, v183, vcc
	v_cndmask_b32_e32 v184, v184, v188, vcc
	v_cndmask_b32_e32 v185, v185, v189, vcc
	global_store_dwordx4 v[176:177], v[178:181], off
	global_store_dwordx4 v[176:177], v[182:185], off offset:16
	v_accvgpr_read_b32 v162, a66
	v_cvt_pk_bf16_f32 v161, v160, v161
	v_accvgpr_read_b32 v163, a67
	v_cvt_pk_bf16_f32 v163, v162, v163
	v_accvgpr_read_b32 v164, a68
	v_accvgpr_read_b32 v165, a69
	v_cvt_pk_bf16_f32 v178, v164, v165
	v_accvgpr_read_b32 v166, a70
	v_accvgpr_read_b32 v167, a71
	v_cvt_pk_bf16_f32 v167, v166, v167
	v_accvgpr_read_b32 v168, a72
	v_accvgpr_read_b32 v169, a73
	v_cvt_pk_bf16_f32 v164, v168, v169
	v_accvgpr_read_b32 v170, a74
	v_accvgpr_read_b32 v171, a75
	v_cvt_pk_bf16_f32 v165, v170, v171
	v_accvgpr_read_b32 v172, a76
	v_accvgpr_read_b32 v173, a77
	v_cvt_pk_bf16_f32 v168, v172, v173
	v_accvgpr_read_b32 v174, a78
	v_cvt_pk_bf16_f32 v169, v174, v175
	v_cndmask_b32_e32 v162, v161, v164, vcc
	ds_bpermute_b32 v171, v194, v162
	v_cndmask_b32_e32 v166, v163, v165, vcc
	v_add_u32_e32 v160, 32, v198
	v_cndmask_b32_e32 v170, v178, v168, vcc
	ds_bpermute_b32 v166, v194, v166
	v_cndmask_b32_e32 v162, v167, v169, vcc
	ds_bpermute_b32 v170, v194, v170
	ds_bpermute_b32 v172, v194, v162
	s_waitcnt lgkmcnt(3)
	v_cndmask_b32_e32 v162, v171, v161, vcc
	v_ashrrev_i32_e32 v161, 31, v160
	v_lshlrev_b64 v[160:161], 11, v[160:161]
	v_lshl_add_u64 v[160:161], s[4:5], 0, v[160:161]
	v_accvgpr_read_b32 v159, a95
	v_lshl_add_u64 v[160:161], v[160:161], 0, v[186:187]
	v_accvgpr_read_b32 v144, a80
	s_waitcnt lgkmcnt(2)
	v_cndmask_b32_e32 v163, v166, v163, vcc
	v_cndmask_b32_e32 v164, v164, v171, vcc
	v_cndmask_b32_e32 v165, v165, v166, vcc
	v_lshl_add_u64 v[160:161], v[160:161], 0, v[192:193]
	v_accvgpr_read_b32 v145, a81
	s_waitcnt lgkmcnt(1)
	v_cndmask_b32_e32 v166, v170, v178, vcc
	s_waitcnt lgkmcnt(0)
	v_cndmask_b32_e32 v167, v172, v167, vcc
	v_cndmask_b32_e32 v168, v168, v170, vcc
	v_cndmask_b32_e32 v169, v169, v172, vcc
	global_store_dwordx4 v[160:161], v[162:165], off
	global_store_dwordx4 v[160:161], v[166:169], off offset:16
	v_accvgpr_read_b32 v146, a82
	v_cvt_pk_bf16_f32 v145, v144, v145
	v_accvgpr_read_b32 v147, a83
	v_cvt_pk_bf16_f32 v147, v146, v147
	v_accvgpr_read_b32 v148, a84
	v_accvgpr_read_b32 v149, a85
	v_cvt_pk_bf16_f32 v162, v148, v149
	v_accvgpr_read_b32 v150, a86
	v_accvgpr_read_b32 v151, a87
	v_cvt_pk_bf16_f32 v151, v150, v151
	v_accvgpr_read_b32 v152, a88
	v_accvgpr_read_b32 v153, a89
	v_cvt_pk_bf16_f32 v148, v152, v153
	v_accvgpr_read_b32 v154, a90
	v_accvgpr_read_b32 v155, a91
	v_cvt_pk_bf16_f32 v149, v154, v155
	v_accvgpr_read_b32 v156, a92
	v_accvgpr_read_b32 v157, a93
	v_cvt_pk_bf16_f32 v152, v156, v157
	v_accvgpr_read_b32 v158, a94
	v_cvt_pk_bf16_f32 v153, v158, v159
	v_cndmask_b32_e32 v146, v145, v148, vcc
	ds_bpermute_b32 v155, v194, v146
	v_cndmask_b32_e32 v150, v147, v149, vcc
	v_add_u32_e32 v144, 64, v198
	v_cndmask_b32_e32 v154, v162, v152, vcc
	ds_bpermute_b32 v150, v194, v150
	v_cndmask_b32_e32 v146, v151, v153, vcc
	ds_bpermute_b32 v154, v194, v154
	ds_bpermute_b32 v156, v194, v146
	s_waitcnt lgkmcnt(3)
	v_cndmask_b32_e32 v146, v155, v145, vcc
	v_ashrrev_i32_e32 v145, 31, v144
	v_lshlrev_b64 v[144:145], 11, v[144:145]
	v_lshl_add_u64 v[144:145], s[4:5], 0, v[144:145]
	v_accvgpr_read_b32 v143, a111
	v_lshl_add_u64 v[144:145], v[144:145], 0, v[186:187]
	v_accvgpr_read_b32 v128, a96
	s_waitcnt lgkmcnt(2)
	v_cndmask_b32_e32 v147, v150, v147, vcc
	v_cndmask_b32_e32 v148, v148, v155, vcc
	v_cndmask_b32_e32 v149, v149, v150, vcc
	v_lshl_add_u64 v[144:145], v[144:145], 0, v[192:193]
	v_accvgpr_read_b32 v129, a97
	s_waitcnt lgkmcnt(1)
	v_cndmask_b32_e32 v150, v154, v162, vcc
	s_waitcnt lgkmcnt(0)
	v_cndmask_b32_e32 v151, v156, v151, vcc
	v_cndmask_b32_e32 v152, v152, v154, vcc
	v_cndmask_b32_e32 v153, v153, v156, vcc
	global_store_dwordx4 v[144:145], v[146:149], off
	global_store_dwordx4 v[144:145], v[150:153], off offset:16
	v_accvgpr_read_b32 v130, a98
	v_cvt_pk_bf16_f32 v128, v128, v129
	v_accvgpr_read_b32 v131, a99
	v_cvt_pk_bf16_f32 v129, v130, v131
	v_accvgpr_read_b32 v132, a100
	v_accvgpr_read_b32 v133, a101
	v_cvt_pk_bf16_f32 v132, v132, v133
	v_accvgpr_read_b32 v134, a102
	v_accvgpr_read_b32 v135, a103
	v_cvt_pk_bf16_f32 v133, v134, v135
	v_accvgpr_read_b32 v136, a104
	v_accvgpr_read_b32 v137, a105
	v_cvt_pk_bf16_f32 v130, v136, v137
	v_accvgpr_read_b32 v138, a106
	v_accvgpr_read_b32 v139, a107
	v_cvt_pk_bf16_f32 v131, v138, v139
	v_accvgpr_read_b32 v140, a108
	v_accvgpr_read_b32 v141, a109
	v_cvt_pk_bf16_f32 v134, v140, v141
	v_accvgpr_read_b32 v142, a110
	v_cvt_pk_bf16_f32 v135, v142, v143
	v_cndmask_b32_e32 v136, v128, v130, vcc
	v_cndmask_b32_e32 v137, v129, v131, vcc
	v_cndmask_b32_e32 v138, v132, v134, vcc
	ds_bpermute_b32 v136, v194, v136
	ds_bpermute_b32 v137, v194, v137
	v_cndmask_b32_e32 v139, v133, v135, vcc
	ds_bpermute_b32 v138, v194, v138
	ds_bpermute_b32 v139, v194, v139
	v_accvgpr_read_b32 v112, a112
	s_waitcnt lgkmcnt(3)
	v_cndmask_b32_e32 v128, v136, v128, vcc
	s_waitcnt lgkmcnt(2)
	v_cndmask_b32_e32 v129, v137, v129, vcc
	v_cndmask_b32_e32 v130, v130, v136, vcc
	v_cndmask_b32_e32 v131, v131, v137, vcc
	v_accvgpr_read_b32 v113, a113
	s_waitcnt lgkmcnt(1)
	v_cndmask_b32_e32 v132, v138, v132, vcc
	s_waitcnt lgkmcnt(0)
	v_cndmask_b32_e32 v133, v139, v133, vcc
	v_cndmask_b32_e32 v134, v134, v138, vcc
	v_cndmask_b32_e32 v135, v135, v139, vcc
	global_store_dwordx4 v[176:177], v[128:131], off offset:64
	global_store_dwordx4 v[176:177], v[132:135], off offset:80
	v_accvgpr_read_b32 v114, a114
	v_cvt_pk_bf16_f32 v112, v112, v113
	v_accvgpr_read_b32 v115, a115
	v_cvt_pk_bf16_f32 v113, v114, v115
	v_accvgpr_read_b32 v116, a116
	v_accvgpr_read_b32 v117, a117
	v_cvt_pk_bf16_f32 v116, v116, v117
	v_accvgpr_read_b32 v118, a118
	v_accvgpr_read_b32 v119, a119
	v_cvt_pk_bf16_f32 v117, v118, v119
	v_accvgpr_read_b32 v120, a120
	v_accvgpr_read_b32 v121, a121
	v_cvt_pk_bf16_f32 v114, v120, v121
	v_accvgpr_read_b32 v122, a122
	v_accvgpr_read_b32 v123, a123
	v_cvt_pk_bf16_f32 v115, v122, v123
	v_accvgpr_read_b32 v124, a124
	v_accvgpr_read_b32 v125, a125
	v_cvt_pk_bf16_f32 v118, v124, v125
	v_accvgpr_read_b32 v126, a126
	v_accvgpr_read_b32 v127, a127
	v_cvt_pk_bf16_f32 v119, v126, v127
	v_cndmask_b32_e32 v120, v112, v114, vcc
	v_cndmask_b32_e32 v121, v113, v115, vcc
	v_cndmask_b32_e32 v122, v116, v118, vcc
	ds_bpermute_b32 v120, v194, v120
	ds_bpermute_b32 v121, v194, v121
	v_cndmask_b32_e32 v123, v117, v119, vcc
	ds_bpermute_b32 v122, v194, v122
	ds_bpermute_b32 v123, v194, v123
	v_accvgpr_read_b32 v96, a128
	s_waitcnt lgkmcnt(3)
	v_cndmask_b32_e32 v112, v120, v112, vcc
	s_waitcnt lgkmcnt(2)
	v_cndmask_b32_e32 v113, v121, v113, vcc
	v_cndmask_b32_e32 v114, v114, v120, vcc
	v_cndmask_b32_e32 v115, v115, v121, vcc
	v_accvgpr_read_b32 v97, a129
	s_waitcnt lgkmcnt(1)
	v_cndmask_b32_e32 v116, v122, v116, vcc
	s_waitcnt lgkmcnt(0)
	v_cndmask_b32_e32 v117, v123, v117, vcc
	v_cndmask_b32_e32 v118, v118, v122, vcc
	v_cndmask_b32_e32 v119, v119, v123, vcc
	global_store_dwordx4 v[160:161], v[112:115], off offset:64
	global_store_dwordx4 v[160:161], v[116:119], off offset:80
	v_accvgpr_read_b32 v98, a130
	v_cvt_pk_bf16_f32 v96, v96, v97
	v_accvgpr_read_b32 v99, a131
	v_cvt_pk_bf16_f32 v97, v98, v99
	v_accvgpr_read_b32 v100, a132
	v_accvgpr_read_b32 v101, a133
	v_cvt_pk_bf16_f32 v100, v100, v101
	v_accvgpr_read_b32 v102, a134
	v_accvgpr_read_b32 v103, a135
	v_cvt_pk_bf16_f32 v101, v102, v103
	v_accvgpr_read_b32 v104, a136
	v_accvgpr_read_b32 v105, a137
	v_cvt_pk_bf16_f32 v98, v104, v105
	v_accvgpr_read_b32 v106, a138
	v_accvgpr_read_b32 v107, a139
	v_cvt_pk_bf16_f32 v99, v106, v107
	v_accvgpr_read_b32 v108, a140
	v_accvgpr_read_b32 v109, a141
	v_cvt_pk_bf16_f32 v102, v108, v109
	v_accvgpr_read_b32 v110, a142
	v_accvgpr_read_b32 v111, a143
	v_cvt_pk_bf16_f32 v103, v110, v111
	v_cndmask_b32_e32 v104, v96, v98, vcc
	v_cndmask_b32_e32 v105, v97, v99, vcc
	v_cndmask_b32_e32 v106, v100, v102, vcc
	ds_bpermute_b32 v104, v194, v104
	ds_bpermute_b32 v105, v194, v105
	v_cndmask_b32_e32 v107, v101, v103, vcc
	ds_bpermute_b32 v106, v194, v106
	ds_bpermute_b32 v107, v194, v107
	v_accvgpr_read_b32 v80, a144
	s_waitcnt lgkmcnt(3)
	v_cndmask_b32_e32 v96, v104, v96, vcc
	s_waitcnt lgkmcnt(2)
	v_cndmask_b32_e32 v97, v105, v97, vcc
	v_cndmask_b32_e32 v98, v98, v104, vcc
	v_cndmask_b32_e32 v99, v99, v105, vcc
	v_accvgpr_read_b32 v81, a145
	s_waitcnt lgkmcnt(1)
	v_cndmask_b32_e32 v100, v106, v100, vcc
	s_waitcnt lgkmcnt(0)
	v_cndmask_b32_e32 v101, v107, v101, vcc
	v_cndmask_b32_e32 v102, v102, v106, vcc
	v_cndmask_b32_e32 v103, v103, v107, vcc
	global_store_dwordx4 v[144:145], v[96:99], off offset:64
	global_store_dwordx4 v[144:145], v[100:103], off offset:80
	v_accvgpr_read_b32 v82, a146
	v_cvt_pk_bf16_f32 v80, v80, v81
	v_accvgpr_read_b32 v83, a147
	v_cvt_pk_bf16_f32 v81, v82, v83
	v_accvgpr_read_b32 v84, a148
	v_accvgpr_read_b32 v85, a149
	v_cvt_pk_bf16_f32 v84, v84, v85
	v_accvgpr_read_b32 v86, a150
	v_accvgpr_read_b32 v87, a151
	v_cvt_pk_bf16_f32 v85, v86, v87
	v_accvgpr_read_b32 v88, a152
	v_accvgpr_read_b32 v89, a153
	v_cvt_pk_bf16_f32 v82, v88, v89
	v_accvgpr_read_b32 v90, a154
	v_accvgpr_read_b32 v91, a155
	v_cvt_pk_bf16_f32 v83, v90, v91
	v_accvgpr_read_b32 v92, a156
	v_accvgpr_read_b32 v93, a157
	v_cvt_pk_bf16_f32 v86, v92, v93
	v_accvgpr_read_b32 v94, a158
	v_accvgpr_read_b32 v95, a159
	v_cvt_pk_bf16_f32 v87, v94, v95
	v_cndmask_b32_e32 v88, v80, v82, vcc
	v_cndmask_b32_e32 v89, v81, v83, vcc
	v_cndmask_b32_e32 v90, v84, v86, vcc
	ds_bpermute_b32 v88, v194, v88
	ds_bpermute_b32 v89, v194, v89
	v_cndmask_b32_e32 v91, v85, v87, vcc
	ds_bpermute_b32 v90, v194, v90
	ds_bpermute_b32 v91, v194, v91
	v_accvgpr_read_b32 v64, a160
	s_waitcnt lgkmcnt(3)
	v_cndmask_b32_e32 v80, v88, v80, vcc
	s_waitcnt lgkmcnt(2)
	v_cndmask_b32_e32 v81, v89, v81, vcc
	v_cndmask_b32_e32 v82, v82, v88, vcc
	v_cndmask_b32_e32 v83, v83, v89, vcc
	v_accvgpr_read_b32 v65, a161
	s_waitcnt lgkmcnt(1)
	v_cndmask_b32_e32 v84, v90, v84, vcc
	s_waitcnt lgkmcnt(0)
	v_cndmask_b32_e32 v85, v91, v85, vcc
	v_cndmask_b32_e32 v86, v86, v90, vcc
	v_cndmask_b32_e32 v87, v87, v91, vcc
	global_store_dwordx4 v[176:177], v[80:83], off offset:128
	global_store_dwordx4 v[176:177], v[84:87], off offset:144
	v_accvgpr_read_b32 v66, a162
	v_cvt_pk_bf16_f32 v64, v64, v65
	v_accvgpr_read_b32 v67, a163
	v_cvt_pk_bf16_f32 v65, v66, v67
	v_accvgpr_read_b32 v68, a164
	v_accvgpr_read_b32 v69, a165
	v_cvt_pk_bf16_f32 v68, v68, v69
	v_accvgpr_read_b32 v70, a166
	v_accvgpr_read_b32 v71, a167
	v_cvt_pk_bf16_f32 v69, v70, v71
	v_accvgpr_read_b32 v72, a168
	v_accvgpr_read_b32 v73, a169
	v_cvt_pk_bf16_f32 v66, v72, v73
	v_accvgpr_read_b32 v74, a170
	v_accvgpr_read_b32 v75, a171
	v_cvt_pk_bf16_f32 v67, v74, v75
	v_accvgpr_read_b32 v76, a172
	v_accvgpr_read_b32 v77, a173
	v_cvt_pk_bf16_f32 v70, v76, v77
	v_accvgpr_read_b32 v78, a174
	v_accvgpr_read_b32 v79, a175
	v_cvt_pk_bf16_f32 v71, v78, v79
	v_cndmask_b32_e32 v72, v64, v66, vcc
	v_cndmask_b32_e32 v73, v65, v67, vcc
	v_cndmask_b32_e32 v74, v68, v70, vcc
	ds_bpermute_b32 v72, v194, v72
	ds_bpermute_b32 v73, v194, v73
	v_cndmask_b32_e32 v75, v69, v71, vcc
	ds_bpermute_b32 v74, v194, v74
	ds_bpermute_b32 v75, v194, v75
	v_accvgpr_read_b32 v48, a176
	s_waitcnt lgkmcnt(3)
	v_cndmask_b32_e32 v64, v72, v64, vcc
	s_waitcnt lgkmcnt(2)
	v_cndmask_b32_e32 v65, v73, v65, vcc
	v_cndmask_b32_e32 v66, v66, v72, vcc
	v_cndmask_b32_e32 v67, v67, v73, vcc
	v_accvgpr_read_b32 v49, a177
	s_waitcnt lgkmcnt(1)
	v_cndmask_b32_e32 v68, v74, v68, vcc
	s_waitcnt lgkmcnt(0)
	v_cndmask_b32_e32 v69, v75, v69, vcc
	v_cndmask_b32_e32 v70, v70, v74, vcc
	v_cndmask_b32_e32 v71, v71, v75, vcc
	global_store_dwordx4 v[160:161], v[64:67], off offset:128
	global_store_dwordx4 v[160:161], v[68:71], off offset:144
	v_accvgpr_read_b32 v50, a178
	v_cvt_pk_bf16_f32 v48, v48, v49
	v_accvgpr_read_b32 v51, a179
	v_cvt_pk_bf16_f32 v49, v50, v51
	v_accvgpr_read_b32 v52, a180
	v_accvgpr_read_b32 v53, a181
	v_cvt_pk_bf16_f32 v52, v52, v53
	v_accvgpr_read_b32 v54, a182
	v_accvgpr_read_b32 v55, a183
	v_cvt_pk_bf16_f32 v53, v54, v55
	v_accvgpr_read_b32 v56, a184
	v_accvgpr_read_b32 v57, a185
	v_cvt_pk_bf16_f32 v50, v56, v57
	v_accvgpr_read_b32 v58, a186
	v_accvgpr_read_b32 v59, a187
	v_cvt_pk_bf16_f32 v51, v58, v59
	v_accvgpr_read_b32 v60, a188
	v_accvgpr_read_b32 v61, a189
	v_cvt_pk_bf16_f32 v54, v60, v61
	v_accvgpr_read_b32 v62, a190
	v_accvgpr_read_b32 v63, a191
	v_cvt_pk_bf16_f32 v55, v62, v63
	v_cndmask_b32_e32 v56, v48, v50, vcc
	v_cndmask_b32_e32 v57, v49, v51, vcc
	v_cndmask_b32_e32 v58, v52, v54, vcc
	ds_bpermute_b32 v56, v194, v56
	ds_bpermute_b32 v57, v194, v57
	v_cndmask_b32_e32 v59, v53, v55, vcc
	ds_bpermute_b32 v58, v194, v58
	ds_bpermute_b32 v59, v194, v59
	v_accvgpr_read_b32 v32, a32
	s_waitcnt lgkmcnt(3)
	v_cndmask_b32_e32 v48, v56, v48, vcc
	s_waitcnt lgkmcnt(2)
	v_cndmask_b32_e32 v49, v57, v49, vcc
	v_cndmask_b32_e32 v50, v50, v56, vcc
	v_cndmask_b32_e32 v51, v51, v57, vcc
	v_accvgpr_read_b32 v33, a33
	s_waitcnt lgkmcnt(1)
	v_cndmask_b32_e32 v52, v58, v52, vcc
	s_waitcnt lgkmcnt(0)
	v_cndmask_b32_e32 v53, v59, v53, vcc
	v_cndmask_b32_e32 v54, v54, v58, vcc
	v_cndmask_b32_e32 v55, v55, v59, vcc
	global_store_dwordx4 v[144:145], v[48:51], off offset:128
	global_store_dwordx4 v[144:145], v[52:55], off offset:144
	v_accvgpr_read_b32 v34, a34
	v_cvt_pk_bf16_f32 v32, v32, v33
	v_accvgpr_read_b32 v35, a35
	v_cvt_pk_bf16_f32 v33, v34, v35
	v_accvgpr_read_b32 v36, a36
	v_accvgpr_read_b32 v37, a37
	v_cvt_pk_bf16_f32 v36, v36, v37
	v_accvgpr_read_b32 v38, a38
	v_accvgpr_read_b32 v39, a39
	v_cvt_pk_bf16_f32 v37, v38, v39
	v_accvgpr_read_b32 v40, a40
	v_accvgpr_read_b32 v41, a41
	v_cvt_pk_bf16_f32 v34, v40, v41
	v_accvgpr_read_b32 v42, a42
	v_accvgpr_read_b32 v43, a43
	v_cvt_pk_bf16_f32 v35, v42, v43
	v_accvgpr_read_b32 v44, a44
	v_accvgpr_read_b32 v45, a45
	v_cvt_pk_bf16_f32 v38, v44, v45
	v_accvgpr_read_b32 v46, a46
	v_accvgpr_read_b32 v47, a47
	v_cvt_pk_bf16_f32 v39, v46, v47
	v_cndmask_b32_e32 v40, v32, v34, vcc
	v_cndmask_b32_e32 v41, v33, v35, vcc
	v_cndmask_b32_e32 v42, v36, v38, vcc
	ds_bpermute_b32 v40, v194, v40
	ds_bpermute_b32 v41, v194, v41
	v_cndmask_b32_e32 v43, v37, v39, vcc
	ds_bpermute_b32 v42, v194, v42
	ds_bpermute_b32 v43, v194, v43
	s_waitcnt vmcnt(18)
	v_accvgpr_read_b32 v16, a16
	s_waitcnt lgkmcnt(3)
	v_cndmask_b32_e32 v32, v40, v32, vcc
	s_waitcnt lgkmcnt(2)
	v_cndmask_b32_e32 v33, v41, v33, vcc
	v_cndmask_b32_e32 v34, v34, v40, vcc
	v_cndmask_b32_e32 v35, v35, v41, vcc
	v_accvgpr_read_b32 v17, a17
	s_waitcnt lgkmcnt(1)
	v_cndmask_b32_e32 v36, v42, v36, vcc
	s_waitcnt lgkmcnt(0)
	v_cndmask_b32_e32 v37, v43, v37, vcc
	v_cndmask_b32_e32 v38, v38, v42, vcc
	v_cndmask_b32_e32 v39, v39, v43, vcc
	global_store_dwordx4 v[176:177], v[32:35], off offset:192
	global_store_dwordx4 v[176:177], v[36:39], off offset:208
	v_accvgpr_read_b32 v18, a18
	v_cvt_pk_bf16_f32 v16, v16, v17
	v_accvgpr_read_b32 v19, a19
	v_cvt_pk_bf16_f32 v17, v18, v19
	v_accvgpr_read_b32 v20, a20
	v_accvgpr_read_b32 v21, a21
	v_cvt_pk_bf16_f32 v20, v20, v21
	v_accvgpr_read_b32 v22, a22
	v_accvgpr_read_b32 v23, a23
	v_cvt_pk_bf16_f32 v21, v22, v23
	v_accvgpr_read_b32 v24, a24
	v_accvgpr_read_b32 v25, a25
	v_cvt_pk_bf16_f32 v18, v24, v25
	v_accvgpr_read_b32 v26, a26
	v_accvgpr_read_b32 v27, a27
	v_cvt_pk_bf16_f32 v19, v26, v27
	v_accvgpr_read_b32 v28, a28
	v_accvgpr_read_b32 v29, a29
	v_cvt_pk_bf16_f32 v22, v28, v29
	v_accvgpr_read_b32 v30, a30
	v_accvgpr_read_b32 v31, a31
	v_cvt_pk_bf16_f32 v23, v30, v31
	v_cndmask_b32_e32 v24, v16, v18, vcc
	v_cndmask_b32_e32 v25, v17, v19, vcc
	v_cndmask_b32_e32 v26, v20, v22, vcc
	ds_bpermute_b32 v24, v194, v24
	ds_bpermute_b32 v25, v194, v25
	v_cndmask_b32_e32 v27, v21, v23, vcc
	ds_bpermute_b32 v26, v194, v26
	ds_bpermute_b32 v27, v194, v27
	v_accvgpr_read_b32 v0, a0
	s_waitcnt lgkmcnt(3)
	v_cndmask_b32_e32 v16, v24, v16, vcc
	s_waitcnt lgkmcnt(2)
	v_cndmask_b32_e32 v17, v25, v17, vcc
	v_cndmask_b32_e32 v18, v18, v24, vcc
	v_cndmask_b32_e32 v19, v19, v25, vcc
	v_accvgpr_read_b32 v1, a1
	s_waitcnt lgkmcnt(1)
	v_cndmask_b32_e32 v20, v26, v20, vcc
	s_waitcnt lgkmcnt(0)
	v_cndmask_b32_e32 v21, v27, v21, vcc
	v_cndmask_b32_e32 v22, v22, v26, vcc
	v_cndmask_b32_e32 v23, v23, v27, vcc
	global_store_dwordx4 v[160:161], v[16:19], off offset:192
	global_store_dwordx4 v[160:161], v[20:23], off offset:208
	v_accvgpr_read_b32 v2, a2
	v_cvt_pk_bf16_f32 v0, v0, v1
	v_accvgpr_read_b32 v3, a3
	v_cvt_pk_bf16_f32 v1, v2, v3
	v_accvgpr_read_b32 v4, a4
	v_accvgpr_read_b32 v5, a5
	v_cvt_pk_bf16_f32 v4, v4, v5
	v_accvgpr_read_b32 v6, a6
	v_accvgpr_read_b32 v7, a7
	v_cvt_pk_bf16_f32 v5, v6, v7
	v_accvgpr_read_b32 v8, a8
	v_accvgpr_read_b32 v9, a9
	v_cvt_pk_bf16_f32 v2, v8, v9
	v_accvgpr_read_b32 v10, a10
	v_accvgpr_read_b32 v11, a11
	v_cvt_pk_bf16_f32 v3, v10, v11
	v_accvgpr_read_b32 v12, a12
	v_accvgpr_read_b32 v13, a13
	v_cvt_pk_bf16_f32 v6, v12, v13
	v_accvgpr_read_b32 v14, a14
	v_accvgpr_read_b32 v15, a15
	v_cvt_pk_bf16_f32 v7, v14, v15
	v_cndmask_b32_e32 v8, v0, v2, vcc
	v_cndmask_b32_e32 v9, v1, v3, vcc
	v_cndmask_b32_e32 v10, v4, v6, vcc
	v_cndmask_b32_e32 v11, v5, v7, vcc
	ds_bpermute_b32 v8, v194, v8
	ds_bpermute_b32 v9, v194, v9
	ds_bpermute_b32 v10, v194, v10
	ds_bpermute_b32 v11, v194, v11
	v_readlane_b32 s1, v255, 6
	s_add_i32 s0, s0, s1
	v_readlane_b32 s8, v254, 28
	s_waitcnt lgkmcnt(3)
	v_cndmask_b32_e32 v0, v8, v0, vcc
	s_waitcnt lgkmcnt(2)
	v_cndmask_b32_e32 v1, v9, v1, vcc
	v_cndmask_b32_e32 v2, v2, v8, vcc
	v_cndmask_b32_e32 v3, v3, v9, vcc
	s_waitcnt lgkmcnt(1)
	v_cndmask_b32_e32 v4, v10, v4, vcc
	s_waitcnt lgkmcnt(0)
	v_cndmask_b32_e32 v5, v11, v5, vcc
	v_cndmask_b32_e32 v6, v6, v10, vcc
	v_cndmask_b32_e32 v7, v7, v11, vcc
	s_cmp_ge_i32 s0, s8
	global_store_dwordx4 v[144:145], v[0:3], off offset:192
	global_store_dwordx4 v[144:145], v[4:7], off offset:208
	s_cbranch_scc1 .LBB0_126

.LBB0_129:
	s_nop 4
	v_accvgpr_read_b32 v127, a15
	v_accvgpr_read_b32 v112, a0
	v_accvgpr_read_b32 v113, a1
	v_mfma_f32_32x32x16_bf16 a[16:31], v[132:135], v[128:131], a[16:31]
	v_cvt_pk_bf16_f32 v112, v112, v113
	v_accvgpr_read_b32 v114, a2
	v_accvgpr_read_b32 v115, a3
	v_cvt_pk_bf16_f32 v113, v114, v115
	v_accvgpr_read_b32 v116, a4
	v_accvgpr_read_b32 v117, a5
	v_cvt_pk_bf16_f32 v129, v116, v117
	v_accvgpr_read_b32 v118, a6
	v_accvgpr_read_b32 v119, a7
	v_cvt_pk_bf16_f32 v119, v118, v119
	v_accvgpr_read_b32 v120, a8
	v_accvgpr_read_b32 v121, a9
	v_cvt_pk_bf16_f32 v116, v120, v121
	v_accvgpr_read_b32 v122, a10
	v_accvgpr_read_b32 v123, a11
	v_cvt_pk_bf16_f32 v117, v122, v123
	v_accvgpr_read_b32 v124, a12
	v_accvgpr_read_b32 v125, a13
	v_cvt_pk_bf16_f32 v120, v124, v125
	v_accvgpr_read_b32 v126, a14
	v_cvt_pk_bf16_f32 v121, v126, v127
	v_or_b32_e32 v128, s2, v137
	v_cmp_lt_i32_e32 vcc, v211, v210
	v_and_b32_e32 v114, 63, v136
	v_mfma_f32_32x32x16_bf16 a[32:47], v[132:135], v[40:43], a[32:47]
	v_add_u32_e32 v132, v128, v139
	v_cndmask_b32_e32 v128, v209, v211, vcc
	v_cmp_gt_u32_e32 vcc, 32, v114
	v_lshlrev_b32_e32 v128, 2, v128
	v_or_b32_e32 v130, s1, v138
	v_cndmask_b32_e32 v114, v112, v116, vcc
	v_cndmask_b32_e32 v115, v113, v117, vcc
	ds_bpermute_b32 v122, v128, v114
	ds_bpermute_b32 v123, v128, v115
	v_cndmask_b32_e32 v118, v129, v120, vcc
	v_cndmask_b32_e32 v114, v119, v121, vcc
	ds_bpermute_b32 v124, v128, v118
	ds_bpermute_b32 v125, v128, v114
	v_ashrrev_i32_e32 v133, 31, v132
	v_readlane_b32 s2, v253, 43
	v_ashrrev_i32_e32 v131, 31, v130
	s_waitcnt lgkmcnt(3)
	v_cndmask_b32_e32 v114, v122, v112, vcc
	s_waitcnt lgkmcnt(2)
	v_cndmask_b32_e32 v115, v123, v113, vcc
	v_lshlrev_b64 v[112:113], 11, v[132:133]
	v_readlane_b32 s3, v253, 44
	v_cndmask_b32_e32 v116, v116, v122, vcc
	v_cndmask_b32_e32 v117, v117, v123, vcc
	v_lshl_add_u64 v[112:113], s[2:3], 0, v[112:113]
	v_lshlrev_b64 v[122:123], 1, v[130:131]
	v_accvgpr_read_b32 v111, a63
	v_lshl_add_u64 v[112:113], v[112:113], 0, v[122:123]
	v_and_b32_e32 v192, 32, v136
	v_accvgpr_read_b32 v96, a48
	v_lshl_add_u64 v[112:113], v[112:113], 0, v[192:193]
	v_accvgpr_read_b32 v97, a49
	s_waitcnt lgkmcnt(1)
	v_cndmask_b32_e32 v118, v124, v129, vcc
	s_waitcnt lgkmcnt(0)
	v_cndmask_b32_e32 v119, v125, v119, vcc
	v_cndmask_b32_e32 v120, v120, v124, vcc
	v_cndmask_b32_e32 v121, v121, v125, vcc
	global_store_dwordx4 v[112:113], v[114:117], off
	global_store_dwordx4 v[112:113], v[118:121], off offset:16
	v_accvgpr_read_b32 v98, a50
	v_cvt_pk_bf16_f32 v97, v96, v97
	v_accvgpr_read_b32 v99, a51
	v_cvt_pk_bf16_f32 v99, v98, v99
	v_accvgpr_read_b32 v100, a52
	v_accvgpr_read_b32 v101, a53
	v_cvt_pk_bf16_f32 v114, v100, v101
	v_accvgpr_read_b32 v102, a54
	v_accvgpr_read_b32 v103, a55
	v_cvt_pk_bf16_f32 v103, v102, v103
	v_accvgpr_read_b32 v104, a56
	v_accvgpr_read_b32 v105, a57
	v_cvt_pk_bf16_f32 v100, v104, v105
	v_accvgpr_read_b32 v106, a58
	v_accvgpr_read_b32 v107, a59
	v_cvt_pk_bf16_f32 v101, v106, v107
	v_accvgpr_read_b32 v108, a60
	v_accvgpr_read_b32 v109, a61
	v_cvt_pk_bf16_f32 v104, v108, v109
	v_accvgpr_read_b32 v110, a62
	v_cvt_pk_bf16_f32 v105, v110, v111
	v_cndmask_b32_e32 v98, v97, v100, vcc
	ds_bpermute_b32 v107, v128, v98
	v_cndmask_b32_e32 v102, v99, v101, vcc
	v_or_b32_e32 v96, 32, v132
	v_cndmask_b32_e32 v106, v114, v104, vcc
	ds_bpermute_b32 v102, v128, v102
	v_cndmask_b32_e32 v98, v103, v105, vcc
	ds_bpermute_b32 v106, v128, v106
	ds_bpermute_b32 v108, v128, v98
	s_waitcnt lgkmcnt(3)
	v_cndmask_b32_e32 v98, v107, v97, vcc
	v_ashrrev_i32_e32 v97, 31, v96
	v_lshlrev_b64 v[96:97], 11, v[96:97]
	v_lshl_add_u64 v[96:97], s[2:3], 0, v[96:97]
	v_accvgpr_read_b32 v95, a79
	v_lshl_add_u64 v[96:97], v[96:97], 0, v[122:123]
	v_accvgpr_read_b32 v80, a64
	s_waitcnt lgkmcnt(2)
	v_cndmask_b32_e32 v99, v102, v99, vcc
	v_cndmask_b32_e32 v100, v100, v107, vcc
	v_cndmask_b32_e32 v101, v101, v102, vcc
	v_lshl_add_u64 v[96:97], v[96:97], 0, v[192:193]
	v_accvgpr_read_b32 v81, a65
	s_waitcnt lgkmcnt(1)
	v_cndmask_b32_e32 v102, v106, v114, vcc
	s_waitcnt lgkmcnt(0)
	v_cndmask_b32_e32 v103, v108, v103, vcc
	v_cndmask_b32_e32 v104, v104, v106, vcc
	v_cndmask_b32_e32 v105, v105, v108, vcc
	global_store_dwordx4 v[96:97], v[98:101], off
	global_store_dwordx4 v[96:97], v[102:105], off offset:16
	v_accvgpr_read_b32 v82, a66
	v_cvt_pk_bf16_f32 v80, v80, v81
	v_accvgpr_read_b32 v83, a67
	v_cvt_pk_bf16_f32 v81, v82, v83
	v_accvgpr_read_b32 v84, a68
	v_accvgpr_read_b32 v85, a69
	v_cvt_pk_bf16_f32 v84, v84, v85
	v_accvgpr_read_b32 v86, a70
	v_accvgpr_read_b32 v87, a71
	v_cvt_pk_bf16_f32 v85, v86, v87
	v_accvgpr_read_b32 v88, a72
	v_accvgpr_read_b32 v89, a73
	v_cvt_pk_bf16_f32 v82, v88, v89
	v_accvgpr_read_b32 v90, a74
	v_accvgpr_read_b32 v91, a75
	v_cvt_pk_bf16_f32 v83, v90, v91
	v_accvgpr_read_b32 v92, a76
	v_accvgpr_read_b32 v93, a77
	v_cvt_pk_bf16_f32 v86, v92, v93
	v_accvgpr_read_b32 v94, a78
	v_cvt_pk_bf16_f32 v87, v94, v95
	v_cndmask_b32_e32 v88, v80, v82, vcc
	v_cndmask_b32_e32 v89, v81, v83, vcc
	v_cndmask_b32_e32 v90, v84, v86, vcc
	ds_bpermute_b32 v88, v128, v88
	ds_bpermute_b32 v89, v128, v89
	v_cndmask_b32_e32 v91, v85, v87, vcc
	ds_bpermute_b32 v90, v128, v90
	ds_bpermute_b32 v91, v128, v91
	v_accvgpr_read_b32 v64, a80
	s_waitcnt lgkmcnt(3)
	v_cndmask_b32_e32 v80, v88, v80, vcc
	s_waitcnt lgkmcnt(2)
	v_cndmask_b32_e32 v81, v89, v81, vcc
	v_cndmask_b32_e32 v82, v82, v88, vcc
	v_cndmask_b32_e32 v83, v83, v89, vcc
	v_accvgpr_read_b32 v65, a81
	s_waitcnt lgkmcnt(1)
	v_cndmask_b32_e32 v84, v90, v84, vcc
	s_waitcnt lgkmcnt(0)
	v_cndmask_b32_e32 v85, v91, v85, vcc
	v_cndmask_b32_e32 v86, v86, v90, vcc
	v_cndmask_b32_e32 v87, v87, v91, vcc
	global_store_dwordx4 v[112:113], v[80:83], off offset:64
	global_store_dwordx4 v[112:113], v[84:87], off offset:80
	v_accvgpr_read_b32 v66, a82
	v_cvt_pk_bf16_f32 v64, v64, v65
	v_accvgpr_read_b32 v67, a83
	v_cvt_pk_bf16_f32 v65, v66, v67
	v_accvgpr_read_b32 v68, a84
	v_accvgpr_read_b32 v69, a85
	v_cvt_pk_bf16_f32 v68, v68, v69
	v_accvgpr_read_b32 v70, a86
	v_accvgpr_read_b32 v71, a87
	v_cvt_pk_bf16_f32 v69, v70, v71
	v_accvgpr_read_b32 v72, a88
	v_accvgpr_read_b32 v73, a89
	v_cvt_pk_bf16_f32 v66, v72, v73
	v_accvgpr_read_b32 v74, a90
	v_accvgpr_read_b32 v75, a91
	v_cvt_pk_bf16_f32 v67, v74, v75
	v_accvgpr_read_b32 v76, a92
	v_accvgpr_read_b32 v77, a93
	v_cvt_pk_bf16_f32 v70, v76, v77
	v_accvgpr_read_b32 v78, a94
	v_accvgpr_read_b32 v79, a95
	v_cvt_pk_bf16_f32 v71, v78, v79
	v_cndmask_b32_e32 v72, v64, v66, vcc
	v_cndmask_b32_e32 v73, v65, v67, vcc
	v_cndmask_b32_e32 v74, v68, v70, vcc
	ds_bpermute_b32 v72, v128, v72
	ds_bpermute_b32 v73, v128, v73
	v_cndmask_b32_e32 v75, v69, v71, vcc
	ds_bpermute_b32 v74, v128, v74
	ds_bpermute_b32 v75, v128, v75
	v_accvgpr_read_b32 v48, a96
	s_waitcnt lgkmcnt(3)
	v_cndmask_b32_e32 v64, v72, v64, vcc
	s_waitcnt lgkmcnt(2)
	v_cndmask_b32_e32 v65, v73, v65, vcc
	v_cndmask_b32_e32 v66, v66, v72, vcc
	v_cndmask_b32_e32 v67, v67, v73, vcc
	v_accvgpr_read_b32 v49, a97
	s_waitcnt lgkmcnt(1)
	v_cndmask_b32_e32 v68, v74, v68, vcc
	s_waitcnt lgkmcnt(0)
	v_cndmask_b32_e32 v69, v75, v69, vcc
	v_cndmask_b32_e32 v70, v70, v74, vcc
	v_cndmask_b32_e32 v71, v71, v75, vcc
	global_store_dwordx4 v[96:97], v[64:67], off offset:64
	global_store_dwordx4 v[96:97], v[68:71], off offset:80
	v_accvgpr_read_b32 v50, a98
	v_cvt_pk_bf16_f32 v48, v48, v49
	v_accvgpr_read_b32 v51, a99
	v_cvt_pk_bf16_f32 v49, v50, v51
	v_accvgpr_read_b32 v52, a100
	v_accvgpr_read_b32 v53, a101
	v_cvt_pk_bf16_f32 v52, v52, v53
	v_accvgpr_read_b32 v54, a102
	v_accvgpr_read_b32 v55, a103
	v_cvt_pk_bf16_f32 v53, v54, v55
	v_accvgpr_read_b32 v56, a104
	v_accvgpr_read_b32 v57, a105
	v_cvt_pk_bf16_f32 v50, v56, v57
	v_accvgpr_read_b32 v58, a106
	v_accvgpr_read_b32 v59, a107
	v_cvt_pk_bf16_f32 v51, v58, v59
	v_accvgpr_read_b32 v60, a108
	v_accvgpr_read_b32 v61, a109
	v_cvt_pk_bf16_f32 v54, v60, v61
	v_accvgpr_read_b32 v62, a110
	v_accvgpr_read_b32 v63, a111
	v_cvt_pk_bf16_f32 v55, v62, v63
	v_cndmask_b32_e32 v56, v48, v50, vcc
	v_cndmask_b32_e32 v57, v49, v51, vcc
	v_cndmask_b32_e32 v58, v52, v54, vcc
	ds_bpermute_b32 v56, v128, v56
	ds_bpermute_b32 v57, v128, v57
	v_cndmask_b32_e32 v59, v53, v55, vcc
	ds_bpermute_b32 v58, v128, v58
	ds_bpermute_b32 v59, v128, v59
	v_accvgpr_read_b32 v32, a112
	s_waitcnt lgkmcnt(3)
	v_cndmask_b32_e32 v48, v56, v48, vcc
	s_waitcnt lgkmcnt(2)
	v_cndmask_b32_e32 v49, v57, v49, vcc
	v_cndmask_b32_e32 v50, v50, v56, vcc
	v_cndmask_b32_e32 v51, v51, v57, vcc
	v_accvgpr_read_b32 v33, a113
	s_waitcnt lgkmcnt(1)
	v_cndmask_b32_e32 v52, v58, v52, vcc
	s_waitcnt lgkmcnt(0)
	v_cndmask_b32_e32 v53, v59, v53, vcc
	v_cndmask_b32_e32 v54, v54, v58, vcc
	v_cndmask_b32_e32 v55, v55, v59, vcc
	global_store_dwordx4 v[112:113], v[48:51], off offset:128
	global_store_dwordx4 v[112:113], v[52:55], off offset:144
	v_accvgpr_read_b32 v34, a114
	v_cvt_pk_bf16_f32 v32, v32, v33
	v_accvgpr_read_b32 v35, a115
	v_cvt_pk_bf16_f32 v33, v34, v35
	v_accvgpr_read_b32 v36, a116
	v_accvgpr_read_b32 v37, a117
	v_cvt_pk_bf16_f32 v36, v36, v37
	v_accvgpr_read_b32 v38, a118
	v_accvgpr_read_b32 v39, a119
	v_cvt_pk_bf16_f32 v37, v38, v39
	v_accvgpr_read_b32 v40, a120
	v_accvgpr_read_b32 v41, a121
	v_cvt_pk_bf16_f32 v34, v40, v41
	v_accvgpr_read_b32 v42, a122
	v_accvgpr_read_b32 v43, a123
	v_cvt_pk_bf16_f32 v35, v42, v43
	v_accvgpr_read_b32 v44, a124
	v_accvgpr_read_b32 v45, a125
	v_cvt_pk_bf16_f32 v38, v44, v45
	v_accvgpr_read_b32 v46, a126
	v_accvgpr_read_b32 v47, a127
	v_cvt_pk_bf16_f32 v39, v46, v47
	v_cndmask_b32_e32 v40, v32, v34, vcc
	v_cndmask_b32_e32 v41, v33, v35, vcc
	v_cndmask_b32_e32 v42, v36, v38, vcc
	ds_bpermute_b32 v40, v128, v40
	ds_bpermute_b32 v41, v128, v41
	v_cndmask_b32_e32 v43, v37, v39, vcc
	ds_bpermute_b32 v42, v128, v42
	ds_bpermute_b32 v43, v128, v43
	s_waitcnt vmcnt(10)
	v_accvgpr_read_b32 v16, a32
	s_waitcnt lgkmcnt(3)
	v_cndmask_b32_e32 v32, v40, v32, vcc
	s_waitcnt lgkmcnt(2)
	v_cndmask_b32_e32 v33, v41, v33, vcc
	v_cndmask_b32_e32 v34, v34, v40, vcc
	v_cndmask_b32_e32 v35, v35, v41, vcc
	v_accvgpr_read_b32 v17, a33
	s_waitcnt lgkmcnt(1)
	v_cndmask_b32_e32 v36, v42, v36, vcc
	s_waitcnt lgkmcnt(0)
	v_cndmask_b32_e32 v37, v43, v37, vcc
	v_cndmask_b32_e32 v38, v38, v42, vcc
	v_cndmask_b32_e32 v39, v39, v43, vcc
	global_store_dwordx4 v[96:97], v[32:35], off offset:128
	global_store_dwordx4 v[96:97], v[36:39], off offset:144
	v_accvgpr_read_b32 v18, a34
	v_cvt_pk_bf16_f32 v16, v16, v17
	v_accvgpr_read_b32 v19, a35
	v_cvt_pk_bf16_f32 v17, v18, v19
	v_accvgpr_read_b32 v20, a36
	v_accvgpr_read_b32 v21, a37
	v_cvt_pk_bf16_f32 v20, v20, v21
	v_accvgpr_read_b32 v22, a38
	v_accvgpr_read_b32 v23, a39
	v_cvt_pk_bf16_f32 v21, v22, v23
	v_accvgpr_read_b32 v24, a40
	v_accvgpr_read_b32 v25, a41
	v_cvt_pk_bf16_f32 v18, v24, v25
	v_accvgpr_read_b32 v26, a42
	v_accvgpr_read_b32 v27, a43
	v_cvt_pk_bf16_f32 v19, v26, v27
	v_accvgpr_read_b32 v28, a44
	v_accvgpr_read_b32 v29, a45
	v_cvt_pk_bf16_f32 v22, v28, v29
	v_accvgpr_read_b32 v30, a46
	v_accvgpr_read_b32 v31, a47
	v_cvt_pk_bf16_f32 v23, v30, v31
	v_cndmask_b32_e32 v24, v16, v18, vcc
	v_cndmask_b32_e32 v25, v17, v19, vcc
	v_cndmask_b32_e32 v26, v20, v22, vcc
	ds_bpermute_b32 v24, v128, v24
	ds_bpermute_b32 v25, v128, v25
	v_cndmask_b32_e32 v27, v21, v23, vcc
	ds_bpermute_b32 v26, v128, v26
	ds_bpermute_b32 v27, v128, v27
	v_accvgpr_read_b32 v0, a16
	s_waitcnt lgkmcnt(3)
	v_cndmask_b32_e32 v16, v24, v16, vcc
	s_waitcnt lgkmcnt(2)
	v_cndmask_b32_e32 v17, v25, v17, vcc
	v_cndmask_b32_e32 v18, v18, v24, vcc
	v_cndmask_b32_e32 v19, v19, v25, vcc
	v_accvgpr_read_b32 v1, a17
	s_waitcnt lgkmcnt(1)
	v_cndmask_b32_e32 v20, v26, v20, vcc
	s_waitcnt lgkmcnt(0)
	v_cndmask_b32_e32 v21, v27, v21, vcc
	v_cndmask_b32_e32 v22, v22, v26, vcc
	v_cndmask_b32_e32 v23, v23, v27, vcc
	global_store_dwordx4 v[112:113], v[16:19], off offset:192
	global_store_dwordx4 v[112:113], v[20:23], off offset:208
	v_accvgpr_read_b32 v2, a18
	v_cvt_pk_bf16_f32 v0, v0, v1
	v_accvgpr_read_b32 v3, a19
	v_cvt_pk_bf16_f32 v1, v2, v3
	v_accvgpr_read_b32 v4, a20
	v_accvgpr_read_b32 v5, a21
	v_cvt_pk_bf16_f32 v4, v4, v5
	v_accvgpr_read_b32 v6, a22
	v_accvgpr_read_b32 v7, a23
	v_cvt_pk_bf16_f32 v5, v6, v7
	v_accvgpr_read_b32 v8, a24
	v_accvgpr_read_b32 v9, a25
	v_cvt_pk_bf16_f32 v2, v8, v9
	v_accvgpr_read_b32 v10, a26
	v_accvgpr_read_b32 v11, a27
	v_cvt_pk_bf16_f32 v3, v10, v11
	v_accvgpr_read_b32 v12, a28
	v_accvgpr_read_b32 v13, a29
	v_cvt_pk_bf16_f32 v6, v12, v13
	v_accvgpr_read_b32 v14, a30
	v_accvgpr_read_b32 v15, a31
	v_cvt_pk_bf16_f32 v7, v14, v15
	v_cndmask_b32_e32 v8, v0, v2, vcc
	v_cndmask_b32_e32 v9, v1, v3, vcc
	v_cndmask_b32_e32 v10, v4, v6, vcc
	v_cndmask_b32_e32 v11, v5, v7, vcc
	ds_bpermute_b32 v8, v128, v8
	ds_bpermute_b32 v9, v128, v9
	ds_bpermute_b32 v10, v128, v10
	ds_bpermute_b32 v11, v128, v11
	s_add_i32 s0, s0, s93
	s_waitcnt lgkmcnt(3)
	v_cndmask_b32_e32 v0, v8, v0, vcc
	s_waitcnt lgkmcnt(2)
	v_cndmask_b32_e32 v1, v9, v1, vcc
	v_cndmask_b32_e32 v2, v2, v8, vcc
	v_cndmask_b32_e32 v3, v3, v9, vcc
	s_waitcnt lgkmcnt(1)
	v_cndmask_b32_e32 v4, v10, v4, vcc
	s_waitcnt lgkmcnt(0)
	v_cndmask_b32_e32 v5, v11, v5, vcc
	v_cndmask_b32_e32 v6, v6, v10, vcc
	v_cndmask_b32_e32 v7, v7, v11, vcc
	s_cmpk_gt_i32 s0, 0x8f
	global_store_dwordx4 v[96:97], v[0:3], off offset:192
	global_store_dwordx4 v[96:97], v[4:7], off offset:208
	s_cbranch_scc1 .LBB0_135

.LBB0_139:
	s_nop 4
	v_accvgpr_read_b32 v127, a47
	v_accvgpr_read_b32 v112, a32
	v_accvgpr_read_b32 v113, a33
	v_mfma_f32_32x32x16_bf16 a[0:15], v[132:135], v[128:131], a[0:15]
	v_cvt_pk_bf16_f32 v112, v112, v113
	v_accvgpr_read_b32 v114, a34
	v_accvgpr_read_b32 v115, a35
	v_cvt_pk_bf16_f32 v113, v114, v115
	v_accvgpr_read_b32 v116, a36
	v_accvgpr_read_b32 v117, a37
	v_cvt_pk_bf16_f32 v129, v116, v117
	v_accvgpr_read_b32 v118, a38
	v_accvgpr_read_b32 v119, a39
	v_cvt_pk_bf16_f32 v119, v118, v119
	v_accvgpr_read_b32 v120, a40
	v_accvgpr_read_b32 v121, a41
	v_cvt_pk_bf16_f32 v116, v120, v121
	v_accvgpr_read_b32 v122, a42
	v_accvgpr_read_b32 v123, a43
	v_cvt_pk_bf16_f32 v117, v122, v123
	v_accvgpr_read_b32 v124, a44
	v_accvgpr_read_b32 v125, a45
	v_cvt_pk_bf16_f32 v120, v124, v125
	v_accvgpr_read_b32 v126, a46
	v_cvt_pk_bf16_f32 v121, v126, v127
	v_or_b32_e32 v128, s2, v137
	v_cmp_lt_i32_e32 vcc, v211, v210
	v_and_b32_e32 v114, 63, v136
	v_mfma_f32_32x32x16_bf16 a[16:31], v[132:135], v[40:43], a[16:31]
	v_add_u32_e32 v132, v128, v139
	v_cndmask_b32_e32 v128, v209, v211, vcc
	v_cmp_gt_u32_e32 vcc, 32, v114
	v_lshlrev_b32_e32 v128, 2, v128
	v_or_b32_e32 v130, s1, v138
	v_cndmask_b32_e32 v114, v112, v116, vcc
	v_cndmask_b32_e32 v115, v113, v117, vcc
	ds_bpermute_b32 v122, v128, v114
	ds_bpermute_b32 v123, v128, v115
	v_cndmask_b32_e32 v118, v129, v120, vcc
	v_cndmask_b32_e32 v114, v119, v121, vcc
	ds_bpermute_b32 v124, v128, v118
	ds_bpermute_b32 v125, v128, v114
	v_ashrrev_i32_e32 v133, 31, v132
	v_readlane_b32 s2, v253, 43
	v_ashrrev_i32_e32 v131, 31, v130
	s_waitcnt lgkmcnt(3)
	v_cndmask_b32_e32 v114, v122, v112, vcc
	s_waitcnt lgkmcnt(2)
	v_cndmask_b32_e32 v115, v123, v113, vcc
	v_lshlrev_b64 v[112:113], 11, v[132:133]
	v_readlane_b32 s3, v253, 44
	v_cndmask_b32_e32 v116, v116, v122, vcc
	v_cndmask_b32_e32 v117, v117, v123, vcc
	v_lshl_add_u64 v[112:113], s[2:3], 0, v[112:113]
	v_lshlrev_b64 v[122:123], 1, v[130:131]
	v_accvgpr_read_b32 v111, a63
	v_lshl_add_u64 v[112:113], v[112:113], 0, v[122:123]
	v_and_b32_e32 v192, 32, v136
	v_accvgpr_read_b32 v96, a48
	v_lshl_add_u64 v[112:113], v[112:113], 0, v[192:193]
	v_accvgpr_read_b32 v97, a49
	s_waitcnt lgkmcnt(1)
	v_cndmask_b32_e32 v118, v124, v129, vcc
	s_waitcnt lgkmcnt(0)
	v_cndmask_b32_e32 v119, v125, v119, vcc
	v_cndmask_b32_e32 v120, v120, v124, vcc
	v_cndmask_b32_e32 v121, v121, v125, vcc
	global_store_dwordx4 v[112:113], v[114:117], off
	global_store_dwordx4 v[112:113], v[118:121], off offset:16
	v_accvgpr_read_b32 v98, a50
	v_cvt_pk_bf16_f32 v97, v96, v97
	v_accvgpr_read_b32 v99, a51
	v_cvt_pk_bf16_f32 v99, v98, v99
	v_accvgpr_read_b32 v100, a52
	v_accvgpr_read_b32 v101, a53
	v_cvt_pk_bf16_f32 v114, v100, v101
	v_accvgpr_read_b32 v102, a54
	v_accvgpr_read_b32 v103, a55
	v_cvt_pk_bf16_f32 v103, v102, v103
	v_accvgpr_read_b32 v104, a56
	v_accvgpr_read_b32 v105, a57
	v_cvt_pk_bf16_f32 v100, v104, v105
	v_accvgpr_read_b32 v106, a58
	v_accvgpr_read_b32 v107, a59
	v_cvt_pk_bf16_f32 v101, v106, v107
	v_accvgpr_read_b32 v108, a60
	v_accvgpr_read_b32 v109, a61
	v_cvt_pk_bf16_f32 v104, v108, v109
	v_accvgpr_read_b32 v110, a62
	v_cvt_pk_bf16_f32 v105, v110, v111
	v_cndmask_b32_e32 v98, v97, v100, vcc
	ds_bpermute_b32 v107, v128, v98
	v_cndmask_b32_e32 v102, v99, v101, vcc
	v_or_b32_e32 v96, 32, v132
	v_cndmask_b32_e32 v106, v114, v104, vcc
	ds_bpermute_b32 v102, v128, v102
	v_cndmask_b32_e32 v98, v103, v105, vcc
	ds_bpermute_b32 v106, v128, v106
	ds_bpermute_b32 v108, v128, v98
	s_waitcnt lgkmcnt(3)
	v_cndmask_b32_e32 v98, v107, v97, vcc
	v_ashrrev_i32_e32 v97, 31, v96
	v_lshlrev_b64 v[96:97], 11, v[96:97]
	v_lshl_add_u64 v[96:97], s[2:3], 0, v[96:97]
	v_accvgpr_read_b32 v95, a79
	v_lshl_add_u64 v[96:97], v[96:97], 0, v[122:123]
	v_accvgpr_read_b32 v80, a64
	s_waitcnt lgkmcnt(2)
	v_cndmask_b32_e32 v99, v102, v99, vcc
	v_cndmask_b32_e32 v100, v100, v107, vcc
	v_cndmask_b32_e32 v101, v101, v102, vcc
	v_lshl_add_u64 v[96:97], v[96:97], 0, v[192:193]
	v_accvgpr_read_b32 v81, a65
	s_waitcnt lgkmcnt(1)
	v_cndmask_b32_e32 v102, v106, v114, vcc
	s_waitcnt lgkmcnt(0)
	v_cndmask_b32_e32 v103, v108, v103, vcc
	v_cndmask_b32_e32 v104, v104, v106, vcc
	v_cndmask_b32_e32 v105, v105, v108, vcc
	global_store_dwordx4 v[96:97], v[98:101], off
	global_store_dwordx4 v[96:97], v[102:105], off offset:16
	v_accvgpr_read_b32 v82, a66
	v_cvt_pk_bf16_f32 v80, v80, v81
	v_accvgpr_read_b32 v83, a67
	v_cvt_pk_bf16_f32 v81, v82, v83
	v_accvgpr_read_b32 v84, a68
	v_accvgpr_read_b32 v85, a69
	v_cvt_pk_bf16_f32 v84, v84, v85
	v_accvgpr_read_b32 v86, a70
	v_accvgpr_read_b32 v87, a71
	v_cvt_pk_bf16_f32 v85, v86, v87
	v_accvgpr_read_b32 v88, a72
	v_accvgpr_read_b32 v89, a73
	v_cvt_pk_bf16_f32 v82, v88, v89
	v_accvgpr_read_b32 v90, a74
	v_accvgpr_read_b32 v91, a75
	v_cvt_pk_bf16_f32 v83, v90, v91
	v_accvgpr_read_b32 v92, a76
	v_accvgpr_read_b32 v93, a77
	v_cvt_pk_bf16_f32 v86, v92, v93
	v_accvgpr_read_b32 v94, a78
	v_cvt_pk_bf16_f32 v87, v94, v95
	v_cndmask_b32_e32 v88, v80, v82, vcc
	v_cndmask_b32_e32 v89, v81, v83, vcc
	v_cndmask_b32_e32 v90, v84, v86, vcc
	ds_bpermute_b32 v88, v128, v88
	ds_bpermute_b32 v89, v128, v89
	v_cndmask_b32_e32 v91, v85, v87, vcc
	ds_bpermute_b32 v90, v128, v90
	ds_bpermute_b32 v91, v128, v91
	v_accvgpr_read_b32 v64, a80
	s_waitcnt lgkmcnt(3)
	v_cndmask_b32_e32 v80, v88, v80, vcc
	s_waitcnt lgkmcnt(2)
	v_cndmask_b32_e32 v81, v89, v81, vcc
	v_cndmask_b32_e32 v82, v82, v88, vcc
	v_cndmask_b32_e32 v83, v83, v89, vcc
	v_accvgpr_read_b32 v65, a81
	s_waitcnt lgkmcnt(1)
	v_cndmask_b32_e32 v84, v90, v84, vcc
	s_waitcnt lgkmcnt(0)
	v_cndmask_b32_e32 v85, v91, v85, vcc
	v_cndmask_b32_e32 v86, v86, v90, vcc
	v_cndmask_b32_e32 v87, v87, v91, vcc
	global_store_dwordx4 v[112:113], v[80:83], off offset:64
	global_store_dwordx4 v[112:113], v[84:87], off offset:80
	v_accvgpr_read_b32 v66, a82
	v_cvt_pk_bf16_f32 v64, v64, v65
	v_accvgpr_read_b32 v67, a83
	v_cvt_pk_bf16_f32 v65, v66, v67
	v_accvgpr_read_b32 v68, a84
	v_accvgpr_read_b32 v69, a85
	v_cvt_pk_bf16_f32 v68, v68, v69
	v_accvgpr_read_b32 v70, a86
	v_accvgpr_read_b32 v71, a87
	v_cvt_pk_bf16_f32 v69, v70, v71
	v_accvgpr_read_b32 v72, a88
	v_accvgpr_read_b32 v73, a89
	v_cvt_pk_bf16_f32 v66, v72, v73
	v_accvgpr_read_b32 v74, a90
	v_accvgpr_read_b32 v75, a91
	v_cvt_pk_bf16_f32 v67, v74, v75
	v_accvgpr_read_b32 v76, a92
	v_accvgpr_read_b32 v77, a93
	v_cvt_pk_bf16_f32 v70, v76, v77
	v_accvgpr_read_b32 v78, a94
	v_accvgpr_read_b32 v79, a95
	v_cvt_pk_bf16_f32 v71, v78, v79
	v_cndmask_b32_e32 v72, v64, v66, vcc
	v_cndmask_b32_e32 v73, v65, v67, vcc
	v_cndmask_b32_e32 v74, v68, v70, vcc
	ds_bpermute_b32 v72, v128, v72
	ds_bpermute_b32 v73, v128, v73
	v_cndmask_b32_e32 v75, v69, v71, vcc
	ds_bpermute_b32 v74, v128, v74
	ds_bpermute_b32 v75, v128, v75
	v_accvgpr_read_b32 v48, a96
	s_waitcnt lgkmcnt(3)
	v_cndmask_b32_e32 v64, v72, v64, vcc
	s_waitcnt lgkmcnt(2)
	v_cndmask_b32_e32 v65, v73, v65, vcc
	v_cndmask_b32_e32 v66, v66, v72, vcc
	v_cndmask_b32_e32 v67, v67, v73, vcc
	v_accvgpr_read_b32 v49, a97
	s_waitcnt lgkmcnt(1)
	v_cndmask_b32_e32 v68, v74, v68, vcc
	s_waitcnt lgkmcnt(0)
	v_cndmask_b32_e32 v69, v75, v69, vcc
	v_cndmask_b32_e32 v70, v70, v74, vcc
	v_cndmask_b32_e32 v71, v71, v75, vcc
	global_store_dwordx4 v[96:97], v[64:67], off offset:64
	global_store_dwordx4 v[96:97], v[68:71], off offset:80
	v_accvgpr_read_b32 v50, a98
	v_cvt_pk_bf16_f32 v48, v48, v49
	v_accvgpr_read_b32 v51, a99
	v_cvt_pk_bf16_f32 v49, v50, v51
	v_accvgpr_read_b32 v52, a100
	v_accvgpr_read_b32 v53, a101
	v_cvt_pk_bf16_f32 v52, v52, v53
	v_accvgpr_read_b32 v54, a102
	v_accvgpr_read_b32 v55, a103
	v_cvt_pk_bf16_f32 v53, v54, v55
	v_accvgpr_read_b32 v56, a104
	v_accvgpr_read_b32 v57, a105
	v_cvt_pk_bf16_f32 v50, v56, v57
	v_accvgpr_read_b32 v58, a106
	v_accvgpr_read_b32 v59, a107
	v_cvt_pk_bf16_f32 v51, v58, v59
	v_accvgpr_read_b32 v60, a108
	v_accvgpr_read_b32 v61, a109
	v_cvt_pk_bf16_f32 v54, v60, v61
	v_accvgpr_read_b32 v62, a110
	v_accvgpr_read_b32 v63, a111
	v_cvt_pk_bf16_f32 v55, v62, v63
	v_cndmask_b32_e32 v56, v48, v50, vcc
	v_cndmask_b32_e32 v57, v49, v51, vcc
	v_cndmask_b32_e32 v58, v52, v54, vcc
	ds_bpermute_b32 v56, v128, v56
	ds_bpermute_b32 v57, v128, v57
	v_cndmask_b32_e32 v59, v53, v55, vcc
	ds_bpermute_b32 v58, v128, v58
	ds_bpermute_b32 v59, v128, v59
	v_accvgpr_read_b32 v32, a112
	s_waitcnt lgkmcnt(3)
	v_cndmask_b32_e32 v48, v56, v48, vcc
	s_waitcnt lgkmcnt(2)
	v_cndmask_b32_e32 v49, v57, v49, vcc
	v_cndmask_b32_e32 v50, v50, v56, vcc
	v_cndmask_b32_e32 v51, v51, v57, vcc
	v_accvgpr_read_b32 v33, a113
	s_waitcnt lgkmcnt(1)
	v_cndmask_b32_e32 v52, v58, v52, vcc
	s_waitcnt lgkmcnt(0)
	v_cndmask_b32_e32 v53, v59, v53, vcc
	v_cndmask_b32_e32 v54, v54, v58, vcc
	v_cndmask_b32_e32 v55, v55, v59, vcc
	global_store_dwordx4 v[112:113], v[48:51], off offset:128
	global_store_dwordx4 v[112:113], v[52:55], off offset:144
	v_accvgpr_read_b32 v34, a114
	v_cvt_pk_bf16_f32 v32, v32, v33
	v_accvgpr_read_b32 v35, a115
	v_cvt_pk_bf16_f32 v33, v34, v35
	v_accvgpr_read_b32 v36, a116
	v_accvgpr_read_b32 v37, a117
	v_cvt_pk_bf16_f32 v36, v36, v37
	v_accvgpr_read_b32 v38, a118
	v_accvgpr_read_b32 v39, a119
	v_cvt_pk_bf16_f32 v37, v38, v39
	v_accvgpr_read_b32 v40, a120
	v_accvgpr_read_b32 v41, a121
	v_cvt_pk_bf16_f32 v34, v40, v41
	v_accvgpr_read_b32 v42, a122
	v_accvgpr_read_b32 v43, a123
	v_cvt_pk_bf16_f32 v35, v42, v43
	v_accvgpr_read_b32 v44, a124
	v_accvgpr_read_b32 v45, a125
	v_cvt_pk_bf16_f32 v38, v44, v45
	v_accvgpr_read_b32 v46, a126
	v_accvgpr_read_b32 v47, a127
	v_cvt_pk_bf16_f32 v39, v46, v47
	v_cndmask_b32_e32 v40, v32, v34, vcc
	v_cndmask_b32_e32 v41, v33, v35, vcc
	v_cndmask_b32_e32 v42, v36, v38, vcc
	ds_bpermute_b32 v40, v128, v40
	ds_bpermute_b32 v41, v128, v41
	v_cndmask_b32_e32 v43, v37, v39, vcc
	ds_bpermute_b32 v42, v128, v42
	ds_bpermute_b32 v43, v128, v43
	s_waitcnt vmcnt(10)
	v_accvgpr_read_b32 v16, a16
	s_waitcnt lgkmcnt(3)
	v_cndmask_b32_e32 v32, v40, v32, vcc
	s_waitcnt lgkmcnt(2)
	v_cndmask_b32_e32 v33, v41, v33, vcc
	v_cndmask_b32_e32 v34, v34, v40, vcc
	v_cndmask_b32_e32 v35, v35, v41, vcc
	v_accvgpr_read_b32 v17, a17
	s_waitcnt lgkmcnt(1)
	v_cndmask_b32_e32 v36, v42, v36, vcc
	s_waitcnt lgkmcnt(0)
	v_cndmask_b32_e32 v37, v43, v37, vcc
	v_cndmask_b32_e32 v38, v38, v42, vcc
	v_cndmask_b32_e32 v39, v39, v43, vcc
	global_store_dwordx4 v[96:97], v[32:35], off offset:128
	global_store_dwordx4 v[96:97], v[36:39], off offset:144
	v_accvgpr_read_b32 v18, a18
	v_cvt_pk_bf16_f32 v16, v16, v17
	v_accvgpr_read_b32 v19, a19
	v_cvt_pk_bf16_f32 v17, v18, v19
	v_accvgpr_read_b32 v20, a20
	v_accvgpr_read_b32 v21, a21
	v_cvt_pk_bf16_f32 v20, v20, v21
	v_accvgpr_read_b32 v22, a22
	v_accvgpr_read_b32 v23, a23
	v_cvt_pk_bf16_f32 v21, v22, v23
	v_accvgpr_read_b32 v24, a24
	v_accvgpr_read_b32 v25, a25
	v_cvt_pk_bf16_f32 v18, v24, v25
	v_accvgpr_read_b32 v26, a26
	v_accvgpr_read_b32 v27, a27
	v_cvt_pk_bf16_f32 v19, v26, v27
	v_accvgpr_read_b32 v28, a28
	v_accvgpr_read_b32 v29, a29
	v_cvt_pk_bf16_f32 v22, v28, v29
	v_accvgpr_read_b32 v30, a30
	v_accvgpr_read_b32 v31, a31
	v_cvt_pk_bf16_f32 v23, v30, v31
	v_cndmask_b32_e32 v24, v16, v18, vcc
	v_cndmask_b32_e32 v25, v17, v19, vcc
	v_cndmask_b32_e32 v26, v20, v22, vcc
	ds_bpermute_b32 v24, v128, v24
	ds_bpermute_b32 v25, v128, v25
	v_cndmask_b32_e32 v27, v21, v23, vcc
	ds_bpermute_b32 v26, v128, v26
	ds_bpermute_b32 v27, v128, v27
	v_accvgpr_read_b32 v0, a0
	s_waitcnt lgkmcnt(3)
	v_cndmask_b32_e32 v16, v24, v16, vcc
	s_waitcnt lgkmcnt(2)
	v_cndmask_b32_e32 v17, v25, v17, vcc
	v_cndmask_b32_e32 v18, v18, v24, vcc
	v_cndmask_b32_e32 v19, v19, v25, vcc
	v_accvgpr_read_b32 v1, a1
	s_waitcnt lgkmcnt(1)
	v_cndmask_b32_e32 v20, v26, v20, vcc
	s_waitcnt lgkmcnt(0)
	v_cndmask_b32_e32 v21, v27, v21, vcc
	v_cndmask_b32_e32 v22, v22, v26, vcc
	v_cndmask_b32_e32 v23, v23, v27, vcc
	global_store_dwordx4 v[112:113], v[16:19], off offset:192
	global_store_dwordx4 v[112:113], v[20:23], off offset:208
	v_accvgpr_read_b32 v2, a2
	v_cvt_pk_bf16_f32 v0, v0, v1
	v_accvgpr_read_b32 v3, a3
	v_cvt_pk_bf16_f32 v1, v2, v3
	v_accvgpr_read_b32 v4, a4
	v_accvgpr_read_b32 v5, a5
	v_cvt_pk_bf16_f32 v4, v4, v5
	v_accvgpr_read_b32 v6, a6
	v_accvgpr_read_b32 v7, a7
	v_cvt_pk_bf16_f32 v5, v6, v7
	v_accvgpr_read_b32 v8, a8
	v_accvgpr_read_b32 v9, a9
	v_cvt_pk_bf16_f32 v2, v8, v9
	v_accvgpr_read_b32 v10, a10
	v_accvgpr_read_b32 v11, a11
	v_cvt_pk_bf16_f32 v3, v10, v11
	v_accvgpr_read_b32 v12, a12
	v_accvgpr_read_b32 v13, a13
	v_cvt_pk_bf16_f32 v6, v12, v13
	v_accvgpr_read_b32 v14, a14
	v_accvgpr_read_b32 v15, a15
	v_cvt_pk_bf16_f32 v7, v14, v15
	v_cndmask_b32_e32 v8, v0, v2, vcc
	v_cndmask_b32_e32 v9, v1, v3, vcc
	v_cndmask_b32_e32 v10, v4, v6, vcc
	v_cndmask_b32_e32 v11, v5, v7, vcc
	ds_bpermute_b32 v8, v128, v8
	ds_bpermute_b32 v9, v128, v9
	ds_bpermute_b32 v10, v128, v10
	ds_bpermute_b32 v11, v128, v11
	v_readlane_b32 s1, v255, 6
	s_add_i32 s0, s0, s1
	v_readlane_b32 s6, v254, 35
	s_waitcnt lgkmcnt(3)
	v_cndmask_b32_e32 v0, v8, v0, vcc
	s_waitcnt lgkmcnt(2)
	v_cndmask_b32_e32 v1, v9, v1, vcc
	v_cndmask_b32_e32 v2, v2, v8, vcc
	v_cndmask_b32_e32 v3, v3, v9, vcc
	s_waitcnt lgkmcnt(1)
	v_cndmask_b32_e32 v4, v10, v4, vcc
	s_waitcnt lgkmcnt(0)
	v_cndmask_b32_e32 v5, v11, v5, vcc
	v_cndmask_b32_e32 v6, v6, v10, vcc
	v_cndmask_b32_e32 v7, v7, v11, vcc
	s_cmp_ge_i32 s0, s6
	global_store_dwordx4 v[96:97], v[0:3], off offset:192
	global_store_dwordx4 v[96:97], v[4:7], off offset:208
	s_cbranch_scc1 .LBB0_145

.LBB0_193:
	s_nop 1
	v_accvgpr_read_b32 v191, a15
	v_or_b32_e32 v192, s4, v192
	v_cmp_lt_i32_e32 vcc, v211, v210
	v_mfma_f32_32x32x16_bf16 a[48:63], v[198:201], v[40:43], a[48:63]
	v_accvgpr_read_b32 v176, a0
	v_accvgpr_read_b32 v177, a1
	v_accvgpr_read_b32 v178, a2
	v_accvgpr_read_b32 v179, a3
	v_accvgpr_read_b32 v180, a4
	v_accvgpr_read_b32 v181, a5
	v_accvgpr_read_b32 v182, a6
	v_mfma_f32_32x32x16_bf16 a[32:47], v[198:201], v[36:39], a[32:47]
	v_accvgpr_read_b32 v183, a7
	v_accvgpr_read_b32 v184, a8
	v_accvgpr_read_b32 v185, a9
	v_accvgpr_read_b32 v186, a10
	v_accvgpr_read_b32 v187, a11
	v_accvgpr_read_b32 v188, a12
	v_accvgpr_read_b32 v189, a13
	v_mfma_f32_32x32x16_bf16 a[16:31], v[198:201], v[194:197], a[16:31]
	v_add_u32_e32 v198, v205, v192
	v_cndmask_b32_e32 v192, v209, v211, vcc
	v_lshlrev_b32_e32 v194, 2, v192
	v_cvt_pk_bf16_f32 v176, v176, v177
	v_cvt_pk_bf16_f32 v177, v178, v179
	v_cvt_pk_bf16_f32 v192, v180, v181
	v_cvt_pk_bf16_f32 v183, v182, v183
	v_cvt_pk_bf16_f32 v180, v184, v185
	v_cvt_pk_bf16_f32 v181, v186, v187
	v_cvt_pk_bf16_f32 v184, v188, v189
	v_accvgpr_read_b32 v190, a14
	v_cvt_pk_bf16_f32 v185, v190, v191
	v_and_b32_e32 v178, 63, v203
	v_cmp_gt_u32_e32 vcc, 32, v178
	v_or_b32_e32 v196, s1, v204
	v_ashrrev_i32_e32 v199, 31, v198
	v_cndmask_b32_e32 v178, v176, v180, vcc
	v_cndmask_b32_e32 v179, v177, v181, vcc
	ds_bpermute_b32 v186, v194, v178
	ds_bpermute_b32 v187, v194, v179
	v_cndmask_b32_e32 v182, v192, v184, vcc
	ds_bpermute_b32 v188, v194, v182
	v_cndmask_b32_e32 v178, v183, v185, vcc
	ds_bpermute_b32 v189, v194, v178
	v_readlane_b32 s4, v253, 43
	v_ashrrev_i32_e32 v197, 31, v196
	s_waitcnt lgkmcnt(3)
	v_cndmask_b32_e32 v178, v186, v176, vcc
	s_waitcnt lgkmcnt(2)
	v_cndmask_b32_e32 v179, v187, v177, vcc
	v_lshlrev_b64 v[176:177], 11, v[198:199]
	v_readlane_b32 s5, v253, 44
	v_cndmask_b32_e32 v180, v180, v186, vcc
	v_cndmask_b32_e32 v181, v181, v187, vcc
	v_lshl_add_u64 v[176:177], s[4:5], 0, v[176:177]
	v_lshlrev_b64 v[186:187], 1, v[196:197]
	v_accvgpr_read_b32 v175, a79
	s_waitcnt lgkmcnt(1)
	v_cndmask_b32_e32 v182, v188, v192, vcc
	v_lshl_add_u64 v[176:177], v[176:177], 0, v[186:187]
	v_and_b32_e32 v192, 32, v203
	v_accvgpr_read_b32 v160, a64
	v_lshl_add_u64 v[176:177], v[176:177], 0, v[192:193]
	v_accvgpr_read_b32 v161, a65
	s_waitcnt lgkmcnt(0)
	v_cndmask_b32_e32 v183, v189, v183, vcc
	v_cndmask_b32_e32 v184, v184, v188, vcc
	v_cndmask_b32_e32 v185, v185, v189, vcc
	global_store_dwordx4 v[176:177], v[178:181], off
	global_store_dwordx4 v[176:177], v[182:185], off offset:16
	v_accvgpr_read_b32 v162, a66
	v_cvt_pk_bf16_f32 v161, v160, v161
	v_accvgpr_read_b32 v163, a67
	v_cvt_pk_bf16_f32 v163, v162, v163
	v_accvgpr_read_b32 v164, a68
	v_accvgpr_read_b32 v165, a69
	v_cvt_pk_bf16_f32 v178, v164, v165
	v_accvgpr_read_b32 v166, a70
	v_accvgpr_read_b32 v167, a71
	v_cvt_pk_bf16_f32 v167, v166, v167
	v_accvgpr_read_b32 v168, a72
	v_accvgpr_read_b32 v169, a73
	v_cvt_pk_bf16_f32 v164, v168, v169
	v_accvgpr_read_b32 v170, a74
	v_accvgpr_read_b32 v171, a75
	v_cvt_pk_bf16_f32 v165, v170, v171
	v_accvgpr_read_b32 v172, a76
	v_accvgpr_read_b32 v173, a77
	v_cvt_pk_bf16_f32 v168, v172, v173
	v_accvgpr_read_b32 v174, a78
	v_cvt_pk_bf16_f32 v169, v174, v175
	v_cndmask_b32_e32 v162, v161, v164, vcc
	ds_bpermute_b32 v171, v194, v162
	v_cndmask_b32_e32 v166, v163, v165, vcc
	v_add_u32_e32 v160, 32, v198
	v_cndmask_b32_e32 v170, v178, v168, vcc
	ds_bpermute_b32 v166, v194, v166
	v_cndmask_b32_e32 v162, v167, v169, vcc
	ds_bpermute_b32 v170, v194, v170
	ds_bpermute_b32 v172, v194, v162
	s_waitcnt lgkmcnt(3)
	v_cndmask_b32_e32 v162, v171, v161, vcc
	v_ashrrev_i32_e32 v161, 31, v160
	v_lshlrev_b64 v[160:161], 11, v[160:161]
	v_lshl_add_u64 v[160:161], s[4:5], 0, v[160:161]
	v_accvgpr_read_b32 v159, a95
	v_lshl_add_u64 v[160:161], v[160:161], 0, v[186:187]
	v_accvgpr_read_b32 v144, a80
	s_waitcnt lgkmcnt(2)
	v_cndmask_b32_e32 v163, v166, v163, vcc
	v_cndmask_b32_e32 v164, v164, v171, vcc
	v_cndmask_b32_e32 v165, v165, v166, vcc
	v_lshl_add_u64 v[160:161], v[160:161], 0, v[192:193]
	v_accvgpr_read_b32 v145, a81
	s_waitcnt lgkmcnt(1)
	v_cndmask_b32_e32 v166, v170, v178, vcc
	s_waitcnt lgkmcnt(0)
	v_cndmask_b32_e32 v167, v172, v167, vcc
	v_cndmask_b32_e32 v168, v168, v170, vcc
	v_cndmask_b32_e32 v169, v169, v172, vcc
	global_store_dwordx4 v[160:161], v[162:165], off
	global_store_dwordx4 v[160:161], v[166:169], off offset:16
	v_accvgpr_read_b32 v146, a82
	v_cvt_pk_bf16_f32 v145, v144, v145
	v_accvgpr_read_b32 v147, a83
	v_cvt_pk_bf16_f32 v147, v146, v147
	v_accvgpr_read_b32 v148, a84
	v_accvgpr_read_b32 v149, a85
	v_cvt_pk_bf16_f32 v162, v148, v149
	v_accvgpr_read_b32 v150, a86
	v_accvgpr_read_b32 v151, a87
	v_cvt_pk_bf16_f32 v151, v150, v151
	v_accvgpr_read_b32 v152, a88
	v_accvgpr_read_b32 v153, a89
	v_cvt_pk_bf16_f32 v148, v152, v153
	v_accvgpr_read_b32 v154, a90
	v_accvgpr_read_b32 v155, a91
	v_cvt_pk_bf16_f32 v149, v154, v155
	v_accvgpr_read_b32 v156, a92
	v_accvgpr_read_b32 v157, a93
	v_cvt_pk_bf16_f32 v152, v156, v157
	v_accvgpr_read_b32 v158, a94
	v_cvt_pk_bf16_f32 v153, v158, v159
	v_cndmask_b32_e32 v146, v145, v148, vcc
	ds_bpermute_b32 v155, v194, v146
	v_cndmask_b32_e32 v150, v147, v149, vcc
	v_add_u32_e32 v144, 64, v198
	v_cndmask_b32_e32 v154, v162, v152, vcc
	ds_bpermute_b32 v150, v194, v150
	v_cndmask_b32_e32 v146, v151, v153, vcc
	ds_bpermute_b32 v154, v194, v154
	ds_bpermute_b32 v156, v194, v146
	s_waitcnt lgkmcnt(3)
	v_cndmask_b32_e32 v146, v155, v145, vcc
	v_ashrrev_i32_e32 v145, 31, v144
	v_lshlrev_b64 v[144:145], 11, v[144:145]
	v_lshl_add_u64 v[144:145], s[4:5], 0, v[144:145]
	v_accvgpr_read_b32 v143, a111
	v_lshl_add_u64 v[144:145], v[144:145], 0, v[186:187]
	v_accvgpr_read_b32 v128, a96
	s_waitcnt lgkmcnt(2)
	v_cndmask_b32_e32 v147, v150, v147, vcc
	v_cndmask_b32_e32 v148, v148, v155, vcc
	v_cndmask_b32_e32 v149, v149, v150, vcc
	v_lshl_add_u64 v[144:145], v[144:145], 0, v[192:193]
	v_accvgpr_read_b32 v129, a97
	s_waitcnt lgkmcnt(1)
	v_cndmask_b32_e32 v150, v154, v162, vcc
	s_waitcnt lgkmcnt(0)
	v_cndmask_b32_e32 v151, v156, v151, vcc
	v_cndmask_b32_e32 v152, v152, v154, vcc
	v_cndmask_b32_e32 v153, v153, v156, vcc
	global_store_dwordx4 v[144:145], v[146:149], off
	global_store_dwordx4 v[144:145], v[150:153], off offset:16
	v_accvgpr_read_b32 v130, a98
	v_cvt_pk_bf16_f32 v128, v128, v129
	v_accvgpr_read_b32 v131, a99
	v_cvt_pk_bf16_f32 v129, v130, v131
	v_accvgpr_read_b32 v132, a100
	v_accvgpr_read_b32 v133, a101
	v_cvt_pk_bf16_f32 v132, v132, v133
	v_accvgpr_read_b32 v134, a102
	v_accvgpr_read_b32 v135, a103
	v_cvt_pk_bf16_f32 v133, v134, v135
	v_accvgpr_read_b32 v136, a104
	v_accvgpr_read_b32 v137, a105
	v_cvt_pk_bf16_f32 v130, v136, v137
	v_accvgpr_read_b32 v138, a106
	v_accvgpr_read_b32 v139, a107
	v_cvt_pk_bf16_f32 v131, v138, v139
	v_accvgpr_read_b32 v140, a108
	v_accvgpr_read_b32 v141, a109
	v_cvt_pk_bf16_f32 v134, v140, v141
	v_accvgpr_read_b32 v142, a110
	v_cvt_pk_bf16_f32 v135, v142, v143
	v_cndmask_b32_e32 v136, v128, v130, vcc
	v_cndmask_b32_e32 v137, v129, v131, vcc
	v_cndmask_b32_e32 v138, v132, v134, vcc
	ds_bpermute_b32 v136, v194, v136
	ds_bpermute_b32 v137, v194, v137
	v_cndmask_b32_e32 v139, v133, v135, vcc
	ds_bpermute_b32 v138, v194, v138
	ds_bpermute_b32 v139, v194, v139
	v_accvgpr_read_b32 v112, a112
	s_waitcnt lgkmcnt(3)
	v_cndmask_b32_e32 v128, v136, v128, vcc
	s_waitcnt lgkmcnt(2)
	v_cndmask_b32_e32 v129, v137, v129, vcc
	v_cndmask_b32_e32 v130, v130, v136, vcc
	v_cndmask_b32_e32 v131, v131, v137, vcc
	v_accvgpr_read_b32 v113, a113
	s_waitcnt lgkmcnt(1)
	v_cndmask_b32_e32 v132, v138, v132, vcc
	s_waitcnt lgkmcnt(0)
	v_cndmask_b32_e32 v133, v139, v133, vcc
	v_cndmask_b32_e32 v134, v134, v138, vcc
	v_cndmask_b32_e32 v135, v135, v139, vcc
	global_store_dwordx4 v[176:177], v[128:131], off offset:64
	global_store_dwordx4 v[176:177], v[132:135], off offset:80
	v_accvgpr_read_b32 v114, a114
	v_cvt_pk_bf16_f32 v112, v112, v113
	v_accvgpr_read_b32 v115, a115
	v_cvt_pk_bf16_f32 v113, v114, v115
	v_accvgpr_read_b32 v116, a116
	v_accvgpr_read_b32 v117, a117
	v_cvt_pk_bf16_f32 v116, v116, v117
	v_accvgpr_read_b32 v118, a118
	v_accvgpr_read_b32 v119, a119
	v_cvt_pk_bf16_f32 v117, v118, v119
	v_accvgpr_read_b32 v120, a120
	v_accvgpr_read_b32 v121, a121
	v_cvt_pk_bf16_f32 v114, v120, v121
	v_accvgpr_read_b32 v122, a122
	v_accvgpr_read_b32 v123, a123
	v_cvt_pk_bf16_f32 v115, v122, v123
	v_accvgpr_read_b32 v124, a124
	v_accvgpr_read_b32 v125, a125
	v_cvt_pk_bf16_f32 v118, v124, v125
	v_accvgpr_read_b32 v126, a126
	v_accvgpr_read_b32 v127, a127
	v_cvt_pk_bf16_f32 v119, v126, v127
	v_cndmask_b32_e32 v120, v112, v114, vcc
	v_cndmask_b32_e32 v121, v113, v115, vcc
	v_cndmask_b32_e32 v122, v116, v118, vcc
	ds_bpermute_b32 v120, v194, v120
	ds_bpermute_b32 v121, v194, v121
	v_cndmask_b32_e32 v123, v117, v119, vcc
	ds_bpermute_b32 v122, v194, v122
	ds_bpermute_b32 v123, v194, v123
	v_accvgpr_read_b32 v96, a128
	s_waitcnt lgkmcnt(3)
	v_cndmask_b32_e32 v112, v120, v112, vcc
	s_waitcnt lgkmcnt(2)
	v_cndmask_b32_e32 v113, v121, v113, vcc
	v_cndmask_b32_e32 v114, v114, v120, vcc
	v_cndmask_b32_e32 v115, v115, v121, vcc
	v_accvgpr_read_b32 v97, a129
	s_waitcnt lgkmcnt(1)
	v_cndmask_b32_e32 v116, v122, v116, vcc
	s_waitcnt lgkmcnt(0)
	v_cndmask_b32_e32 v117, v123, v117, vcc
	v_cndmask_b32_e32 v118, v118, v122, vcc
	v_cndmask_b32_e32 v119, v119, v123, vcc
	global_store_dwordx4 v[160:161], v[112:115], off offset:64
	global_store_dwordx4 v[160:161], v[116:119], off offset:80
	v_accvgpr_read_b32 v98, a130
	v_cvt_pk_bf16_f32 v96, v96, v97
	v_accvgpr_read_b32 v99, a131
	v_cvt_pk_bf16_f32 v97, v98, v99
	v_accvgpr_read_b32 v100, a132
	v_accvgpr_read_b32 v101, a133
	v_cvt_pk_bf16_f32 v100, v100, v101
	v_accvgpr_read_b32 v102, a134
	v_accvgpr_read_b32 v103, a135
	v_cvt_pk_bf16_f32 v101, v102, v103
	v_accvgpr_read_b32 v104, a136
	v_accvgpr_read_b32 v105, a137
	v_cvt_pk_bf16_f32 v98, v104, v105
	v_accvgpr_read_b32 v106, a138
	v_accvgpr_read_b32 v107, a139
	v_cvt_pk_bf16_f32 v99, v106, v107
	v_accvgpr_read_b32 v108, a140
	v_accvgpr_read_b32 v109, a141
	v_cvt_pk_bf16_f32 v102, v108, v109
	v_accvgpr_read_b32 v110, a142
	v_accvgpr_read_b32 v111, a143
	v_cvt_pk_bf16_f32 v103, v110, v111
	v_cndmask_b32_e32 v104, v96, v98, vcc
	v_cndmask_b32_e32 v105, v97, v99, vcc
	v_cndmask_b32_e32 v106, v100, v102, vcc
	ds_bpermute_b32 v104, v194, v104
	ds_bpermute_b32 v105, v194, v105
	v_cndmask_b32_e32 v107, v101, v103, vcc
	ds_bpermute_b32 v106, v194, v106
	ds_bpermute_b32 v107, v194, v107
	v_accvgpr_read_b32 v80, a144
	s_waitcnt lgkmcnt(3)
	v_cndmask_b32_e32 v96, v104, v96, vcc
	s_waitcnt lgkmcnt(2)
	v_cndmask_b32_e32 v97, v105, v97, vcc
	v_cndmask_b32_e32 v98, v98, v104, vcc
	v_cndmask_b32_e32 v99, v99, v105, vcc
	v_accvgpr_read_b32 v81, a145
	s_waitcnt lgkmcnt(1)
	v_cndmask_b32_e32 v100, v106, v100, vcc
	s_waitcnt lgkmcnt(0)
	v_cndmask_b32_e32 v101, v107, v101, vcc
	v_cndmask_b32_e32 v102, v102, v106, vcc
	v_cndmask_b32_e32 v103, v103, v107, vcc
	global_store_dwordx4 v[144:145], v[96:99], off offset:64
	global_store_dwordx4 v[144:145], v[100:103], off offset:80
	v_accvgpr_read_b32 v82, a146
	v_cvt_pk_bf16_f32 v80, v80, v81
	v_accvgpr_read_b32 v83, a147
	v_cvt_pk_bf16_f32 v81, v82, v83
	v_accvgpr_read_b32 v84, a148
	v_accvgpr_read_b32 v85, a149
	v_cvt_pk_bf16_f32 v84, v84, v85
	v_accvgpr_read_b32 v86, a150
	v_accvgpr_read_b32 v87, a151
	v_cvt_pk_bf16_f32 v85, v86, v87
	v_accvgpr_read_b32 v88, a152
	v_accvgpr_read_b32 v89, a153
	v_cvt_pk_bf16_f32 v82, v88, v89
	v_accvgpr_read_b32 v90, a154
	v_accvgpr_read_b32 v91, a155
	v_cvt_pk_bf16_f32 v83, v90, v91
	v_accvgpr_read_b32 v92, a156
	v_accvgpr_read_b32 v93, a157
	v_cvt_pk_bf16_f32 v86, v92, v93
	v_accvgpr_read_b32 v94, a158
	v_accvgpr_read_b32 v95, a159
	v_cvt_pk_bf16_f32 v87, v94, v95
	v_cndmask_b32_e32 v88, v80, v82, vcc
	v_cndmask_b32_e32 v89, v81, v83, vcc
	v_cndmask_b32_e32 v90, v84, v86, vcc
	ds_bpermute_b32 v88, v194, v88
	ds_bpermute_b32 v89, v194, v89
	v_cndmask_b32_e32 v91, v85, v87, vcc
	ds_bpermute_b32 v90, v194, v90
	ds_bpermute_b32 v91, v194, v91
	v_accvgpr_read_b32 v64, a160
	s_waitcnt lgkmcnt(3)
	v_cndmask_b32_e32 v80, v88, v80, vcc
	s_waitcnt lgkmcnt(2)
	v_cndmask_b32_e32 v81, v89, v81, vcc
	v_cndmask_b32_e32 v82, v82, v88, vcc
	v_cndmask_b32_e32 v83, v83, v89, vcc
	v_accvgpr_read_b32 v65, a161
	s_waitcnt lgkmcnt(1)
	v_cndmask_b32_e32 v84, v90, v84, vcc
	s_waitcnt lgkmcnt(0)
	v_cndmask_b32_e32 v85, v91, v85, vcc
	v_cndmask_b32_e32 v86, v86, v90, vcc
	v_cndmask_b32_e32 v87, v87, v91, vcc
	global_store_dwordx4 v[176:177], v[80:83], off offset:128
	global_store_dwordx4 v[176:177], v[84:87], off offset:144
	v_accvgpr_read_b32 v66, a162
	v_cvt_pk_bf16_f32 v64, v64, v65
	v_accvgpr_read_b32 v67, a163
	v_cvt_pk_bf16_f32 v65, v66, v67
	v_accvgpr_read_b32 v68, a164
	v_accvgpr_read_b32 v69, a165
	v_cvt_pk_bf16_f32 v68, v68, v69
	v_accvgpr_read_b32 v70, a166
	v_accvgpr_read_b32 v71, a167
	v_cvt_pk_bf16_f32 v69, v70, v71
	v_accvgpr_read_b32 v72, a168
	v_accvgpr_read_b32 v73, a169
	v_cvt_pk_bf16_f32 v66, v72, v73
	v_accvgpr_read_b32 v74, a170
	v_accvgpr_read_b32 v75, a171
	v_cvt_pk_bf16_f32 v67, v74, v75
	v_accvgpr_read_b32 v76, a172
	v_accvgpr_read_b32 v77, a173
	v_cvt_pk_bf16_f32 v70, v76, v77
	v_accvgpr_read_b32 v78, a174
	v_accvgpr_read_b32 v79, a175
	v_cvt_pk_bf16_f32 v71, v78, v79
	v_cndmask_b32_e32 v72, v64, v66, vcc
	v_cndmask_b32_e32 v73, v65, v67, vcc
	v_cndmask_b32_e32 v74, v68, v70, vcc
	ds_bpermute_b32 v72, v194, v72
	ds_bpermute_b32 v73, v194, v73
	v_cndmask_b32_e32 v75, v69, v71, vcc
	ds_bpermute_b32 v74, v194, v74
	ds_bpermute_b32 v75, v194, v75
	v_accvgpr_read_b32 v48, a176
	s_waitcnt lgkmcnt(3)
	v_cndmask_b32_e32 v64, v72, v64, vcc
	s_waitcnt lgkmcnt(2)
	v_cndmask_b32_e32 v65, v73, v65, vcc
	v_cndmask_b32_e32 v66, v66, v72, vcc
	v_cndmask_b32_e32 v67, v67, v73, vcc
	v_accvgpr_read_b32 v49, a177
	s_waitcnt lgkmcnt(1)
	v_cndmask_b32_e32 v68, v74, v68, vcc
	s_waitcnt lgkmcnt(0)
	v_cndmask_b32_e32 v69, v75, v69, vcc
	v_cndmask_b32_e32 v70, v70, v74, vcc
	v_cndmask_b32_e32 v71, v71, v75, vcc
	global_store_dwordx4 v[160:161], v[64:67], off offset:128
	global_store_dwordx4 v[160:161], v[68:71], off offset:144
	v_accvgpr_read_b32 v50, a178
	v_cvt_pk_bf16_f32 v48, v48, v49
	v_accvgpr_read_b32 v51, a179
	v_cvt_pk_bf16_f32 v49, v50, v51
	v_accvgpr_read_b32 v52, a180
	v_accvgpr_read_b32 v53, a181
	v_cvt_pk_bf16_f32 v52, v52, v53
	v_accvgpr_read_b32 v54, a182
	v_accvgpr_read_b32 v55, a183
	v_cvt_pk_bf16_f32 v53, v54, v55
	v_accvgpr_read_b32 v56, a184
	v_accvgpr_read_b32 v57, a185
	v_cvt_pk_bf16_f32 v50, v56, v57
	v_accvgpr_read_b32 v58, a186
	v_accvgpr_read_b32 v59, a187
	v_cvt_pk_bf16_f32 v51, v58, v59
	v_accvgpr_read_b32 v60, a188
	v_accvgpr_read_b32 v61, a189
	v_cvt_pk_bf16_f32 v54, v60, v61
	v_accvgpr_read_b32 v62, a190
	v_accvgpr_read_b32 v63, a191
	v_cvt_pk_bf16_f32 v55, v62, v63
	v_cndmask_b32_e32 v56, v48, v50, vcc
	v_cndmask_b32_e32 v57, v49, v51, vcc
	v_cndmask_b32_e32 v58, v52, v54, vcc
	ds_bpermute_b32 v56, v194, v56
	ds_bpermute_b32 v57, v194, v57
	v_cndmask_b32_e32 v59, v53, v55, vcc
	ds_bpermute_b32 v58, v194, v58
	ds_bpermute_b32 v59, v194, v59
	v_accvgpr_read_b32 v32, a48
	s_waitcnt lgkmcnt(3)
	v_cndmask_b32_e32 v48, v56, v48, vcc
	s_waitcnt lgkmcnt(2)
	v_cndmask_b32_e32 v49, v57, v49, vcc
	v_cndmask_b32_e32 v50, v50, v56, vcc
	v_cndmask_b32_e32 v51, v51, v57, vcc
	v_accvgpr_read_b32 v33, a49
	s_waitcnt lgkmcnt(1)
	v_cndmask_b32_e32 v52, v58, v52, vcc
	s_waitcnt lgkmcnt(0)
	v_cndmask_b32_e32 v53, v59, v53, vcc
	v_cndmask_b32_e32 v54, v54, v58, vcc
	v_cndmask_b32_e32 v55, v55, v59, vcc
	global_store_dwordx4 v[144:145], v[48:51], off offset:128
	global_store_dwordx4 v[144:145], v[52:55], off offset:144
	v_accvgpr_read_b32 v34, a50
	v_cvt_pk_bf16_f32 v32, v32, v33
	v_accvgpr_read_b32 v35, a51
	v_cvt_pk_bf16_f32 v33, v34, v35
	v_accvgpr_read_b32 v36, a52
	v_accvgpr_read_b32 v37, a53
	v_cvt_pk_bf16_f32 v36, v36, v37
	v_accvgpr_read_b32 v38, a54
	v_accvgpr_read_b32 v39, a55
	v_cvt_pk_bf16_f32 v37, v38, v39
	v_accvgpr_read_b32 v40, a56
	v_accvgpr_read_b32 v41, a57
	v_cvt_pk_bf16_f32 v34, v40, v41
	v_accvgpr_read_b32 v42, a58
	v_accvgpr_read_b32 v43, a59
	v_cvt_pk_bf16_f32 v35, v42, v43
	v_accvgpr_read_b32 v44, a60
	v_accvgpr_read_b32 v45, a61
	v_cvt_pk_bf16_f32 v38, v44, v45
	v_accvgpr_read_b32 v46, a62
	v_accvgpr_read_b32 v47, a63
	v_cvt_pk_bf16_f32 v39, v46, v47
	v_cndmask_b32_e32 v40, v32, v34, vcc
	v_cndmask_b32_e32 v41, v33, v35, vcc
	v_cndmask_b32_e32 v42, v36, v38, vcc
	ds_bpermute_b32 v40, v194, v40
	ds_bpermute_b32 v41, v194, v41
	v_cndmask_b32_e32 v43, v37, v39, vcc
	ds_bpermute_b32 v42, v194, v42
	ds_bpermute_b32 v43, v194, v43
	s_waitcnt vmcnt(18)
	v_accvgpr_read_b32 v16, a32
	s_waitcnt lgkmcnt(3)
	v_cndmask_b32_e32 v32, v40, v32, vcc
	s_waitcnt lgkmcnt(2)
	v_cndmask_b32_e32 v33, v41, v33, vcc
	v_cndmask_b32_e32 v34, v34, v40, vcc
	v_cndmask_b32_e32 v35, v35, v41, vcc
	v_accvgpr_read_b32 v17, a33
	s_waitcnt lgkmcnt(1)
	v_cndmask_b32_e32 v36, v42, v36, vcc
	s_waitcnt lgkmcnt(0)
	v_cndmask_b32_e32 v37, v43, v37, vcc
	v_cndmask_b32_e32 v38, v38, v42, vcc
	v_cndmask_b32_e32 v39, v39, v43, vcc
	global_store_dwordx4 v[176:177], v[32:35], off offset:192
	global_store_dwordx4 v[176:177], v[36:39], off offset:208
	v_accvgpr_read_b32 v18, a34
	v_cvt_pk_bf16_f32 v16, v16, v17
	v_accvgpr_read_b32 v19, a35
	v_cvt_pk_bf16_f32 v17, v18, v19
	v_accvgpr_read_b32 v20, a36
	v_accvgpr_read_b32 v21, a37
	v_cvt_pk_bf16_f32 v20, v20, v21
	v_accvgpr_read_b32 v22, a38
	v_accvgpr_read_b32 v23, a39
	v_cvt_pk_bf16_f32 v21, v22, v23
	v_accvgpr_read_b32 v24, a40
	v_accvgpr_read_b32 v25, a41
	v_cvt_pk_bf16_f32 v18, v24, v25
	v_accvgpr_read_b32 v26, a42
	v_accvgpr_read_b32 v27, a43
	v_cvt_pk_bf16_f32 v19, v26, v27
	v_accvgpr_read_b32 v28, a44
	v_accvgpr_read_b32 v29, a45
	v_cvt_pk_bf16_f32 v22, v28, v29
	v_accvgpr_read_b32 v30, a46
	v_accvgpr_read_b32 v31, a47
	v_cvt_pk_bf16_f32 v23, v30, v31
	v_cndmask_b32_e32 v24, v16, v18, vcc
	v_cndmask_b32_e32 v25, v17, v19, vcc
	v_cndmask_b32_e32 v26, v20, v22, vcc
	ds_bpermute_b32 v24, v194, v24
	ds_bpermute_b32 v25, v194, v25
	v_cndmask_b32_e32 v27, v21, v23, vcc
	ds_bpermute_b32 v26, v194, v26
	ds_bpermute_b32 v27, v194, v27
	v_accvgpr_read_b32 v0, a16
	s_waitcnt lgkmcnt(3)
	v_cndmask_b32_e32 v16, v24, v16, vcc
	s_waitcnt lgkmcnt(2)
	v_cndmask_b32_e32 v17, v25, v17, vcc
	v_cndmask_b32_e32 v18, v18, v24, vcc
	v_cndmask_b32_e32 v19, v19, v25, vcc
	v_accvgpr_read_b32 v1, a17
	s_waitcnt lgkmcnt(1)
	v_cndmask_b32_e32 v20, v26, v20, vcc
	s_waitcnt lgkmcnt(0)
	v_cndmask_b32_e32 v21, v27, v21, vcc
	v_cndmask_b32_e32 v22, v22, v26, vcc
	v_cndmask_b32_e32 v23, v23, v27, vcc
	global_store_dwordx4 v[160:161], v[16:19], off offset:192
	global_store_dwordx4 v[160:161], v[20:23], off offset:208
	v_accvgpr_read_b32 v2, a18
	v_cvt_pk_bf16_f32 v0, v0, v1
	v_accvgpr_read_b32 v3, a19
	v_cvt_pk_bf16_f32 v1, v2, v3
	v_accvgpr_read_b32 v4, a20
	v_accvgpr_read_b32 v5, a21
	v_cvt_pk_bf16_f32 v4, v4, v5
	v_accvgpr_read_b32 v6, a22
	v_accvgpr_read_b32 v7, a23
	v_cvt_pk_bf16_f32 v5, v6, v7
	v_accvgpr_read_b32 v8, a24
	v_accvgpr_read_b32 v9, a25
	v_cvt_pk_bf16_f32 v2, v8, v9
	v_accvgpr_read_b32 v10, a26
	v_accvgpr_read_b32 v11, a27
	v_cvt_pk_bf16_f32 v3, v10, v11
	v_accvgpr_read_b32 v12, a28
	v_accvgpr_read_b32 v13, a29
	v_cvt_pk_bf16_f32 v6, v12, v13
	v_accvgpr_read_b32 v14, a30
	v_accvgpr_read_b32 v15, a31
	v_cvt_pk_bf16_f32 v7, v14, v15
	v_cndmask_b32_e32 v8, v0, v2, vcc
	v_cndmask_b32_e32 v9, v1, v3, vcc
	v_cndmask_b32_e32 v10, v4, v6, vcc
	v_cndmask_b32_e32 v11, v5, v7, vcc
	ds_bpermute_b32 v8, v194, v8
	ds_bpermute_b32 v9, v194, v9
	ds_bpermute_b32 v10, v194, v10
	ds_bpermute_b32 v11, v194, v11
	s_add_i32 s0, s0, s93
	s_waitcnt lgkmcnt(3)
	v_cndmask_b32_e32 v0, v8, v0, vcc
	s_waitcnt lgkmcnt(2)
	v_cndmask_b32_e32 v1, v9, v1, vcc
	v_cndmask_b32_e32 v2, v2, v8, vcc
	v_cndmask_b32_e32 v3, v3, v9, vcc
	s_waitcnt lgkmcnt(1)
	v_cndmask_b32_e32 v4, v10, v4, vcc
	s_waitcnt lgkmcnt(0)
	v_cndmask_b32_e32 v5, v11, v5, vcc
	v_cndmask_b32_e32 v6, v6, v10, vcc
	v_cndmask_b32_e32 v7, v7, v11, vcc
	s_cmpk_lt_i32 s0, 0x100
	global_store_dwordx4 v[144:145], v[0:3], off offset:192
	global_store_dwordx4 v[144:145], v[4:7], off offset:208
	s_cbranch_scc0 .LBB0_199

.LBB0_203:
	s_nop 1
	v_accvgpr_read_b32 v191, a63
	v_or_b32_e32 v192, s4, v192
	v_cmp_lt_i32_e32 vcc, v211, v210
	v_mfma_f32_32x32x16_bf16 a[32:47], v[198:201], v[40:43], a[32:47]
	v_accvgpr_read_b32 v176, a48
	v_accvgpr_read_b32 v177, a49
	v_accvgpr_read_b32 v178, a50
	v_accvgpr_read_b32 v179, a51
	v_accvgpr_read_b32 v180, a52
	v_accvgpr_read_b32 v181, a53
	v_accvgpr_read_b32 v182, a54
	v_mfma_f32_32x32x16_bf16 a[16:31], v[198:201], v[36:39], a[16:31]
	v_accvgpr_read_b32 v183, a55
	v_accvgpr_read_b32 v184, a56
	v_accvgpr_read_b32 v185, a57
	v_accvgpr_read_b32 v186, a58
	v_accvgpr_read_b32 v187, a59
	v_accvgpr_read_b32 v188, a60
	v_accvgpr_read_b32 v189, a61
	v_mfma_f32_32x32x16_bf16 a[0:15], v[198:201], v[194:197], a[0:15]
	v_add_u32_e32 v198, v205, v192
	v_cndmask_b32_e32 v192, v209, v211, vcc
	v_lshlrev_b32_e32 v194, 2, v192
	v_cvt_pk_bf16_f32 v176, v176, v177
	v_cvt_pk_bf16_f32 v177, v178, v179
	v_cvt_pk_bf16_f32 v192, v180, v181
	v_cvt_pk_bf16_f32 v183, v182, v183
	v_cvt_pk_bf16_f32 v180, v184, v185
	v_cvt_pk_bf16_f32 v181, v186, v187
	v_cvt_pk_bf16_f32 v184, v188, v189
	v_accvgpr_read_b32 v190, a62
	v_cvt_pk_bf16_f32 v185, v190, v191
	v_and_b32_e32 v178, 63, v203
	v_cmp_gt_u32_e32 vcc, 32, v178
	v_or_b32_e32 v196, s1, v204
	v_ashrrev_i32_e32 v199, 31, v198
	v_cndmask_b32_e32 v178, v176, v180, vcc
	v_cndmask_b32_e32 v179, v177, v181, vcc
	ds_bpermute_b32 v186, v194, v178
	ds_bpermute_b32 v187, v194, v179
	v_cndmask_b32_e32 v182, v192, v184, vcc
	ds_bpermute_b32 v188, v194, v182
	v_cndmask_b32_e32 v178, v183, v185, vcc
	ds_bpermute_b32 v189, v194, v178
	v_readlane_b32 s4, v253, 43
	v_ashrrev_i32_e32 v197, 31, v196
	s_waitcnt lgkmcnt(3)
	v_cndmask_b32_e32 v178, v186, v176, vcc
	s_waitcnt lgkmcnt(2)
	v_cndmask_b32_e32 v179, v187, v177, vcc
	v_lshlrev_b64 v[176:177], 11, v[198:199]
	v_readlane_b32 s5, v253, 44
	v_cndmask_b32_e32 v180, v180, v186, vcc
	v_cndmask_b32_e32 v181, v181, v187, vcc
	v_lshl_add_u64 v[176:177], s[4:5], 0, v[176:177]
	v_lshlrev_b64 v[186:187], 1, v[196:197]
	v_accvgpr_read_b32 v175, a79
	s_waitcnt lgkmcnt(1)
	v_cndmask_b32_e32 v182, v188, v192, vcc
	v_lshl_add_u64 v[176:177], v[176:177], 0, v[186:187]
	v_and_b32_e32 v192, 32, v203
	v_accvgpr_read_b32 v160, a64
	v_lshl_add_u64 v[176:177], v[176:177], 0, v[192:193]
	v_accvgpr_read_b32 v161, a65
	s_waitcnt lgkmcnt(0)
	v_cndmask_b32_e32 v183, v189, v183, vcc
	v_cndmask_b32_e32 v184, v184, v188, vcc
	v_cndmask_b32_e32 v185, v185, v189, vcc
	global_store_dwordx4 v[176:177], v[178:181], off
	global_store_dwordx4 v[176:177], v[182:185], off offset:16
	v_accvgpr_read_b32 v162, a66
	v_cvt_pk_bf16_f32 v161, v160, v161
	v_accvgpr_read_b32 v163, a67
	v_cvt_pk_bf16_f32 v163, v162, v163
	v_accvgpr_read_b32 v164, a68
	v_accvgpr_read_b32 v165, a69
	v_cvt_pk_bf16_f32 v178, v164, v165
	v_accvgpr_read_b32 v166, a70
	v_accvgpr_read_b32 v167, a71
	v_cvt_pk_bf16_f32 v167, v166, v167
	v_accvgpr_read_b32 v168, a72
	v_accvgpr_read_b32 v169, a73
	v_cvt_pk_bf16_f32 v164, v168, v169
	v_accvgpr_read_b32 v170, a74
	v_accvgpr_read_b32 v171, a75
	v_cvt_pk_bf16_f32 v165, v170, v171
	v_accvgpr_read_b32 v172, a76
	v_accvgpr_read_b32 v173, a77
	v_cvt_pk_bf16_f32 v168, v172, v173
	v_accvgpr_read_b32 v174, a78
	v_cvt_pk_bf16_f32 v169, v174, v175
	v_cndmask_b32_e32 v162, v161, v164, vcc
	ds_bpermute_b32 v171, v194, v162
	v_cndmask_b32_e32 v166, v163, v165, vcc
	v_add_u32_e32 v160, 32, v198
	v_cndmask_b32_e32 v170, v178, v168, vcc
	ds_bpermute_b32 v166, v194, v166
	v_cndmask_b32_e32 v162, v167, v169, vcc
	ds_bpermute_b32 v170, v194, v170
	ds_bpermute_b32 v172, v194, v162
	s_waitcnt lgkmcnt(3)
	v_cndmask_b32_e32 v162, v171, v161, vcc
	v_ashrrev_i32_e32 v161, 31, v160
	v_lshlrev_b64 v[160:161], 11, v[160:161]
	v_lshl_add_u64 v[160:161], s[4:5], 0, v[160:161]
	v_accvgpr_read_b32 v159, a95
	v_lshl_add_u64 v[160:161], v[160:161], 0, v[186:187]
	v_accvgpr_read_b32 v144, a80
	s_waitcnt lgkmcnt(2)
	v_cndmask_b32_e32 v163, v166, v163, vcc
	v_cndmask_b32_e32 v164, v164, v171, vcc
	v_cndmask_b32_e32 v165, v165, v166, vcc
	v_lshl_add_u64 v[160:161], v[160:161], 0, v[192:193]
	v_accvgpr_read_b32 v145, a81
	s_waitcnt lgkmcnt(1)
	v_cndmask_b32_e32 v166, v170, v178, vcc
	s_waitcnt lgkmcnt(0)
	v_cndmask_b32_e32 v167, v172, v167, vcc
	v_cndmask_b32_e32 v168, v168, v170, vcc
	v_cndmask_b32_e32 v169, v169, v172, vcc
	global_store_dwordx4 v[160:161], v[162:165], off
	global_store_dwordx4 v[160:161], v[166:169], off offset:16
	v_accvgpr_read_b32 v146, a82
	v_cvt_pk_bf16_f32 v145, v144, v145
	v_accvgpr_read_b32 v147, a83
	v_cvt_pk_bf16_f32 v147, v146, v147
	v_accvgpr_read_b32 v148, a84
	v_accvgpr_read_b32 v149, a85
	v_cvt_pk_bf16_f32 v162, v148, v149
	v_accvgpr_read_b32 v150, a86
	v_accvgpr_read_b32 v151, a87
	v_cvt_pk_bf16_f32 v151, v150, v151
	v_accvgpr_read_b32 v152, a88
	v_accvgpr_read_b32 v153, a89
	v_cvt_pk_bf16_f32 v148, v152, v153
	v_accvgpr_read_b32 v154, a90
	v_accvgpr_read_b32 v155, a91
	v_cvt_pk_bf16_f32 v149, v154, v155
	v_accvgpr_read_b32 v156, a92
	v_accvgpr_read_b32 v157, a93
	v_cvt_pk_bf16_f32 v152, v156, v157
	v_accvgpr_read_b32 v158, a94
	v_cvt_pk_bf16_f32 v153, v158, v159
	v_cndmask_b32_e32 v146, v145, v148, vcc
	ds_bpermute_b32 v155, v194, v146
	v_cndmask_b32_e32 v150, v147, v149, vcc
	v_add_u32_e32 v144, 64, v198
	v_cndmask_b32_e32 v154, v162, v152, vcc
	ds_bpermute_b32 v150, v194, v150
	v_cndmask_b32_e32 v146, v151, v153, vcc
	ds_bpermute_b32 v154, v194, v154
	ds_bpermute_b32 v156, v194, v146
	s_waitcnt lgkmcnt(3)
	v_cndmask_b32_e32 v146, v155, v145, vcc
	v_ashrrev_i32_e32 v145, 31, v144
	v_lshlrev_b64 v[144:145], 11, v[144:145]
	v_lshl_add_u64 v[144:145], s[4:5], 0, v[144:145]
	v_accvgpr_read_b32 v143, a111
	v_lshl_add_u64 v[144:145], v[144:145], 0, v[186:187]
	v_accvgpr_read_b32 v128, a96
	s_waitcnt lgkmcnt(2)
	v_cndmask_b32_e32 v147, v150, v147, vcc
	v_cndmask_b32_e32 v148, v148, v155, vcc
	v_cndmask_b32_e32 v149, v149, v150, vcc
	v_lshl_add_u64 v[144:145], v[144:145], 0, v[192:193]
	v_accvgpr_read_b32 v129, a97
	s_waitcnt lgkmcnt(1)
	v_cndmask_b32_e32 v150, v154, v162, vcc
	s_waitcnt lgkmcnt(0)
	v_cndmask_b32_e32 v151, v156, v151, vcc
	v_cndmask_b32_e32 v152, v152, v154, vcc
	v_cndmask_b32_e32 v153, v153, v156, vcc
	global_store_dwordx4 v[144:145], v[146:149], off
	global_store_dwordx4 v[144:145], v[150:153], off offset:16
	v_accvgpr_read_b32 v130, a98
	v_cvt_pk_bf16_f32 v128, v128, v129
	v_accvgpr_read_b32 v131, a99
	v_cvt_pk_bf16_f32 v129, v130, v131
	v_accvgpr_read_b32 v132, a100
	v_accvgpr_read_b32 v133, a101
	v_cvt_pk_bf16_f32 v132, v132, v133
	v_accvgpr_read_b32 v134, a102
	v_accvgpr_read_b32 v135, a103
	v_cvt_pk_bf16_f32 v133, v134, v135
	v_accvgpr_read_b32 v136, a104
	v_accvgpr_read_b32 v137, a105
	v_cvt_pk_bf16_f32 v130, v136, v137
	v_accvgpr_read_b32 v138, a106
	v_accvgpr_read_b32 v139, a107
	v_cvt_pk_bf16_f32 v131, v138, v139
	v_accvgpr_read_b32 v140, a108
	v_accvgpr_read_b32 v141, a109
	v_cvt_pk_bf16_f32 v134, v140, v141
	v_accvgpr_read_b32 v142, a110
	v_cvt_pk_bf16_f32 v135, v142, v143
	v_cndmask_b32_e32 v136, v128, v130, vcc
	v_cndmask_b32_e32 v137, v129, v131, vcc
	v_cndmask_b32_e32 v138, v132, v134, vcc
	ds_bpermute_b32 v136, v194, v136
	ds_bpermute_b32 v137, v194, v137
	v_cndmask_b32_e32 v139, v133, v135, vcc
	ds_bpermute_b32 v138, v194, v138
	ds_bpermute_b32 v139, v194, v139
	v_accvgpr_read_b32 v112, a112
	s_waitcnt lgkmcnt(3)
	v_cndmask_b32_e32 v128, v136, v128, vcc
	s_waitcnt lgkmcnt(2)
	v_cndmask_b32_e32 v129, v137, v129, vcc
	v_cndmask_b32_e32 v130, v130, v136, vcc
	v_cndmask_b32_e32 v131, v131, v137, vcc
	v_accvgpr_read_b32 v113, a113
	s_waitcnt lgkmcnt(1)
	v_cndmask_b32_e32 v132, v138, v132, vcc
	s_waitcnt lgkmcnt(0)
	v_cndmask_b32_e32 v133, v139, v133, vcc
	v_cndmask_b32_e32 v134, v134, v138, vcc
	v_cndmask_b32_e32 v135, v135, v139, vcc
	global_store_dwordx4 v[176:177], v[128:131], off offset:64
	global_store_dwordx4 v[176:177], v[132:135], off offset:80
	v_accvgpr_read_b32 v114, a114
	v_cvt_pk_bf16_f32 v112, v112, v113
	v_accvgpr_read_b32 v115, a115
	v_cvt_pk_bf16_f32 v113, v114, v115
	v_accvgpr_read_b32 v116, a116
	v_accvgpr_read_b32 v117, a117
	v_cvt_pk_bf16_f32 v116, v116, v117
	v_accvgpr_read_b32 v118, a118
	v_accvgpr_read_b32 v119, a119
	v_cvt_pk_bf16_f32 v117, v118, v119
	v_accvgpr_read_b32 v120, a120
	v_accvgpr_read_b32 v121, a121
	v_cvt_pk_bf16_f32 v114, v120, v121
	v_accvgpr_read_b32 v122, a122
	v_accvgpr_read_b32 v123, a123
	v_cvt_pk_bf16_f32 v115, v122, v123
	v_accvgpr_read_b32 v124, a124
	v_accvgpr_read_b32 v125, a125
	v_cvt_pk_bf16_f32 v118, v124, v125
	v_accvgpr_read_b32 v126, a126
	v_accvgpr_read_b32 v127, a127
	v_cvt_pk_bf16_f32 v119, v126, v127
	v_cndmask_b32_e32 v120, v112, v114, vcc
	v_cndmask_b32_e32 v121, v113, v115, vcc
	v_cndmask_b32_e32 v122, v116, v118, vcc
	ds_bpermute_b32 v120, v194, v120
	ds_bpermute_b32 v121, v194, v121
	v_cndmask_b32_e32 v123, v117, v119, vcc
	ds_bpermute_b32 v122, v194, v122
	ds_bpermute_b32 v123, v194, v123
	v_accvgpr_read_b32 v96, a128
	s_waitcnt lgkmcnt(3)
	v_cndmask_b32_e32 v112, v120, v112, vcc
	s_waitcnt lgkmcnt(2)
	v_cndmask_b32_e32 v113, v121, v113, vcc
	v_cndmask_b32_e32 v114, v114, v120, vcc
	v_cndmask_b32_e32 v115, v115, v121, vcc
	v_accvgpr_read_b32 v97, a129
	s_waitcnt lgkmcnt(1)
	v_cndmask_b32_e32 v116, v122, v116, vcc
	s_waitcnt lgkmcnt(0)
	v_cndmask_b32_e32 v117, v123, v117, vcc
	v_cndmask_b32_e32 v118, v118, v122, vcc
	v_cndmask_b32_e32 v119, v119, v123, vcc
	global_store_dwordx4 v[160:161], v[112:115], off offset:64
	global_store_dwordx4 v[160:161], v[116:119], off offset:80
	v_accvgpr_read_b32 v98, a130
	v_cvt_pk_bf16_f32 v96, v96, v97
	v_accvgpr_read_b32 v99, a131
	v_cvt_pk_bf16_f32 v97, v98, v99
	v_accvgpr_read_b32 v100, a132
	v_accvgpr_read_b32 v101, a133
	v_cvt_pk_bf16_f32 v100, v100, v101
	v_accvgpr_read_b32 v102, a134
	v_accvgpr_read_b32 v103, a135
	v_cvt_pk_bf16_f32 v101, v102, v103
	v_accvgpr_read_b32 v104, a136
	v_accvgpr_read_b32 v105, a137
	v_cvt_pk_bf16_f32 v98, v104, v105
	v_accvgpr_read_b32 v106, a138
	v_accvgpr_read_b32 v107, a139
	v_cvt_pk_bf16_f32 v99, v106, v107
	v_accvgpr_read_b32 v108, a140
	v_accvgpr_read_b32 v109, a141
	v_cvt_pk_bf16_f32 v102, v108, v109
	v_accvgpr_read_b32 v110, a142
	v_accvgpr_read_b32 v111, a143
	v_cvt_pk_bf16_f32 v103, v110, v111
	v_cndmask_b32_e32 v104, v96, v98, vcc
	v_cndmask_b32_e32 v105, v97, v99, vcc
	v_cndmask_b32_e32 v106, v100, v102, vcc
	ds_bpermute_b32 v104, v194, v104
	ds_bpermute_b32 v105, v194, v105
	v_cndmask_b32_e32 v107, v101, v103, vcc
	ds_bpermute_b32 v106, v194, v106
	ds_bpermute_b32 v107, v194, v107
	v_accvgpr_read_b32 v80, a144
	s_waitcnt lgkmcnt(3)
	v_cndmask_b32_e32 v96, v104, v96, vcc
	s_waitcnt lgkmcnt(2)
	v_cndmask_b32_e32 v97, v105, v97, vcc
	v_cndmask_b32_e32 v98, v98, v104, vcc
	v_cndmask_b32_e32 v99, v99, v105, vcc
	v_accvgpr_read_b32 v81, a145
	s_waitcnt lgkmcnt(1)
	v_cndmask_b32_e32 v100, v106, v100, vcc
	s_waitcnt lgkmcnt(0)
	v_cndmask_b32_e32 v101, v107, v101, vcc
	v_cndmask_b32_e32 v102, v102, v106, vcc
	v_cndmask_b32_e32 v103, v103, v107, vcc
	global_store_dwordx4 v[144:145], v[96:99], off offset:64
	global_store_dwordx4 v[144:145], v[100:103], off offset:80
	v_accvgpr_read_b32 v82, a146
	v_cvt_pk_bf16_f32 v80, v80, v81
	v_accvgpr_read_b32 v83, a147
	v_cvt_pk_bf16_f32 v81, v82, v83
	v_accvgpr_read_b32 v84, a148
	v_accvgpr_read_b32 v85, a149
	v_cvt_pk_bf16_f32 v84, v84, v85
	v_accvgpr_read_b32 v86, a150
	v_accvgpr_read_b32 v87, a151
	v_cvt_pk_bf16_f32 v85, v86, v87
	v_accvgpr_read_b32 v88, a152
	v_accvgpr_read_b32 v89, a153
	v_cvt_pk_bf16_f32 v82, v88, v89
	v_accvgpr_read_b32 v90, a154
	v_accvgpr_read_b32 v91, a155
	v_cvt_pk_bf16_f32 v83, v90, v91
	v_accvgpr_read_b32 v92, a156
	v_accvgpr_read_b32 v93, a157
	v_cvt_pk_bf16_f32 v86, v92, v93
	v_accvgpr_read_b32 v94, a158
	v_accvgpr_read_b32 v95, a159
	v_cvt_pk_bf16_f32 v87, v94, v95
	v_cndmask_b32_e32 v88, v80, v82, vcc
	v_cndmask_b32_e32 v89, v81, v83, vcc
	v_cndmask_b32_e32 v90, v84, v86, vcc
	ds_bpermute_b32 v88, v194, v88
	ds_bpermute_b32 v89, v194, v89
	v_cndmask_b32_e32 v91, v85, v87, vcc
	ds_bpermute_b32 v90, v194, v90
	ds_bpermute_b32 v91, v194, v91
	v_accvgpr_read_b32 v64, a160
	s_waitcnt lgkmcnt(3)
	v_cndmask_b32_e32 v80, v88, v80, vcc
	s_waitcnt lgkmcnt(2)
	v_cndmask_b32_e32 v81, v89, v81, vcc
	v_cndmask_b32_e32 v82, v82, v88, vcc
	v_cndmask_b32_e32 v83, v83, v89, vcc
	v_accvgpr_read_b32 v65, a161
	s_waitcnt lgkmcnt(1)
	v_cndmask_b32_e32 v84, v90, v84, vcc
	s_waitcnt lgkmcnt(0)
	v_cndmask_b32_e32 v85, v91, v85, vcc
	v_cndmask_b32_e32 v86, v86, v90, vcc
	v_cndmask_b32_e32 v87, v87, v91, vcc
	global_store_dwordx4 v[176:177], v[80:83], off offset:128
	global_store_dwordx4 v[176:177], v[84:87], off offset:144
	v_accvgpr_read_b32 v66, a162
	v_cvt_pk_bf16_f32 v64, v64, v65
	v_accvgpr_read_b32 v67, a163
	v_cvt_pk_bf16_f32 v65, v66, v67
	v_accvgpr_read_b32 v68, a164
	v_accvgpr_read_b32 v69, a165
	v_cvt_pk_bf16_f32 v68, v68, v69
	v_accvgpr_read_b32 v70, a166
	v_accvgpr_read_b32 v71, a167
	v_cvt_pk_bf16_f32 v69, v70, v71
	v_accvgpr_read_b32 v72, a168
	v_accvgpr_read_b32 v73, a169
	v_cvt_pk_bf16_f32 v66, v72, v73
	v_accvgpr_read_b32 v74, a170
	v_accvgpr_read_b32 v75, a171
	v_cvt_pk_bf16_f32 v67, v74, v75
	v_accvgpr_read_b32 v76, a172
	v_accvgpr_read_b32 v77, a173
	v_cvt_pk_bf16_f32 v70, v76, v77
	v_accvgpr_read_b32 v78, a174
	v_accvgpr_read_b32 v79, a175
	v_cvt_pk_bf16_f32 v71, v78, v79
	v_cndmask_b32_e32 v72, v64, v66, vcc
	v_cndmask_b32_e32 v73, v65, v67, vcc
	v_cndmask_b32_e32 v74, v68, v70, vcc
	ds_bpermute_b32 v72, v194, v72
	ds_bpermute_b32 v73, v194, v73
	v_cndmask_b32_e32 v75, v69, v71, vcc
	ds_bpermute_b32 v74, v194, v74
	ds_bpermute_b32 v75, v194, v75
	v_accvgpr_read_b32 v48, a176
	s_waitcnt lgkmcnt(3)
	v_cndmask_b32_e32 v64, v72, v64, vcc
	s_waitcnt lgkmcnt(2)
	v_cndmask_b32_e32 v65, v73, v65, vcc
	v_cndmask_b32_e32 v66, v66, v72, vcc
	v_cndmask_b32_e32 v67, v67, v73, vcc
	v_accvgpr_read_b32 v49, a177
	s_waitcnt lgkmcnt(1)
	v_cndmask_b32_e32 v68, v74, v68, vcc
	s_waitcnt lgkmcnt(0)
	v_cndmask_b32_e32 v69, v75, v69, vcc
	v_cndmask_b32_e32 v70, v70, v74, vcc
	v_cndmask_b32_e32 v71, v71, v75, vcc
	global_store_dwordx4 v[160:161], v[64:67], off offset:128
	global_store_dwordx4 v[160:161], v[68:71], off offset:144
	v_accvgpr_read_b32 v50, a178
	v_cvt_pk_bf16_f32 v48, v48, v49
	v_accvgpr_read_b32 v51, a179
	v_cvt_pk_bf16_f32 v49, v50, v51
	v_accvgpr_read_b32 v52, a180
	v_accvgpr_read_b32 v53, a181
	v_cvt_pk_bf16_f32 v52, v52, v53
	v_accvgpr_read_b32 v54, a182
	v_accvgpr_read_b32 v55, a183
	v_cvt_pk_bf16_f32 v53, v54, v55
	v_accvgpr_read_b32 v56, a184
	v_accvgpr_read_b32 v57, a185
	v_cvt_pk_bf16_f32 v50, v56, v57
	v_accvgpr_read_b32 v58, a186
	v_accvgpr_read_b32 v59, a187
	v_cvt_pk_bf16_f32 v51, v58, v59
	v_accvgpr_read_b32 v60, a188
	v_accvgpr_read_b32 v61, a189
	v_cvt_pk_bf16_f32 v54, v60, v61
	v_accvgpr_read_b32 v62, a190
	v_accvgpr_read_b32 v63, a191
	v_cvt_pk_bf16_f32 v55, v62, v63
	v_cndmask_b32_e32 v56, v48, v50, vcc
	v_cndmask_b32_e32 v57, v49, v51, vcc
	v_cndmask_b32_e32 v58, v52, v54, vcc
	ds_bpermute_b32 v56, v194, v56
	ds_bpermute_b32 v57, v194, v57
	v_cndmask_b32_e32 v59, v53, v55, vcc
	ds_bpermute_b32 v58, v194, v58
	ds_bpermute_b32 v59, v194, v59
	v_accvgpr_read_b32 v32, a32
	s_waitcnt lgkmcnt(3)
	v_cndmask_b32_e32 v48, v56, v48, vcc
	s_waitcnt lgkmcnt(2)
	v_cndmask_b32_e32 v49, v57, v49, vcc
	v_cndmask_b32_e32 v50, v50, v56, vcc
	v_cndmask_b32_e32 v51, v51, v57, vcc
	v_accvgpr_read_b32 v33, a33
	s_waitcnt lgkmcnt(1)
	v_cndmask_b32_e32 v52, v58, v52, vcc
	s_waitcnt lgkmcnt(0)
	v_cndmask_b32_e32 v53, v59, v53, vcc
	v_cndmask_b32_e32 v54, v54, v58, vcc
	v_cndmask_b32_e32 v55, v55, v59, vcc
	global_store_dwordx4 v[144:145], v[48:51], off offset:128
	global_store_dwordx4 v[144:145], v[52:55], off offset:144
	v_accvgpr_read_b32 v34, a34
	v_cvt_pk_bf16_f32 v32, v32, v33
	v_accvgpr_read_b32 v35, a35
	v_cvt_pk_bf16_f32 v33, v34, v35
	v_accvgpr_read_b32 v36, a36
	v_accvgpr_read_b32 v37, a37
	v_cvt_pk_bf16_f32 v36, v36, v37
	v_accvgpr_read_b32 v38, a38
	v_accvgpr_read_b32 v39, a39
	v_cvt_pk_bf16_f32 v37, v38, v39
	v_accvgpr_read_b32 v40, a40
	v_accvgpr_read_b32 v41, a41
	v_cvt_pk_bf16_f32 v34, v40, v41
	v_accvgpr_read_b32 v42, a42
	v_accvgpr_read_b32 v43, a43
	v_cvt_pk_bf16_f32 v35, v42, v43
	v_accvgpr_read_b32 v44, a44
	v_accvgpr_read_b32 v45, a45
	v_cvt_pk_bf16_f32 v38, v44, v45
	v_accvgpr_read_b32 v46, a46
	v_accvgpr_read_b32 v47, a47
	v_cvt_pk_bf16_f32 v39, v46, v47
	v_cndmask_b32_e32 v40, v32, v34, vcc
	v_cndmask_b32_e32 v41, v33, v35, vcc
	v_cndmask_b32_e32 v42, v36, v38, vcc
	ds_bpermute_b32 v40, v194, v40
	ds_bpermute_b32 v41, v194, v41
	v_cndmask_b32_e32 v43, v37, v39, vcc
	ds_bpermute_b32 v42, v194, v42
	ds_bpermute_b32 v43, v194, v43
	s_waitcnt vmcnt(18)
	v_accvgpr_read_b32 v16, a16
	s_waitcnt lgkmcnt(3)
	v_cndmask_b32_e32 v32, v40, v32, vcc
	s_waitcnt lgkmcnt(2)
	v_cndmask_b32_e32 v33, v41, v33, vcc
	v_cndmask_b32_e32 v34, v34, v40, vcc
	v_cndmask_b32_e32 v35, v35, v41, vcc
	v_accvgpr_read_b32 v17, a17
	s_waitcnt lgkmcnt(1)
	v_cndmask_b32_e32 v36, v42, v36, vcc
	s_waitcnt lgkmcnt(0)
	v_cndmask_b32_e32 v37, v43, v37, vcc
	v_cndmask_b32_e32 v38, v38, v42, vcc
	v_cndmask_b32_e32 v39, v39, v43, vcc
	global_store_dwordx4 v[176:177], v[32:35], off offset:192
	global_store_dwordx4 v[176:177], v[36:39], off offset:208
	v_accvgpr_read_b32 v18, a18
	v_cvt_pk_bf16_f32 v16, v16, v17
	v_accvgpr_read_b32 v19, a19
	v_cvt_pk_bf16_f32 v17, v18, v19
	v_accvgpr_read_b32 v20, a20
	v_accvgpr_read_b32 v21, a21
	v_cvt_pk_bf16_f32 v20, v20, v21
	v_accvgpr_read_b32 v22, a22
	v_accvgpr_read_b32 v23, a23
	v_cvt_pk_bf16_f32 v21, v22, v23
	v_accvgpr_read_b32 v24, a24
	v_accvgpr_read_b32 v25, a25
	v_cvt_pk_bf16_f32 v18, v24, v25
	v_accvgpr_read_b32 v26, a26
	v_accvgpr_read_b32 v27, a27
	v_cvt_pk_bf16_f32 v19, v26, v27
	v_accvgpr_read_b32 v28, a28
	v_accvgpr_read_b32 v29, a29
	v_cvt_pk_bf16_f32 v22, v28, v29
	v_accvgpr_read_b32 v30, a30
	v_accvgpr_read_b32 v31, a31
	v_cvt_pk_bf16_f32 v23, v30, v31
	v_cndmask_b32_e32 v24, v16, v18, vcc
	v_cndmask_b32_e32 v25, v17, v19, vcc
	v_cndmask_b32_e32 v26, v20, v22, vcc
	ds_bpermute_b32 v24, v194, v24
	ds_bpermute_b32 v25, v194, v25
	v_cndmask_b32_e32 v27, v21, v23, vcc
	ds_bpermute_b32 v26, v194, v26
	ds_bpermute_b32 v27, v194, v27
	v_accvgpr_read_b32 v0, a0
	s_waitcnt lgkmcnt(3)
	v_cndmask_b32_e32 v16, v24, v16, vcc
	s_waitcnt lgkmcnt(2)
	v_cndmask_b32_e32 v17, v25, v17, vcc
	v_cndmask_b32_e32 v18, v18, v24, vcc
	v_cndmask_b32_e32 v19, v19, v25, vcc
	v_accvgpr_read_b32 v1, a1
	s_waitcnt lgkmcnt(1)
	v_cndmask_b32_e32 v20, v26, v20, vcc
	s_waitcnt lgkmcnt(0)
	v_cndmask_b32_e32 v21, v27, v21, vcc
	v_cndmask_b32_e32 v22, v22, v26, vcc
	v_cndmask_b32_e32 v23, v23, v27, vcc
	global_store_dwordx4 v[160:161], v[16:19], off offset:192
	global_store_dwordx4 v[160:161], v[20:23], off offset:208
	v_accvgpr_read_b32 v2, a2
	v_cvt_pk_bf16_f32 v0, v0, v1
	v_accvgpr_read_b32 v3, a3
	v_cvt_pk_bf16_f32 v1, v2, v3
	v_accvgpr_read_b32 v4, a4
	v_accvgpr_read_b32 v5, a5
	v_cvt_pk_bf16_f32 v4, v4, v5
	v_accvgpr_read_b32 v6, a6
	v_accvgpr_read_b32 v7, a7
	v_cvt_pk_bf16_f32 v5, v6, v7
	v_accvgpr_read_b32 v8, a8
	v_accvgpr_read_b32 v9, a9
	v_cvt_pk_bf16_f32 v2, v8, v9
	v_accvgpr_read_b32 v10, a10
	v_accvgpr_read_b32 v11, a11
	v_cvt_pk_bf16_f32 v3, v10, v11
	v_accvgpr_read_b32 v12, a12
	v_accvgpr_read_b32 v13, a13
	v_cvt_pk_bf16_f32 v6, v12, v13
	v_accvgpr_read_b32 v14, a14
	v_accvgpr_read_b32 v15, a15
	v_cvt_pk_bf16_f32 v7, v14, v15
	v_cndmask_b32_e32 v8, v0, v2, vcc
	v_cndmask_b32_e32 v9, v1, v3, vcc
	v_cndmask_b32_e32 v10, v4, v6, vcc
	v_cndmask_b32_e32 v11, v5, v7, vcc
	ds_bpermute_b32 v8, v194, v8
	ds_bpermute_b32 v9, v194, v9
	ds_bpermute_b32 v10, v194, v10
	ds_bpermute_b32 v11, v194, v11
	v_readlane_b32 s1, v255, 6
	s_add_i32 s0, s0, s1
	v_readlane_b32 s8, v254, 50
	s_waitcnt lgkmcnt(3)
	v_cndmask_b32_e32 v0, v8, v0, vcc
	s_waitcnt lgkmcnt(2)
	v_cndmask_b32_e32 v1, v9, v1, vcc
	v_cndmask_b32_e32 v2, v2, v8, vcc
	v_cndmask_b32_e32 v3, v3, v9, vcc
	s_waitcnt lgkmcnt(1)
	v_cndmask_b32_e32 v4, v10, v4, vcc
	s_waitcnt lgkmcnt(0)
	v_cndmask_b32_e32 v5, v11, v5, vcc
	v_cndmask_b32_e32 v6, v6, v10, vcc
	v_cndmask_b32_e32 v7, v7, v11, vcc
	s_cmp_ge_i32 s0, s8
	global_store_dwordx4 v[144:145], v[0:3], off offset:192
	global_store_dwordx4 v[144:145], v[4:7], off offset:208
	s_cbranch_scc1 .LBB0_209

.LBB0_222:
	s_nop 4
	v_accvgpr_read_b32 v127, a47
	v_accvgpr_read_b32 v112, a32
	v_accvgpr_read_b32 v113, a33
	v_mfma_f32_32x32x16_bf16 a[0:15], v[132:135], v[128:131], a[0:15]
	v_cvt_pk_bf16_f32 v112, v112, v113
	v_accvgpr_read_b32 v114, a34
	v_accvgpr_read_b32 v115, a35
	v_cvt_pk_bf16_f32 v113, v114, v115
	v_accvgpr_read_b32 v116, a36
	v_accvgpr_read_b32 v117, a37
	v_cvt_pk_bf16_f32 v129, v116, v117
	v_accvgpr_read_b32 v118, a38
	v_accvgpr_read_b32 v119, a39
	v_cvt_pk_bf16_f32 v119, v118, v119
	v_accvgpr_read_b32 v120, a40
	v_accvgpr_read_b32 v121, a41
	v_cvt_pk_bf16_f32 v116, v120, v121
	v_accvgpr_read_b32 v122, a42
	v_accvgpr_read_b32 v123, a43
	v_cvt_pk_bf16_f32 v117, v122, v123
	v_accvgpr_read_b32 v124, a44
	v_accvgpr_read_b32 v125, a45
	v_cvt_pk_bf16_f32 v120, v124, v125
	v_accvgpr_read_b32 v126, a46
	v_cvt_pk_bf16_f32 v121, v126, v127
	v_or_b32_e32 v128, s2, v137
	v_cmp_lt_i32_e32 vcc, v211, v210
	v_and_b32_e32 v114, 63, v136
	v_mfma_f32_32x32x16_bf16 a[16:31], v[132:135], v[40:43], a[16:31]
	v_add_u32_e32 v132, v128, v139
	v_cndmask_b32_e32 v128, v209, v211, vcc
	v_cmp_gt_u32_e32 vcc, 32, v114
	v_lshlrev_b32_e32 v128, 2, v128
	v_or_b32_e32 v130, s1, v138
	v_cndmask_b32_e32 v114, v112, v116, vcc
	v_cndmask_b32_e32 v115, v113, v117, vcc
	ds_bpermute_b32 v122, v128, v114
	ds_bpermute_b32 v123, v128, v115
	v_cndmask_b32_e32 v118, v129, v120, vcc
	v_cndmask_b32_e32 v114, v119, v121, vcc
	ds_bpermute_b32 v124, v128, v118
	ds_bpermute_b32 v125, v128, v114
	v_ashrrev_i32_e32 v133, 31, v132
	v_readlane_b32 s2, v253, 43
	v_ashrrev_i32_e32 v131, 31, v130
	s_waitcnt lgkmcnt(3)
	v_cndmask_b32_e32 v114, v122, v112, vcc
	s_waitcnt lgkmcnt(2)
	v_cndmask_b32_e32 v115, v123, v113, vcc
	v_lshlrev_b64 v[112:113], 11, v[132:133]
	v_readlane_b32 s3, v253, 44
	v_cndmask_b32_e32 v116, v116, v122, vcc
	v_cndmask_b32_e32 v117, v117, v123, vcc
	v_lshl_add_u64 v[112:113], s[2:3], 0, v[112:113]
	v_lshlrev_b64 v[122:123], 1, v[130:131]
	v_accvgpr_read_b32 v111, a63
	v_lshl_add_u64 v[112:113], v[112:113], 0, v[122:123]
	v_and_b32_e32 v192, 32, v136
	v_accvgpr_read_b32 v96, a48
	v_lshl_add_u64 v[112:113], v[112:113], 0, v[192:193]
	v_accvgpr_read_b32 v97, a49
	s_waitcnt lgkmcnt(1)
	v_cndmask_b32_e32 v118, v124, v129, vcc
	s_waitcnt lgkmcnt(0)
	v_cndmask_b32_e32 v119, v125, v119, vcc
	v_cndmask_b32_e32 v120, v120, v124, vcc
	v_cndmask_b32_e32 v121, v121, v125, vcc
	global_store_dwordx4 v[112:113], v[114:117], off
	global_store_dwordx4 v[112:113], v[118:121], off offset:16
	v_accvgpr_read_b32 v98, a50
	v_cvt_pk_bf16_f32 v97, v96, v97
	v_accvgpr_read_b32 v99, a51
	v_cvt_pk_bf16_f32 v99, v98, v99
	v_accvgpr_read_b32 v100, a52
	v_accvgpr_read_b32 v101, a53
	v_cvt_pk_bf16_f32 v114, v100, v101
	v_accvgpr_read_b32 v102, a54
	v_accvgpr_read_b32 v103, a55
	v_cvt_pk_bf16_f32 v103, v102, v103
	v_accvgpr_read_b32 v104, a56
	v_accvgpr_read_b32 v105, a57
	v_cvt_pk_bf16_f32 v100, v104, v105
	v_accvgpr_read_b32 v106, a58
	v_accvgpr_read_b32 v107, a59
	v_cvt_pk_bf16_f32 v101, v106, v107
	v_accvgpr_read_b32 v108, a60
	v_accvgpr_read_b32 v109, a61
	v_cvt_pk_bf16_f32 v104, v108, v109
	v_accvgpr_read_b32 v110, a62
	v_cvt_pk_bf16_f32 v105, v110, v111
	v_cndmask_b32_e32 v98, v97, v100, vcc
	ds_bpermute_b32 v107, v128, v98
	v_cndmask_b32_e32 v102, v99, v101, vcc
	v_or_b32_e32 v96, 32, v132
	v_cndmask_b32_e32 v106, v114, v104, vcc
	ds_bpermute_b32 v102, v128, v102
	v_cndmask_b32_e32 v98, v103, v105, vcc
	ds_bpermute_b32 v106, v128, v106
	ds_bpermute_b32 v108, v128, v98
	s_waitcnt lgkmcnt(3)
	v_cndmask_b32_e32 v98, v107, v97, vcc
	v_ashrrev_i32_e32 v97, 31, v96
	v_lshlrev_b64 v[96:97], 11, v[96:97]
	v_lshl_add_u64 v[96:97], s[2:3], 0, v[96:97]
	v_accvgpr_read_b32 v95, a79
	v_lshl_add_u64 v[96:97], v[96:97], 0, v[122:123]
	v_accvgpr_read_b32 v80, a64
	s_waitcnt lgkmcnt(2)
	v_cndmask_b32_e32 v99, v102, v99, vcc
	v_cndmask_b32_e32 v100, v100, v107, vcc
	v_cndmask_b32_e32 v101, v101, v102, vcc
	v_lshl_add_u64 v[96:97], v[96:97], 0, v[192:193]
	v_accvgpr_read_b32 v81, a65
	s_waitcnt lgkmcnt(1)
	v_cndmask_b32_e32 v102, v106, v114, vcc
	s_waitcnt lgkmcnt(0)
	v_cndmask_b32_e32 v103, v108, v103, vcc
	v_cndmask_b32_e32 v104, v104, v106, vcc
	v_cndmask_b32_e32 v105, v105, v108, vcc
	global_store_dwordx4 v[96:97], v[98:101], off
	global_store_dwordx4 v[96:97], v[102:105], off offset:16
	v_accvgpr_read_b32 v82, a66
	v_cvt_pk_bf16_f32 v80, v80, v81
	v_accvgpr_read_b32 v83, a67
	v_cvt_pk_bf16_f32 v81, v82, v83
	v_accvgpr_read_b32 v84, a68
	v_accvgpr_read_b32 v85, a69
	v_cvt_pk_bf16_f32 v84, v84, v85
	v_accvgpr_read_b32 v86, a70
	v_accvgpr_read_b32 v87, a71
	v_cvt_pk_bf16_f32 v85, v86, v87
	v_accvgpr_read_b32 v88, a72
	v_accvgpr_read_b32 v89, a73
	v_cvt_pk_bf16_f32 v82, v88, v89
	v_accvgpr_read_b32 v90, a74
	v_accvgpr_read_b32 v91, a75
	v_cvt_pk_bf16_f32 v83, v90, v91
	v_accvgpr_read_b32 v92, a76
	v_accvgpr_read_b32 v93, a77
	v_cvt_pk_bf16_f32 v86, v92, v93
	v_accvgpr_read_b32 v94, a78
	v_cvt_pk_bf16_f32 v87, v94, v95
	v_cndmask_b32_e32 v88, v80, v82, vcc
	v_cndmask_b32_e32 v89, v81, v83, vcc
	v_cndmask_b32_e32 v90, v84, v86, vcc
	ds_bpermute_b32 v88, v128, v88
	ds_bpermute_b32 v89, v128, v89
	v_cndmask_b32_e32 v91, v85, v87, vcc
	ds_bpermute_b32 v90, v128, v90
	ds_bpermute_b32 v91, v128, v91
	v_accvgpr_read_b32 v64, a80
	s_waitcnt lgkmcnt(3)
	v_cndmask_b32_e32 v80, v88, v80, vcc
	s_waitcnt lgkmcnt(2)
	v_cndmask_b32_e32 v81, v89, v81, vcc
	v_cndmask_b32_e32 v82, v82, v88, vcc
	v_cndmask_b32_e32 v83, v83, v89, vcc
	v_accvgpr_read_b32 v65, a81
	s_waitcnt lgkmcnt(1)
	v_cndmask_b32_e32 v84, v90, v84, vcc
	s_waitcnt lgkmcnt(0)
	v_cndmask_b32_e32 v85, v91, v85, vcc
	v_cndmask_b32_e32 v86, v86, v90, vcc
	v_cndmask_b32_e32 v87, v87, v91, vcc
	global_store_dwordx4 v[112:113], v[80:83], off offset:64
	global_store_dwordx4 v[112:113], v[84:87], off offset:80
	v_accvgpr_read_b32 v66, a82
	v_cvt_pk_bf16_f32 v64, v64, v65
	v_accvgpr_read_b32 v67, a83
	v_cvt_pk_bf16_f32 v65, v66, v67
	v_accvgpr_read_b32 v68, a84
	v_accvgpr_read_b32 v69, a85
	v_cvt_pk_bf16_f32 v68, v68, v69
	v_accvgpr_read_b32 v70, a86
	v_accvgpr_read_b32 v71, a87
	v_cvt_pk_bf16_f32 v69, v70, v71
	v_accvgpr_read_b32 v72, a88
	v_accvgpr_read_b32 v73, a89
	v_cvt_pk_bf16_f32 v66, v72, v73
	v_accvgpr_read_b32 v74, a90
	v_accvgpr_read_b32 v75, a91
	v_cvt_pk_bf16_f32 v67, v74, v75
	v_accvgpr_read_b32 v76, a92
	v_accvgpr_read_b32 v77, a93
	v_cvt_pk_bf16_f32 v70, v76, v77
	v_accvgpr_read_b32 v78, a94
	v_accvgpr_read_b32 v79, a95
	v_cvt_pk_bf16_f32 v71, v78, v79
	v_cndmask_b32_e32 v72, v64, v66, vcc
	v_cndmask_b32_e32 v73, v65, v67, vcc
	v_cndmask_b32_e32 v74, v68, v70, vcc
	ds_bpermute_b32 v72, v128, v72
	ds_bpermute_b32 v73, v128, v73
	v_cndmask_b32_e32 v75, v69, v71, vcc
	ds_bpermute_b32 v74, v128, v74
	ds_bpermute_b32 v75, v128, v75
	v_accvgpr_read_b32 v48, a96
	s_waitcnt lgkmcnt(3)
	v_cndmask_b32_e32 v64, v72, v64, vcc
	s_waitcnt lgkmcnt(2)
	v_cndmask_b32_e32 v65, v73, v65, vcc
	v_cndmask_b32_e32 v66, v66, v72, vcc
	v_cndmask_b32_e32 v67, v67, v73, vcc
	v_accvgpr_read_b32 v49, a97
	s_waitcnt lgkmcnt(1)
	v_cndmask_b32_e32 v68, v74, v68, vcc
	s_waitcnt lgkmcnt(0)
	v_cndmask_b32_e32 v69, v75, v69, vcc
	v_cndmask_b32_e32 v70, v70, v74, vcc
	v_cndmask_b32_e32 v71, v71, v75, vcc
	global_store_dwordx4 v[96:97], v[64:67], off offset:64
	global_store_dwordx4 v[96:97], v[68:71], off offset:80
	v_accvgpr_read_b32 v50, a98
	v_cvt_pk_bf16_f32 v48, v48, v49
	v_accvgpr_read_b32 v51, a99
	v_cvt_pk_bf16_f32 v49, v50, v51
	v_accvgpr_read_b32 v52, a100
	v_accvgpr_read_b32 v53, a101
	v_cvt_pk_bf16_f32 v52, v52, v53
	v_accvgpr_read_b32 v54, a102
	v_accvgpr_read_b32 v55, a103
	v_cvt_pk_bf16_f32 v53, v54, v55
	v_accvgpr_read_b32 v56, a104
	v_accvgpr_read_b32 v57, a105
	v_cvt_pk_bf16_f32 v50, v56, v57
	v_accvgpr_read_b32 v58, a106
	v_accvgpr_read_b32 v59, a107
	v_cvt_pk_bf16_f32 v51, v58, v59
	v_accvgpr_read_b32 v60, a108
	v_accvgpr_read_b32 v61, a109
	v_cvt_pk_bf16_f32 v54, v60, v61
	v_accvgpr_read_b32 v62, a110
	v_accvgpr_read_b32 v63, a111
	v_cvt_pk_bf16_f32 v55, v62, v63
	v_cndmask_b32_e32 v56, v48, v50, vcc
	v_cndmask_b32_e32 v57, v49, v51, vcc
	v_cndmask_b32_e32 v58, v52, v54, vcc
	ds_bpermute_b32 v56, v128, v56
	ds_bpermute_b32 v57, v128, v57
	v_cndmask_b32_e32 v59, v53, v55, vcc
	ds_bpermute_b32 v58, v128, v58
	ds_bpermute_b32 v59, v128, v59
	v_accvgpr_read_b32 v32, a112
	s_waitcnt lgkmcnt(3)
	v_cndmask_b32_e32 v48, v56, v48, vcc
	s_waitcnt lgkmcnt(2)
	v_cndmask_b32_e32 v49, v57, v49, vcc
	v_cndmask_b32_e32 v50, v50, v56, vcc
	v_cndmask_b32_e32 v51, v51, v57, vcc
	v_accvgpr_read_b32 v33, a113
	s_waitcnt lgkmcnt(1)
	v_cndmask_b32_e32 v52, v58, v52, vcc
	s_waitcnt lgkmcnt(0)
	v_cndmask_b32_e32 v53, v59, v53, vcc
	v_cndmask_b32_e32 v54, v54, v58, vcc
	v_cndmask_b32_e32 v55, v55, v59, vcc
	global_store_dwordx4 v[112:113], v[48:51], off offset:128
	global_store_dwordx4 v[112:113], v[52:55], off offset:144
	v_accvgpr_read_b32 v34, a114
	v_cvt_pk_bf16_f32 v32, v32, v33
	v_accvgpr_read_b32 v35, a115
	v_cvt_pk_bf16_f32 v33, v34, v35
	v_accvgpr_read_b32 v36, a116
	v_accvgpr_read_b32 v37, a117
	v_cvt_pk_bf16_f32 v36, v36, v37
	v_accvgpr_read_b32 v38, a118
	v_accvgpr_read_b32 v39, a119
	v_cvt_pk_bf16_f32 v37, v38, v39
	v_accvgpr_read_b32 v40, a120
	v_accvgpr_read_b32 v41, a121
	v_cvt_pk_bf16_f32 v34, v40, v41
	v_accvgpr_read_b32 v42, a122
	v_accvgpr_read_b32 v43, a123
	v_cvt_pk_bf16_f32 v35, v42, v43
	v_accvgpr_read_b32 v44, a124
	v_accvgpr_read_b32 v45, a125
	v_cvt_pk_bf16_f32 v38, v44, v45
	v_accvgpr_read_b32 v46, a126
	v_accvgpr_read_b32 v47, a127
	v_cvt_pk_bf16_f32 v39, v46, v47
	v_cndmask_b32_e32 v40, v32, v34, vcc
	v_cndmask_b32_e32 v41, v33, v35, vcc
	v_cndmask_b32_e32 v42, v36, v38, vcc
	ds_bpermute_b32 v40, v128, v40
	ds_bpermute_b32 v41, v128, v41
	v_cndmask_b32_e32 v43, v37, v39, vcc
	ds_bpermute_b32 v42, v128, v42
	ds_bpermute_b32 v43, v128, v43
	s_waitcnt vmcnt(10)
	v_accvgpr_read_b32 v16, a16
	s_waitcnt lgkmcnt(3)
	v_cndmask_b32_e32 v32, v40, v32, vcc
	s_waitcnt lgkmcnt(2)
	v_cndmask_b32_e32 v33, v41, v33, vcc
	v_cndmask_b32_e32 v34, v34, v40, vcc
	v_cndmask_b32_e32 v35, v35, v41, vcc
	v_accvgpr_read_b32 v17, a17
	s_waitcnt lgkmcnt(1)
	v_cndmask_b32_e32 v36, v42, v36, vcc
	s_waitcnt lgkmcnt(0)
	v_cndmask_b32_e32 v37, v43, v37, vcc
	v_cndmask_b32_e32 v38, v38, v42, vcc
	v_cndmask_b32_e32 v39, v39, v43, vcc
	global_store_dwordx4 v[96:97], v[32:35], off offset:128
	global_store_dwordx4 v[96:97], v[36:39], off offset:144
	v_accvgpr_read_b32 v18, a18
	v_cvt_pk_bf16_f32 v16, v16, v17
	v_accvgpr_read_b32 v19, a19
	v_cvt_pk_bf16_f32 v17, v18, v19
	v_accvgpr_read_b32 v20, a20
	v_accvgpr_read_b32 v21, a21
	v_cvt_pk_bf16_f32 v20, v20, v21
	v_accvgpr_read_b32 v22, a22
	v_accvgpr_read_b32 v23, a23
	v_cvt_pk_bf16_f32 v21, v22, v23
	v_accvgpr_read_b32 v24, a24
	v_accvgpr_read_b32 v25, a25
	v_cvt_pk_bf16_f32 v18, v24, v25
	v_accvgpr_read_b32 v26, a26
	v_accvgpr_read_b32 v27, a27
	v_cvt_pk_bf16_f32 v19, v26, v27
	v_accvgpr_read_b32 v28, a28
	v_accvgpr_read_b32 v29, a29
	v_cvt_pk_bf16_f32 v22, v28, v29
	v_accvgpr_read_b32 v30, a30
	v_accvgpr_read_b32 v31, a31
	v_cvt_pk_bf16_f32 v23, v30, v31
	v_cndmask_b32_e32 v24, v16, v18, vcc
	v_cndmask_b32_e32 v25, v17, v19, vcc
	v_cndmask_b32_e32 v26, v20, v22, vcc
	ds_bpermute_b32 v24, v128, v24
	ds_bpermute_b32 v25, v128, v25
	v_cndmask_b32_e32 v27, v21, v23, vcc
	ds_bpermute_b32 v26, v128, v26
	ds_bpermute_b32 v27, v128, v27
	v_accvgpr_read_b32 v0, a0
	s_waitcnt lgkmcnt(3)
	v_cndmask_b32_e32 v16, v24, v16, vcc
	s_waitcnt lgkmcnt(2)
	v_cndmask_b32_e32 v17, v25, v17, vcc
	v_cndmask_b32_e32 v18, v18, v24, vcc
	v_cndmask_b32_e32 v19, v19, v25, vcc
	v_accvgpr_read_b32 v1, a1
	s_waitcnt lgkmcnt(1)
	v_cndmask_b32_e32 v20, v26, v20, vcc
	s_waitcnt lgkmcnt(0)
	v_cndmask_b32_e32 v21, v27, v21, vcc
	v_cndmask_b32_e32 v22, v22, v26, vcc
	v_cndmask_b32_e32 v23, v23, v27, vcc
	global_store_dwordx4 v[112:113], v[16:19], off offset:192
	global_store_dwordx4 v[112:113], v[20:23], off offset:208
	v_accvgpr_read_b32 v2, a2
	v_cvt_pk_bf16_f32 v0, v0, v1
	v_accvgpr_read_b32 v3, a3
	v_cvt_pk_bf16_f32 v1, v2, v3
	v_accvgpr_read_b32 v4, a4
	v_accvgpr_read_b32 v5, a5
	v_cvt_pk_bf16_f32 v4, v4, v5
	v_accvgpr_read_b32 v6, a6
	v_accvgpr_read_b32 v7, a7
	v_cvt_pk_bf16_f32 v5, v6, v7
	v_accvgpr_read_b32 v8, a8
	v_accvgpr_read_b32 v9, a9
	v_cvt_pk_bf16_f32 v2, v8, v9
	v_accvgpr_read_b32 v10, a10
	v_accvgpr_read_b32 v11, a11
	v_cvt_pk_bf16_f32 v3, v10, v11
	v_accvgpr_read_b32 v12, a12
	v_accvgpr_read_b32 v13, a13
	v_cvt_pk_bf16_f32 v6, v12, v13
	v_accvgpr_read_b32 v14, a14
	v_accvgpr_read_b32 v15, a15
	v_cvt_pk_bf16_f32 v7, v14, v15
	v_cndmask_b32_e32 v8, v0, v2, vcc
	v_cndmask_b32_e32 v9, v1, v3, vcc
	v_cndmask_b32_e32 v10, v4, v6, vcc
	v_cndmask_b32_e32 v11, v5, v7, vcc
	ds_bpermute_b32 v8, v128, v8
	ds_bpermute_b32 v9, v128, v9
	ds_bpermute_b32 v10, v128, v10
	ds_bpermute_b32 v11, v128, v11
	v_readlane_b32 s1, v255, 6
	s_add_i32 s0, s0, s1
	v_readlane_b32 s6, v254, 57
	s_waitcnt lgkmcnt(3)
	v_cndmask_b32_e32 v0, v8, v0, vcc
	s_waitcnt lgkmcnt(2)
	v_cndmask_b32_e32 v1, v9, v1, vcc
	v_cndmask_b32_e32 v2, v2, v8, vcc
	v_cndmask_b32_e32 v3, v3, v9, vcc
	s_waitcnt lgkmcnt(1)
	v_cndmask_b32_e32 v4, v10, v4, vcc
	s_waitcnt lgkmcnt(0)
	v_cndmask_b32_e32 v5, v11, v5, vcc
	v_cndmask_b32_e32 v6, v6, v10, vcc
	v_cndmask_b32_e32 v7, v7, v11, vcc
	s_cmp_ge_i32 s0, s6
	global_store_dwordx4 v[96:97], v[0:3], off offset:192
	global_store_dwordx4 v[96:97], v[4:7], off offset:208
	s_cbranch_scc1 .LBB0_228

.LBB0_240:
	s_add_i32 s5, s4, 0x80
	s_min_u32 s6, s5, 0x1c0
	s_lshl_b32 s78, s6, 1
	v_lshl_add_u64 v[68:69], v[0:1], 0, s[78:79]
	v_lshl_add_u64 v[72:73], v[2:3], 0, s[78:79]
	v_lshl_add_u64 v[76:77], v[4:5], 0, s[78:79]
	v_lshl_add_u64 v[80:81], v[6:7], 0, s[78:79]
	v_lshl_add_u64 v[84:85], v[8:9], 0, s[78:79]
	v_lshl_add_u64 v[88:89], v[10:11], 0, s[78:79]
	v_lshl_add_u64 v[92:93], v[12:13], 0, s[78:79]
	v_lshl_add_u64 v[96:97], v[14:15], 0, s[78:79]
	global_load_dwordx4 v[68:71], v[68:69], off
	s_nop 0
	global_load_dwordx4 v[72:75], v[72:73], off
	s_nop 0
	global_load_dwordx4 v[76:79], v[76:77], off
	s_nop 0
	global_load_dwordx4 v[80:83], v[80:81], off
	s_nop 0
	global_load_dwordx4 v[84:87], v[84:85], off
	s_nop 0
	global_load_dwordx4 v[88:91], v[88:89], off
	s_nop 0
	global_load_dwordx4 v[92:95], v[92:93], off
	s_nop 0
	global_load_dwordx4 v[96:99], v[96:97], off
	ds_read_b128 v[100:103], v16 offset:0
	ds_read_b128 v[104:107], v16 offset:0x1000
	ds_read_b128 v[108:111], v20 offset:0
	ds_read_b128 v[112:115], v20 offset:0x1000
	s_min_u32 s4, s4, 0x100
	ds_read_b128 v[116:119], v17 offset:0
	ds_read_b128 v[120:123], v17 offset:0x1000
	ds_read_b128 v[124:127], v21 offset:0
	ds_read_b128 v[128:131], v21 offset:0x1000
	ds_read_b128 v[132:135], v18 offset:0
	ds_read_b128 v[136:139], v18 offset:0x1000
	ds_read_b128 v[140:143], v22 offset:0
	ds_read_b128 v[144:147], v22 offset:0x1000
	ds_read_b128 v[148:151], v19 offset:0
	ds_read_b128 v[152:155], v19 offset:0x1000
	ds_read_b128 v[156:159], v23 offset:0
	ds_read_b128 v[160:163], v23 offset:0x1000
	s_waitcnt lgkmcnt(12)
	s_lshl_b32 s78, s4, 1
	v_mfma_f32_32x32x16_bf16 a[32:47], v[100:103], v[108:111], a[32:47]
	v_add_u32_e32 v164, v24, v25
	s_waitcnt lgkmcnt(8)
	s_waitcnt lgkmcnt(4)
	v_add_u32_e32 v165, v26, v27
	v_add_u32_e32 v166, v28, v29
	v_add_u32_e32 v167, v30, v31
	s_waitcnt lgkmcnt(0)
	v_mfma_f32_32x32x16_bf16 a[48:63], v[100:103], v[112:115], a[48:63]
	v_lshl_add_u64 v[100:101], v[0:1], 0, s[78:79]
	v_lshl_add_u64 v[102:103], v[2:3], 0, s[78:79]
	s_waitcnt vmcnt(15)
	ds_write_b128 v164, v[32:35] offset:32768
	s_waitcnt vmcnt(14)
	ds_write_b128 v164, v[36:39] offset:49152
	s_waitcnt vmcnt(13)
	ds_write_b128 v165, v[40:43] offset:32768
	s_waitcnt vmcnt(12)
	ds_write_b128 v165, v[44:47] offset:49152
	s_waitcnt vmcnt(11)
	ds_write_b128 v166, v[48:51] offset:32768
	s_waitcnt vmcnt(10)
	ds_write_b128 v166, v[52:55] offset:49152
	s_waitcnt vmcnt(9)
	ds_write_b128 v167, v[56:59] offset:32768
	s_waitcnt vmcnt(8)
	ds_write_b128 v167, v[60:63] offset:49152
	s_waitcnt lgkmcnt(0)
	s_barrier
	v_mfma_f32_32x32x16_bf16 a[0:15], v[104:107], v[108:111], a[0:15]
	v_lshl_add_u64 v[108:109], v[8:9], 0, s[78:79]
	v_lshl_add_u64 v[110:111], v[10:11], 0, s[78:79]
	s_add_i32 s3, s3, 2
	s_mov_b32 s4, s5
	s_cmp_lt_u32 s3, 6
	v_mfma_f32_32x32x16_bf16 a[16:31], v[104:107], v[112:115], a[16:31]
	v_lshl_add_u64 v[104:105], v[4:5], 0, s[78:79]
	v_lshl_add_u64 v[106:107], v[6:7], 0, s[78:79]
	v_lshl_add_u64 v[112:113], v[12:13], 0, s[78:79]
	v_lshl_add_u64 v[114:115], v[14:15], 0, s[78:79]
	global_load_dwordx4 v[32:35], v[100:101], off offset:384
	global_load_dwordx4 v[36:39], v[102:103], off offset:384
	global_load_dwordx4 v[40:43], v[104:105], off offset:384
	global_load_dwordx4 v[44:47], v[106:107], off offset:384
	global_load_dwordx4 v[48:51], v[108:109], off offset:384
	global_load_dwordx4 v[52:55], v[110:111], off offset:384
	global_load_dwordx4 v[56:59], v[112:113], off offset:384
	global_load_dwordx4 v[60:63], v[114:115], off offset:384
	ds_read_b128 v[100:103], v16 offset:0x8000
	v_mfma_f32_32x32x16_bf16 a[32:47], v[116:119], v[124:127], a[32:47]
	ds_read_b128 v[104:107], v16 offset:0x9000
	ds_read_b128 v[108:111], v20 offset:0x8000
	ds_read_b128 v[112:115], v20 offset:0x9000
	v_mfma_f32_32x32x16_bf16 a[48:63], v[116:119], v[128:131], a[48:63]
	ds_read_b128 v[116:119], v17 offset:0x8000
	v_mfma_f32_32x32x16_bf16 a[0:15], v[120:123], v[124:127], a[0:15]
	v_mfma_f32_32x32x16_bf16 a[16:31], v[120:123], v[128:131], a[16:31]
	ds_read_b128 v[120:123], v17 offset:0x9000
	ds_read_b128 v[124:127], v21 offset:0x8000
	ds_read_b128 v[128:131], v21 offset:0x9000
	v_mfma_f32_32x32x16_bf16 a[32:47], v[132:135], v[140:143], a[32:47]
	v_mfma_f32_32x32x16_bf16 a[48:63], v[132:135], v[144:147], a[48:63]
	ds_read_b128 v[132:135], v18 offset:0x8000
	v_mfma_f32_32x32x16_bf16 a[0:15], v[136:139], v[140:143], a[0:15]
	v_mfma_f32_32x32x16_bf16 a[16:31], v[136:139], v[144:147], a[16:31]
	ds_read_b128 v[136:139], v18 offset:0x9000
	ds_read_b128 v[140:143], v22 offset:0x8000
	ds_read_b128 v[144:147], v22 offset:0x9000
	v_mfma_f32_32x32x16_bf16 a[32:47], v[148:151], v[156:159], a[32:47]
	v_mfma_f32_32x32x16_bf16 a[48:63], v[148:151], v[160:163], a[48:63]
	ds_read_b128 v[148:151], v19 offset:0x8000
	v_mfma_f32_32x32x16_bf16 a[0:15], v[152:155], v[156:159], a[0:15]
	v_mfma_f32_32x32x16_bf16 a[16:31], v[152:155], v[160:163], a[16:31]
	ds_read_b128 v[152:155], v19 offset:0x9000
	ds_read_b128 v[156:159], v23 offset:0x8000
	ds_read_b128 v[160:163], v23 offset:0x9000
	s_waitcnt lgkmcnt(12)
	s_waitcnt lgkmcnt(8)
	s_waitcnt lgkmcnt(4)
	s_nop 0
	v_mfma_f32_32x32x16_bf16 a[32:47], v[100:103], v[108:111], a[32:47]
	s_waitcnt lgkmcnt(0)
	s_waitcnt vmcnt(15)
	ds_write_b128 v164, v[68:71]
	s_waitcnt vmcnt(14)
	ds_write_b128 v164, v[72:75] offset:16384
	s_waitcnt vmcnt(13)
	ds_write_b128 v165, v[76:79]
	s_waitcnt vmcnt(12)
	ds_write_b128 v165, v[80:83] offset:16384
	s_waitcnt vmcnt(11)
	ds_write_b128 v166, v[84:87]
	s_waitcnt vmcnt(10)
	ds_write_b128 v166, v[88:91] offset:16384
	s_waitcnt vmcnt(9)
	ds_write_b128 v167, v[92:95]
	s_waitcnt vmcnt(8)
	ds_write_b128 v167, v[96:99] offset:16384
	s_waitcnt lgkmcnt(0)
	s_barrier
	v_mfma_f32_32x32x16_bf16 a[48:63], v[100:103], v[112:115], a[48:63]
	v_mfma_f32_32x32x16_bf16 a[0:15], v[104:107], v[108:111], a[0:15]
	v_mfma_f32_32x32x16_bf16 a[16:31], v[104:107], v[112:115], a[16:31]
	v_mfma_f32_32x32x16_bf16 a[32:47], v[116:119], v[124:127], a[32:47]
	v_mfma_f32_32x32x16_bf16 a[48:63], v[116:119], v[128:131], a[48:63]
	v_mfma_f32_32x32x16_bf16 a[0:15], v[120:123], v[124:127], a[0:15]
	v_mfma_f32_32x32x16_bf16 a[16:31], v[120:123], v[128:131], a[16:31]
	v_mfma_f32_32x32x16_bf16 a[32:47], v[132:135], v[140:143], a[32:47]
	v_mfma_f32_32x32x16_bf16 a[48:63], v[132:135], v[144:147], a[48:63]
	v_mfma_f32_32x32x16_bf16 a[0:15], v[136:139], v[140:143], a[0:15]
	v_mfma_f32_32x32x16_bf16 a[16:31], v[136:139], v[144:147], a[16:31]
	v_mfma_f32_32x32x16_bf16 a[32:47], v[148:151], v[156:159], a[32:47]
	v_mfma_f32_32x32x16_bf16 a[48:63], v[148:151], v[160:163], a[48:63]
	v_mfma_f32_32x32x16_bf16 a[0:15], v[152:155], v[156:159], a[0:15]
	v_mfma_f32_32x32x16_bf16 a[16:31], v[152:155], v[160:163], a[16:31]
	s_cbranch_scc1 .LBB0_240
	s_waitcnt vmcnt(0)
	s_nop 6
	v_accvgpr_read_b32 v63, a47
	v_or_b32_e32 v66, s1, v66
	v_cmp_lt_i32_e32 vcc, v211, v210
	v_accvgpr_read_b32 v48, a32
	v_add_u32_e32 v66, v66, v67
	v_cndmask_b32_e32 v67, v209, v211, vcc
	v_accvgpr_read_b32 v49, a33
	v_lshlrev_b32_e32 v69, 2, v67
	v_cvt_pk_bf16_f32 v48, v48, v49
	v_accvgpr_read_b32 v50, a34
	v_accvgpr_read_b32 v51, a35
	v_cvt_pk_bf16_f32 v49, v50, v51
	v_accvgpr_read_b32 v52, a36
	v_accvgpr_read_b32 v53, a37
	v_cvt_pk_bf16_f32 v52, v52, v53
	v_accvgpr_read_b32 v54, a38
	v_accvgpr_read_b32 v55, a39
	v_cvt_pk_bf16_f32 v53, v54, v55
	v_accvgpr_read_b32 v56, a40
	v_accvgpr_read_b32 v57, a41
	v_cvt_pk_bf16_f32 v50, v56, v57
	v_accvgpr_read_b32 v58, a42
	v_accvgpr_read_b32 v59, a43
	v_cvt_pk_bf16_f32 v51, v58, v59
	v_accvgpr_read_b32 v60, a44
	v_accvgpr_read_b32 v61, a45
	v_cvt_pk_bf16_f32 v54, v60, v61
	v_accvgpr_read_b32 v62, a46
	v_cvt_pk_bf16_f32 v55, v62, v63
	v_cmp_gt_u32_e32 vcc, 32, v65
	v_and_or_b32 v68, v64, 64, s0
	s_nop 0
	v_cndmask_b32_e32 v56, v48, v50, vcc
	v_cndmask_b32_e32 v57, v49, v51, vcc
	ds_bpermute_b32 v56, v69, v56
	ds_bpermute_b32 v57, v69, v57
	v_cndmask_b32_e32 v58, v52, v54, vcc
	v_cndmask_b32_e32 v59, v53, v55, vcc
	ds_bpermute_b32 v58, v69, v58
	ds_bpermute_b32 v59, v69, v59
	v_ashrrev_i32_e32 v67, 31, v66
	v_readlane_b32 s0, v253, 61
	s_waitcnt lgkmcnt(3)
	v_cndmask_b32_e32 v48, v56, v48, vcc
	s_waitcnt lgkmcnt(2)
	v_cndmask_b32_e32 v49, v57, v49, vcc
	v_cndmask_b32_e32 v50, v50, v56, vcc
	v_cndmask_b32_e32 v51, v51, v57, vcc
	v_lshlrev_b64 v[56:57], 11, v[66:67]
	v_readlane_b32 s1, v253, 62
	v_lshlrev_b32_e32 v192, 1, v68
	s_waitcnt lgkmcnt(1)
	v_cndmask_b32_e32 v52, v58, v52, vcc
	v_lshl_add_u64 v[56:57], s[0:1], 0, v[56:57]
	s_waitcnt lgkmcnt(0)
	v_cndmask_b32_e32 v53, v59, v53, vcc
	v_cndmask_b32_e32 v54, v54, v58, vcc
	v_cndmask_b32_e32 v55, v55, v59, vcc
	v_lshl_add_u64 v[56:57], v[56:57], 0, v[192:193]
	v_and_b32_e32 v58, 32, v64
	v_mov_b32_e32 v59, v193
	v_accvgpr_read_b32 v32, a48
	v_lshl_add_u64 v[56:57], v[56:57], 0, v[58:59]
	v_accvgpr_read_b32 v33, a49
	global_store_dwordx4 v[56:57], v[48:51], off offset:768
	global_store_dwordx4 v[56:57], v[52:55], off offset:784
	v_accvgpr_read_b32 v34, a50
	v_cvt_pk_bf16_f32 v32, v32, v33
	v_accvgpr_read_b32 v35, a51
	v_cvt_pk_bf16_f32 v33, v34, v35
	v_accvgpr_read_b32 v36, a52
	v_accvgpr_read_b32 v37, a53
	v_cvt_pk_bf16_f32 v36, v36, v37
	v_accvgpr_read_b32 v38, a54
	v_accvgpr_read_b32 v39, a55
	v_cvt_pk_bf16_f32 v37, v38, v39
	v_accvgpr_read_b32 v40, a56
	v_accvgpr_read_b32 v41, a57
	v_cvt_pk_bf16_f32 v34, v40, v41
	v_accvgpr_read_b32 v42, a58
	v_accvgpr_read_b32 v43, a59
	v_cvt_pk_bf16_f32 v35, v42, v43
	v_accvgpr_read_b32 v44, a60
	v_accvgpr_read_b32 v45, a61
	v_cvt_pk_bf16_f32 v38, v44, v45
	v_accvgpr_read_b32 v46, a62
	v_cndmask_b32_e32 v41, v32, v34, vcc
	v_accvgpr_read_b32 v47, a63
	ds_bpermute_b32 v41, v69, v41
	v_cvt_pk_bf16_f32 v39, v46, v47
	v_cndmask_b32_e32 v42, v33, v35, vcc
	v_or_b32_e32 v40, 32, v66
	v_cndmask_b32_e32 v43, v36, v38, vcc
	ds_bpermute_b32 v42, v69, v42
	v_cndmask_b32_e32 v44, v37, v39, vcc
	ds_bpermute_b32 v43, v69, v43
	ds_bpermute_b32 v44, v69, v44
	s_waitcnt lgkmcnt(3)
	v_cndmask_b32_e32 v32, v41, v32, vcc
	v_cndmask_b32_e32 v34, v34, v41, vcc
	v_ashrrev_i32_e32 v41, 31, v40
	v_lshlrev_b64 v[40:41], 11, v[40:41]
	v_lshl_add_u64 v[40:41], s[0:1], 0, v[40:41]
	v_accvgpr_read_b32 v31, a15
	v_lshl_add_u64 v[40:41], v[40:41], 0, v[192:193]
	v_accvgpr_read_b32 v16, a0
	s_waitcnt lgkmcnt(2)
	v_cndmask_b32_e32 v33, v42, v33, vcc
	v_cndmask_b32_e32 v35, v35, v42, vcc
	v_lshl_add_u64 v[40:41], v[40:41], 0, v[58:59]
	v_accvgpr_read_b32 v17, a1
	s_waitcnt lgkmcnt(1)
	v_cndmask_b32_e32 v36, v43, v36, vcc
	s_waitcnt lgkmcnt(0)
	v_cndmask_b32_e32 v37, v44, v37, vcc
	v_cndmask_b32_e32 v38, v38, v43, vcc
	v_cndmask_b32_e32 v39, v39, v44, vcc
	global_store_dwordx4 v[40:41], v[32:35], off offset:768
	global_store_dwordx4 v[40:41], v[36:39], off offset:784
	v_accvgpr_read_b32 v18, a2
	v_cvt_pk_bf16_f32 v16, v16, v17
	v_accvgpr_read_b32 v19, a3
	v_cvt_pk_bf16_f32 v17, v18, v19
	v_accvgpr_read_b32 v20, a4
	v_accvgpr_read_b32 v21, a5
	v_cvt_pk_bf16_f32 v20, v20, v21
	v_accvgpr_read_b32 v22, a6
	v_accvgpr_read_b32 v23, a7
	v_cvt_pk_bf16_f32 v21, v22, v23
	v_accvgpr_read_b32 v24, a8
	v_accvgpr_read_b32 v25, a9
	v_cvt_pk_bf16_f32 v18, v24, v25
	v_accvgpr_read_b32 v26, a10
	v_accvgpr_read_b32 v27, a11
	v_cvt_pk_bf16_f32 v19, v26, v27
	v_accvgpr_read_b32 v28, a12
	v_accvgpr_read_b32 v29, a13
	v_cvt_pk_bf16_f32 v22, v28, v29
	v_accvgpr_read_b32 v30, a14
	v_cvt_pk_bf16_f32 v23, v30, v31
	v_cndmask_b32_e32 v24, v16, v18, vcc
	v_cndmask_b32_e32 v25, v17, v19, vcc
	v_cndmask_b32_e32 v26, v20, v22, vcc
	ds_bpermute_b32 v24, v69, v24
	ds_bpermute_b32 v25, v69, v25
	v_cndmask_b32_e32 v27, v21, v23, vcc
	ds_bpermute_b32 v26, v69, v26
	ds_bpermute_b32 v27, v69, v27
	v_accvgpr_read_b32 v0, a16
	s_waitcnt lgkmcnt(3)
	v_cndmask_b32_e32 v16, v24, v16, vcc
	s_waitcnt lgkmcnt(2)
	v_cndmask_b32_e32 v17, v25, v17, vcc
	v_cndmask_b32_e32 v18, v18, v24, vcc
	v_cndmask_b32_e32 v19, v19, v25, vcc
	v_accvgpr_read_b32 v1, a17
	s_waitcnt lgkmcnt(1)
	v_cndmask_b32_e32 v20, v26, v20, vcc
	s_waitcnt lgkmcnt(0)
	v_cndmask_b32_e32 v21, v27, v21, vcc
	v_cndmask_b32_e32 v22, v22, v26, vcc
	v_cndmask_b32_e32 v23, v23, v27, vcc
	global_store_dwordx4 v[56:57], v[16:19], off offset:832
	global_store_dwordx4 v[56:57], v[20:23], off offset:848
	v_accvgpr_read_b32 v2, a18
	v_cvt_pk_bf16_f32 v0, v0, v1
	v_accvgpr_read_b32 v3, a19
	v_cvt_pk_bf16_f32 v1, v2, v3
	v_accvgpr_read_b32 v4, a20
	v_accvgpr_read_b32 v5, a21
	v_cvt_pk_bf16_f32 v4, v4, v5
	v_accvgpr_read_b32 v6, a22
	v_accvgpr_read_b32 v7, a23
	v_cvt_pk_bf16_f32 v5, v6, v7
	v_accvgpr_read_b32 v8, a24
	v_accvgpr_read_b32 v9, a25
	v_cvt_pk_bf16_f32 v2, v8, v9
	v_accvgpr_read_b32 v10, a26
	v_accvgpr_read_b32 v11, a27
	v_cvt_pk_bf16_f32 v3, v10, v11
	v_accvgpr_read_b32 v12, a28
	v_accvgpr_read_b32 v13, a29
	v_cvt_pk_bf16_f32 v6, v12, v13
	v_accvgpr_read_b32 v14, a30
	v_accvgpr_read_b32 v15, a31
	v_cvt_pk_bf16_f32 v7, v14, v15
	v_cndmask_b32_e32 v8, v0, v2, vcc
	v_cndmask_b32_e32 v9, v1, v3, vcc
	v_cndmask_b32_e32 v10, v4, v6, vcc
	ds_bpermute_b32 v8, v69, v8
	ds_bpermute_b32 v9, v69, v9
	v_cndmask_b32_e32 v11, v5, v7, vcc
	ds_bpermute_b32 v10, v69, v10
	ds_bpermute_b32 v11, v69, v11
	s_waitcnt lgkmcnt(3)
	v_cndmask_b32_e32 v0, v8, v0, vcc
	s_waitcnt lgkmcnt(2)
	v_cndmask_b32_e32 v1, v9, v1, vcc
	v_cndmask_b32_e32 v2, v2, v8, vcc
	v_cndmask_b32_e32 v3, v3, v9, vcc
	s_waitcnt lgkmcnt(1)
	v_cndmask_b32_e32 v4, v10, v4, vcc
	s_waitcnt lgkmcnt(0)
	v_cndmask_b32_e32 v5, v11, v5, vcc
	v_cndmask_b32_e32 v6, v6, v10, vcc
	v_cndmask_b32_e32 v7, v7, v11, vcc
	global_store_dwordx4 v[40:41], v[0:3], off offset:832
	global_store_dwordx4 v[40:41], v[4:7], off offset:848
	s_branch .LBB0_236

.LBB0_299:
	s_or_b64 exec, exec, s[0:1]
	v_pk_mul_f32 v[30:31], v[0:1], v[28:29]
	v_mul_f32_e32 v19, v8, v28
	v_sub_f32_e32 v15, v30, v31
	s_waitcnt vmcnt(11)
	v_add_f32_e32 v15, v15, v20
	v_fmac_f32_e32 v19, v0, v29
	v_add_f32_e32 v19, v19, v21
	v_cvt_pk_bf16_f32 v23, v15, v19
	v_add_u32_e32 v11, v11, v50
	v_mov_b64_e32 v[20:21], s[90:91]
	v_mad_i64_i32 v[28:29], s[0:1], v11, s68, v[20:21]
	v_lshl_add_u64 v[28:29], v[28:29], 0, v[192:193]
	v_mov_b32_e32 v11, v193
	v_lshl_add_u64 v[28:29], v[28:29], 0, v[10:11]
	v_add_co_u32_e32 v28, vcc, s92, v28
	s_add_i32 s31, s31, -11
	s_nop 0
	v_addc_co_u32_e32 v29, vcc, 0, v29, vcc
	global_store_dword v[28:29], v23, off offset:1024
	v_mul_f32_e32 v23, v1, v19
	v_fma_f32 v23, v0, v15, -v23
	v_mul_f32_e32 v19, v0, v19
	s_waitcnt vmcnt(11)
	v_add_f32_e32 v23, v23, v36
	v_fmac_f32_e32 v19, v1, v15
	v_add_f32_e32 v15, v19, v37
	v_cvt_pk_bf16_f32 v19, v23, v15
	v_mad_i64_i32 v[26:27], s[0:1], v26, s68, v[20:21]
	v_lshl_add_u64 v[26:27], v[26:27], 0, v[192:193]
	v_lshl_add_u64 v[26:27], v[26:27], 0, v[10:11]
	v_add_co_u32_e32 v26, vcc, s92, v26
	s_cmpk_lg_i32 s31, 0xffdf
	s_nop 0
	v_addc_co_u32_e32 v27, vcc, 0, v27, vcc
	global_store_dword v[26:27], v19, off offset:1024
	v_mul_f32_e32 v19, v1, v15
	v_fma_f32 v19, v0, v23, -v19
	v_mul_f32_e32 v15, v0, v15
	s_waitcnt vmcnt(11)
	v_add_f32_e32 v19, v32, v19
	v_fmac_f32_e32 v15, v1, v23
	v_add_f32_e32 v15, v33, v15
	v_cvt_pk_bf16_f32 v26, v19, v15
	v_mad_i64_i32 v[22:23], s[0:1], v22, s68, v[20:21]
	v_lshl_add_u64 v[22:23], v[22:23], 0, v[192:193]
	v_lshl_add_u64 v[22:23], v[22:23], 0, v[10:11]
	v_add_co_u32_e32 v22, vcc, s92, v22
	s_nop 1
	v_addc_co_u32_e32 v23, vcc, 0, v23, vcc
	global_store_dword v[22:23], v26, off offset:1024
	v_mul_f32_e32 v22, v1, v15
	v_fma_f32 v22, v0, v19, -v22
	v_mul_f32_e32 v19, v1, v19
	s_waitcnt vmcnt(11)
	v_add_f32_e32 v22, v24, v22
	v_fmac_f32_e32 v19, v0, v15
	v_add_f32_e32 v15, v25, v19
	v_cvt_pk_bf16_f32 v23, v22, v15
	v_mad_i64_i32 v[18:19], s[0:1], v18, s68, v[20:21]
	v_lshl_add_u64 v[18:19], v[18:19], 0, v[192:193]
	v_lshl_add_u64 v[18:19], v[18:19], 0, v[10:11]
	v_add_co_u32_e32 v18, vcc, s92, v18
	s_nop 1
	v_addc_co_u32_e32 v19, vcc, 0, v19, vcc
	global_store_dword v[18:19], v23, off offset:1024
	v_mul_f32_e32 v18, v1, v15
	v_fma_f32 v18, v0, v22, -v18
	s_waitcnt vmcnt(11)
	v_add_f32_e32 v16, v16, v18
	v_mul_f32_e32 v18, v1, v22
	v_fmac_f32_e32 v18, v0, v15
	v_add_f32_e32 v18, v17, v18
	v_cvt_pk_bf16_f32 v17, v16, v18
	v_mad_i64_i32 v[14:15], s[0:1], v14, s68, v[20:21]
	v_lshl_add_u64 v[14:15], v[14:15], 0, v[192:193]
	v_lshl_add_u64 v[14:15], v[14:15], 0, v[10:11]
	v_add_co_u32_e32 v14, vcc, s92, v14
	s_nop 1
	v_addc_co_u32_e32 v15, vcc, 0, v15, vcc
	global_store_dword v[14:15], v17, off offset:1024
	v_pk_mul_f32 v[14:15], v[6:7], v[18:19] op_sel_hi:[1,0]
	s_nop 0
	v_pk_fma_f32 v[18:19], v[0:1], v[16:17], v[14:15] neg_lo:[0,0,1] neg_hi:[0,0,1]
	v_pk_fma_f32 v[14:15], v[0:1], v[16:17], v[14:15] op_sel_hi:[1,0,1]
	s_nop 0
	v_mov_b32_e32 v19, v15
	s_waitcnt vmcnt(11)
	v_pk_add_f32 v[30:31], v[12:13], v[18:19]
	v_mov_b32_e32 v14, v9
	s_cbranch_scc0 .LBB0_267
.LBB0_300:
	v_add_u32_e32 v12, s31, v46
	v_add_co_u32_e32 v13, vcc, 8, v14
	v_add_u32_e32 v9, 0x107, v12
	s_xor_b64 s[0:1], vcc, -1
	v_cndmask_b32_e64 v11, v9, v14, s[16:17]
	s_and_saveexec_b64 s[18:19], s[0:1]
	s_xor_b64 s[18:19], exec, s[18:19]
	v_add_u32_e32 v9, v11, v48
	s_or_saveexec_b64 s[18:19], s[18:19]
	v_add_u32_e32 v15, 7, v12
	v_cndmask_b32_e64 v65, v15, v13, s[16:17]
	s_xor_b64 exec, exec, s[18:19]
	v_or_b32_e32 v9, v65, v49
	s_or_b64 exec, exec, s[18:19]
	v_add_u32_e32 v16, v9, v50
	v_ashrrev_i32_e32 v17, 31, v16
	v_lshlrev_b64 v[16:17], 10, v[16:17]
	v_lshl_add_u64 v[16:17], v[4:5], 0, v[16:17]
	global_load_dwordx2 v[42:43], v[16:17], off
	v_add_u32_e32 v9, 1, v14
	v_add_u32_e32 v15, 0x106, v12
	v_cmp_lt_u32_e64 s[28:29], 6, v13
	v_cndmask_b32_e64 v63, v15, v9, s[16:17]
	s_and_saveexec_b64 s[18:19], s[28:29]
	s_xor_b64 s[18:19], exec, s[18:19]
	v_add_u32_e32 v9, v63, v48
	s_or_saveexec_b64 s[18:19], s[18:19]
	v_add_u32_e32 v15, 9, v14
	v_add_u32_e32 v16, 6, v12
	v_cndmask_b32_e64 v64, v16, v15, s[16:17]
	s_xor_b64 exec, exec, s[18:19]
	v_or_b32_e32 v9, v64, v49
	s_or_b64 exec, exec, s[18:19]
	v_add_u32_e32 v16, v9, v50
	v_ashrrev_i32_e32 v17, 31, v16
	v_lshlrev_b64 v[16:17], 10, v[16:17]
	v_lshl_add_u64 v[16:17], v[4:5], 0, v[16:17]
	global_load_dwordx2 v[40:41], v[16:17], off
	v_add_u32_e32 v9, 2, v14
	v_add_u32_e32 v16, 0x105, v12
	v_cmp_lt_u32_e64 s[26:27], 5, v13
	v_cndmask_b32_e64 v61, v16, v9, s[16:17]
	s_and_saveexec_b64 s[18:19], s[26:27]
	s_xor_b64 s[18:19], exec, s[18:19]
	v_add_u32_e32 v9, v61, v48
	s_or_saveexec_b64 s[18:19], s[18:19]
	v_add_u32_e32 v66, 10, v14
	v_add_u32_e32 v16, 5, v12
	v_cndmask_b32_e64 v62, v16, v66, s[16:17]
	s_xor_b64 exec, exec, s[18:19]
	v_or_b32_e32 v9, v62, v49
	s_or_b64 exec, exec, s[18:19]
	v_add_u32_e32 v16, v9, v50
	v_ashrrev_i32_e32 v17, 31, v16
	v_lshlrev_b64 v[16:17], 10, v[16:17]
	v_lshl_add_u64 v[16:17], v[4:5], 0, v[16:17]
	global_load_dwordx2 v[38:39], v[16:17], off
	v_add_u32_e32 v9, 3, v14
	v_add_u32_e32 v16, 0x104, v12
	v_cmp_lt_u32_e64 s[24:25], 4, v13
	v_cndmask_b32_e64 v59, v16, v9, s[16:17]
	s_and_saveexec_b64 s[18:19], s[24:25]
	s_xor_b64 s[18:19], exec, s[18:19]
	v_add_u32_e32 v16, v59, v48
	s_or_saveexec_b64 s[18:19], s[18:19]
	v_add_u32_e32 v9, 11, v14
	v_add_u32_e32 v17, 4, v12
	v_cndmask_b32_e64 v60, v17, v9, s[16:17]
	s_xor_b64 exec, exec, s[18:19]
	v_or_b32_e32 v16, v60, v49
	s_or_b64 exec, exec, s[18:19]
	v_add_u32_e32 v16, v16, v50
	v_ashrrev_i32_e32 v17, 31, v16
	v_lshlrev_b64 v[16:17], 10, v[16:17]
	v_lshl_add_u64 v[16:17], v[4:5], 0, v[16:17]
	global_load_dwordx2 v[34:35], v[16:17], off
	v_add_u32_e32 v16, 4, v14
	v_add_u32_e32 v17, 0x103, v12
	v_cmp_lt_u32_e64 s[22:23], 3, v13
	v_cndmask_b32_e64 v57, v17, v16, s[16:17]
	s_and_saveexec_b64 s[18:19], s[22:23]
	s_xor_b64 s[18:19], exec, s[18:19]
	v_add_u32_e32 v16, v57, v48
	s_or_saveexec_b64 s[18:19], s[18:19]
	v_add_u32_e32 v17, 12, v14
	v_add_u32_e32 v18, 3, v12
	v_cndmask_b32_e64 v58, v18, v17, s[16:17]
	s_xor_b64 exec, exec, s[18:19]
	v_or_b32_e32 v16, v58, v49
	s_or_b64 exec, exec, s[18:19]
	v_add_u32_e32 v16, v16, v50
	v_ashrrev_i32_e32 v17, 31, v16
	v_lshlrev_b64 v[16:17], 10, v[16:17]
	v_lshl_add_u64 v[16:17], v[4:5], 0, v[16:17]
	global_load_dwordx2 v[28:29], v[16:17], off
	v_add_u32_e32 v16, 5, v14
	v_add_u32_e32 v17, 0x102, v12
	v_cmp_lt_u32_e64 s[20:21], 2, v13
	v_cndmask_b32_e64 v55, v17, v16, s[16:17]
	s_and_saveexec_b64 s[18:19], s[20:21]
	s_xor_b64 s[18:19], exec, s[18:19]
	v_add_u32_e32 v16, v55, v48
	s_or_saveexec_b64 s[18:19], s[18:19]
	v_add_u32_e32 v17, 13, v14
	v_add_u32_e32 v18, 2, v12
	v_cndmask_b32_e64 v56, v18, v17, s[16:17]
	s_xor_b64 exec, exec, s[18:19]
	v_or_b32_e32 v16, v56, v49
	s_or_b64 exec, exec, s[18:19]
	v_add_u32_e32 v16, v16, v50
	v_ashrrev_i32_e32 v17, 31, v16
	v_lshlrev_b64 v[16:17], 10, v[16:17]
	v_lshl_add_u64 v[16:17], v[4:5], 0, v[16:17]
	global_load_dwordx2 v[20:21], v[16:17], off
	v_add_u32_e32 v16, 6, v14
	v_add_u32_e32 v17, 0x101, v12
	v_cmp_lt_u32_e64 s[18:19], 1, v13
	v_cndmask_b32_e64 v53, v17, v16, s[16:17]
	s_and_saveexec_b64 s[34:35], s[18:19]
	s_xor_b64 vcc, exec, s[34:35]
	v_add_u32_e32 v16, v53, v48
	s_or_saveexec_b64 vcc, vcc
	v_add_u32_e32 v17, 14, v14
	v_add_u32_e32 v18, 1, v12
	v_cndmask_b32_e64 v54, v18, v17, s[16:17]
	s_xor_b64 exec, exec, vcc
	v_or_b32_e32 v16, v54, v49
	s_or_b64 exec, exec, vcc
	v_add_u32_e32 v14, 7, v14
	v_add_u32_e32 v18, 0x100, v12
	v_cndmask_b32_e64 v14, v18, v14, s[16:17]
	v_add_u32_e32 v14, v14, v48
	v_cmp_eq_u32_e32 vcc, 0, v12
	v_add_u32_e32 v16, v16, v50
	v_ashrrev_i32_e32 v17, 31, v16
	v_cndmask_b32_e32 v14, v14, v51, vcc
	v_add_u32_e32 v26, v14, v50
	v_add_u32_e32 v14, 0xff, v12
	v_cndmask_b32_e64 v13, v14, v13, s[16:17]
	v_ashrrev_i32_e32 v27, 31, v26
	v_add_u32_e32 v22, v13, v52
	v_lshlrev_b64 v[18:19], 10, v[26:27]
	v_ashrrev_i32_e32 v23, 31, v22
	v_add_u32_e32 v13, 0xfe, v12
	v_lshl_add_u64 v[24:25], v[4:5], 0, v[18:19]
	v_lshlrev_b64 v[18:19], 10, v[22:23]
	v_cndmask_b32_e64 v13, v13, v15, s[16:17]
	v_lshl_add_u64 v[68:69], v[4:5], 0, v[18:19]
	v_add_u32_e32 v18, v13, v52
	v_ashrrev_i32_e32 v19, 31, v18
	v_lshlrev_b64 v[16:17], 10, v[16:17]
	v_lshlrev_b64 v[14:15], 10, v[18:19]
	v_add_u32_e32 v12, 0xfd, v12
	v_lshl_add_u64 v[16:17], v[4:5], 0, v[16:17]
	v_lshl_add_u64 v[14:15], v[4:5], 0, v[14:15]
	v_cndmask_b32_e64 v12, v12, v66, s[16:17]
	global_load_dwordx2 v[36:37], v[16:17], off
	global_load_dwordx2 v[32:33], v[24:25], off
	s_nop 0
	global_load_dwordx2 v[24:25], v[68:69], off
	global_load_dwordx2 v[16:17], v[14:15], off
	v_add_u32_e32 v14, v12, v52
	v_ashrrev_i32_e32 v15, 31, v14
	v_lshlrev_b64 v[12:13], 10, v[14:15]
	v_lshl_add_u64 v[12:13], v[4:5], 0, v[12:13]
	global_load_dwordx2 v[12:13], v[12:13], off
	s_and_saveexec_b64 s[34:35], s[0:1]
	s_xor_b64 s[0:1], exec, s[34:35]
	v_add_u32_e32 v15, v11, v48
	s_andn2_saveexec_b64 s[0:1], s[0:1]
	v_or_b32_e32 v15, v65, v49
	s_or_b64 exec, exec, s[0:1]
	v_add_u32_e32 v11, v15, v50
	v_mov_b64_e32 v[66:67], s[90:91]
	v_mad_i64_i32 v[66:67], s[0:1], v11, s68, v[66:67]
	v_lshlrev_b32_e32 v192, 1, v2
	v_lshl_add_u64 v[66:67], v[66:67], 0, v[192:193]
	v_mov_b32_e32 v11, v193
	v_cvt_pk_bf16_f32 v15, v30, v31
	v_lshl_add_u64 v[66:67], v[66:67], 0, v[10:11]
	v_add_co_u32_e32 v66, vcc, 0x7880000, v66
	s_nop 0
	s_nop 0
	v_addc_co_u32_e32 v67, vcc, 0, v67, vcc
	global_store_dword v[66:67], v15, off offset:1024
	s_and_saveexec_b64 s[0:1], s[28:29]
	s_xor_b64 s[0:1], exec, s[0:1]
	v_add_u32_e32 v11, v63, v48
	s_andn2_saveexec_b64 s[0:1], s[0:1]
	v_or_b32_e32 v11, v64, v49
	s_or_b64 exec, exec, s[0:1]
	v_pk_mul_f32 v[64:65], v[6:7], v[30:31] op_sel:[0,1]
	v_add_u32_e32 v11, v11, v50
	v_pk_fma_f32 v[66:67], v[0:1], v[30:31], v[64:65] op_sel_hi:[1,0,1]
	v_pk_fma_f32 v[30:31], v[0:1], v[30:31], v[64:65] op_sel_hi:[1,0,1] neg_lo:[0,0,1] neg_hi:[0,0,1]
	s_nop 0
	v_mov_b32_e32 v31, v67
	s_waitcnt vmcnt(11)
	v_pk_add_f32 v[30:31], v[30:31], v[42:43]
	v_mov_b64_e32 v[42:43], s[90:91]
	v_mad_i64_i32 v[42:43], s[0:1], v11, s68, v[42:43]
	v_lshl_add_u64 v[42:43], v[42:43], 0, v[192:193]
	v_mov_b32_e32 v11, v193
	v_cvt_pk_bf16_f32 v15, v30, v31
	v_lshl_add_u64 v[42:43], v[42:43], 0, v[10:11]
	v_add_co_u32_e32 v42, vcc, 0x7880000, v42
	s_nop 0
	s_nop 0
	v_addc_co_u32_e32 v43, vcc, 0, v43, vcc
	global_store_dword v[42:43], v15, off offset:1024
	s_and_saveexec_b64 s[0:1], s[26:27]
	s_xor_b64 s[0:1], exec, s[0:1]
	v_add_u32_e32 v11, v61, v48
	s_andn2_saveexec_b64 s[0:1], s[0:1]
	v_or_b32_e32 v11, v62, v49
	s_or_b64 exec, exec, s[0:1]
	v_pk_mul_f32 v[42:43], v[6:7], v[30:31] op_sel:[0,1]
	v_add_u32_e32 v11, v11, v50
	v_pk_fma_f32 v[62:63], v[0:1], v[30:31], v[42:43] op_sel_hi:[1,0,1]
	v_pk_fma_f32 v[30:31], v[0:1], v[30:31], v[42:43] op_sel_hi:[1,0,1] neg_lo:[0,0,1] neg_hi:[0,0,1]
	s_nop 0
	v_mov_b32_e32 v31, v63
	s_waitcnt vmcnt(11)
	v_pk_add_f32 v[30:31], v[30:31], v[40:41]
	v_mov_b64_e32 v[40:41], s[90:91]
	v_mad_i64_i32 v[40:41], s[0:1], v11, s68, v[40:41]
	v_lshl_add_u64 v[40:41], v[40:41], 0, v[192:193]
	v_mov_b32_e32 v11, v193
	v_cvt_pk_bf16_f32 v15, v30, v31
	v_lshl_add_u64 v[40:41], v[40:41], 0, v[10:11]
	v_add_co_u32_e32 v40, vcc, 0x7880000, v40
	s_nop 0
	s_nop 0
	v_addc_co_u32_e32 v41, vcc, 0, v41, vcc
	global_store_dword v[40:41], v15, off offset:1024
	s_and_saveexec_b64 s[0:1], s[24:25]
	s_xor_b64 s[0:1], exec, s[0:1]
	v_add_u32_e32 v11, v59, v48
	s_andn2_saveexec_b64 s[0:1], s[0:1]
	v_or_b32_e32 v11, v60, v49
	s_or_b64 exec, exec, s[0:1]
	v_pk_mul_f32 v[40:41], v[6:7], v[30:31] op_sel:[0,1]
	v_add_u32_e32 v11, v11, v50
	v_pk_fma_f32 v[42:43], v[0:1], v[30:31], v[40:41] op_sel_hi:[1,0,1]
	v_pk_fma_f32 v[30:31], v[0:1], v[30:31], v[40:41] op_sel_hi:[1,0,1] neg_lo:[0,0,1] neg_hi:[0,0,1]
	s_nop 0
	v_mov_b32_e32 v31, v43
	s_waitcnt vmcnt(11)
	v_pk_add_f32 v[30:31], v[30:31], v[38:39]
	v_mov_b64_e32 v[38:39], s[90:91]
	v_mad_i64_i32 v[38:39], s[0:1], v11, s68, v[38:39]
	v_lshl_add_u64 v[38:39], v[38:39], 0, v[192:193]
	v_mov_b32_e32 v11, v193
	v_cvt_pk_bf16_f32 v15, v30, v31
	v_lshl_add_u64 v[38:39], v[38:39], 0, v[10:11]
	v_add_co_u32_e32 v38, vcc, 0x7880000, v38
	s_nop 0
	s_nop 0
	v_addc_co_u32_e32 v39, vcc, 0, v39, vcc
	global_store_dword v[38:39], v15, off offset:1024
	s_and_saveexec_b64 s[0:1], s[22:23]
	s_xor_b64 s[0:1], exec, s[0:1]
	v_add_u32_e32 v11, v57, v48
	s_andn2_saveexec_b64 s[0:1], s[0:1]
	v_or_b32_e32 v11, v58, v49
	s_or_b64 exec, exec, s[0:1]
	v_pk_mul_f32 v[38:39], v[6:7], v[30:31] op_sel:[0,1]
	v_add_u32_e32 v11, v11, v50
	v_pk_fma_f32 v[40:41], v[0:1], v[30:31], v[38:39] op_sel_hi:[1,0,1]
	v_pk_fma_f32 v[30:31], v[0:1], v[30:31], v[38:39] op_sel_hi:[1,0,1] neg_lo:[0,0,1] neg_hi:[0,0,1]
	s_nop 0
	v_mov_b32_e32 v31, v41
	s_waitcnt vmcnt(11)
	v_pk_add_f32 v[30:31], v[30:31], v[34:35]
	v_mov_b64_e32 v[34:35], s[90:91]
	v_mad_i64_i32 v[34:35], s[0:1], v11, s68, v[34:35]
	v_lshl_add_u64 v[34:35], v[34:35], 0, v[192:193]
	v_mov_b32_e32 v11, v193
	v_cvt_pk_bf16_f32 v15, v30, v31
	v_lshl_add_u64 v[34:35], v[34:35], 0, v[10:11]
	v_add_co_u32_e32 v34, vcc, 0x7880000, v34
	s_nop 0
	s_nop 0
	v_addc_co_u32_e32 v35, vcc, 0, v35, vcc
	global_store_dword v[34:35], v15, off offset:1024
	s_and_saveexec_b64 s[0:1], s[20:21]
	s_xor_b64 s[0:1], exec, s[0:1]
	v_add_u32_e32 v11, v55, v48
	s_andn2_saveexec_b64 s[0:1], s[0:1]
	v_or_b32_e32 v11, v56, v49
	s_or_b64 exec, exec, s[0:1]
	v_pk_mul_f32 v[34:35], v[6:7], v[30:31] op_sel:[0,1]
	v_add_u32_e32 v11, v11, v50
	v_pk_fma_f32 v[38:39], v[0:1], v[30:31], v[34:35] op_sel_hi:[1,0,1]
	v_pk_fma_f32 v[30:31], v[0:1], v[30:31], v[34:35] op_sel_hi:[1,0,1] neg_lo:[0,0,1] neg_hi:[0,0,1]
	s_nop 0
	v_mov_b32_e32 v31, v39
	s_waitcnt vmcnt(11)
	v_pk_add_f32 v[28:29], v[30:31], v[28:29]
	v_mov_b64_e32 v[30:31], s[90:91]
	v_mad_i64_i32 v[30:31], s[0:1], v11, s68, v[30:31]
	v_lshl_add_u64 v[30:31], v[30:31], 0, v[192:193]
	v_mov_b32_e32 v11, v193
	v_cvt_pk_bf16_f32 v15, v28, v29
	v_lshl_add_u64 v[30:31], v[30:31], 0, v[10:11]
	v_add_co_u32_e32 v30, vcc, 0x7880000, v30
	s_nop 0
	s_nop 0
	v_addc_co_u32_e32 v31, vcc, 0, v31, vcc
	global_store_dword v[30:31], v15, off offset:1024
	s_and_saveexec_b64 s[0:1], s[18:19]
	s_xor_b64 s[0:1], exec, s[0:1]
	v_add_u32_e32 v11, v53, v48
	s_andn2_saveexec_b64 s[0:1], s[0:1]
	s_cbranch_execz .LBB0_299
	v_or_b32_e32 v11, v54, v49
	s_branch .LBB0_299

.LBB0_399:
	s_or_b64 exec, exec, s[2:3]
	s_lshr_b32 s98, s97, 8
	s_lshl_b32 s98, s98, 2
	s_bfe_u32 s99, s97, 0x20001
	s_add_i32 s98, s98, s99
	s_lshl_b32 s98, s98, 6
	s_and_b32 s99, s97, 1
	s_lshl_b32 s99, s99, 5
	s_or_b32 s98, s98, s99
	s_bfe_u32 s99, s97, 0x50003
	s_or_b32 s98, s98, s99
	s_ashr_i32 s1, s98, 6
	s_mul_hi_i32 s0, s1, 0x2aaaaaab
	s_lshr_b32 s2, s0, 31
	s_add_i32 s0, s0, s2
	s_mul_i32 s2, s0, 6
	s_sub_i32 s8, s1, s2
	s_lshl_b32 s1, s98, 1
	s_and_b32 s1, s1, 0x7e
	s_lshl_b32 s2, s0, 13
	s_lshl_b32 s3, s1, 6
	s_or_b32 s2, s3, s2
	v_add_u32_e32 v82, s2, v73
	v_readlane_b32 s2, v254, 3
	v_readlane_b32 s3, v254, 4
	v_lshlrev_b32_e32 v192, 1, v70
	v_sub_u32_e64 v16, s1, 4 clamp
	v_mov_b64_e32 v[0:1], s[2:3]
	s_movk_i32 s2, 0x300
	v_mad_i64_i32 v[0:1], s[2:3], v82, s2, v[0:1]
	s_lshl_b32 s2, s8, 6
	s_ashr_i32 s3, s2, 31
	v_lshl_add_u64 v[0:1], s[2:3], 1, v[0:1]
	v_lshl_add_u64 v[8:9], v[0:1], 0, v[192:193]
	v_add_co_u32_e32 v12, vcc, 0xc000, v8
	global_load_dwordx4 v[0:3], v[8:9], off
	global_load_dwordx4 v[4:7], v[8:9], off offset:64
	v_addc_co_u32_e32 v13, vcc, 0, v9, vcc
	global_load_dwordx4 v[8:11], v[12:13], off
	s_nop 0
	global_load_dwordx4 v[12:15], v[12:13], off offset:64
	v_readfirstlane_b32 s4, v16
	v_sub_u32_e64 v16, s1, 3 clamp
	s_min_u32 s69, s4, 0x78
	v_readfirstlane_b32 s1, v16
	s_min_u32 s33, s1, 0x78
	s_sub_i32 s76, s33, s69
	s_add_i32 s95, s76, 15
	s_add_i32 s94, s76, 8
	s_min_i32 s1, s95, 0
	s_cmp_lt_i32 s76, -7
	s_mov_b64 s[6:7], -1
	s_cbranch_scc0 .LBB0_401
	s_sub_i32 s4, s1, s94
	s_lshl_b32 s78, s4, 5
	s_lshl_b32 s4, s0, 8
	s_ashr_i32 s5, s4, 31
	s_add_u32 s4, s4, s78
	s_addc_u32 s5, s5, 0
	s_add_u32 s4, s4, 0x4000
	s_addc_u32 s5, s5, 0
	s_mov_b64 s[6:7], 0

.LBB0_408:
	s_mul_i32 s1, s0, 0x180
	s_add_i32 s6, s2, s1
	v_readlane_b32 s1, v255, 24
	s_add_i32 s1, s8, s1
	s_mulk_i32 s1, 0x744
	v_readlane_b32 s16, v253, 0
	s_ashr_i32 s7, s6, 31
	s_lshl_b64 s[4:5], s[2:3], 1
	s_add_i32 s76, s76, 16
	s_ashr_i32 s9, s1, 31
	v_readlane_b32 s22, v253, 6
	v_readlane_b32 s23, v253, 7
	s_add_u32 s8, s22, s1
	s_addc_u32 s9, s23, s9
	s_lshr_b32 s98, s97, 8
	s_lshl_b32 s98, s98, 2
	s_bfe_u32 s99, s97, 0x20001
	s_add_i32 s98, s98, s99
	s_lshl_b32 s98, s98, 6
	s_and_b32 s99, s97, 1
	s_lshl_b32 s99, s99, 5
	s_or_b32 s98, s98, s99
	s_bfe_u32 s99, s97, 0x50003
	s_or_b32 s98, s98, s99
	s_and_b32 s1, s98, 63
	s_lshl_b32 s11, s1, 1
	v_sub_u32_e64 v20, s11, 4 clamp
	v_readlane_b32 s26, v253, 10
	v_readfirstlane_b32 s13, v20
	s_min_u32 s83, s13, 0x78
	s_sub_i32 s73, s83, s11
	s_mul_i32 s26, s1, 62
	s_add_u32 s1, s90, s14
	s_addc_u32 s11, s91, s15
	s_lshl_b64 s[12:13], s[6:7], s12
	s_add_u32 s12, s1, s12
	s_addc_u32 s13, s11, s13
	v_mul_u32_u24_e32 v20, s10, v68
	v_lshl_add_u64 v[18:19], v[18:19], 1, s[12:13]
	v_lshlrev_b32_e32 v20, 1, v20
	v_mov_b32_e32 v21, v193
	v_lshl_add_u64 v[18:19], v[18:19], 0, v[20:21]
	v_mov_b32_e32 v85, v193
	s_lshl_b32 s1, s10, 5
	v_lshl_add_u64 v[18:19], v[18:19], 0, v[84:85]
	s_mul_i32 s78, s10, 0x60
	s_sub_u32 s10, 0, s1
	v_lshl_add_u64 v[20:21], v[18:19], 0, s[78:79]
	s_subb_u32 s11, 0, 0
	global_load_dwordx2 v[106:107], v[20:21], off
	global_load_dwordx2 v[108:109], v[20:21], off offset:32
	v_lshl_add_u64 v[20:21], v[20:21], 0, s[10:11]
	global_load_dwordx2 v[110:111], v[20:21], off
	global_load_dwordx2 v[112:113], v[20:21], off offset:32
	v_lshl_add_u64 v[20:21], v[20:21], 0, s[10:11]
	v_readlane_b32 s10, v254, 15
	v_readlane_b32 s11, v254, 16
	global_load_dwordx2 v[114:115], v[20:21], off
	global_load_dwordx2 v[116:117], v[20:21], off offset:32
	global_load_dwordx2 v[118:119], v[18:19], off
	global_load_dwordx2 v[120:121], v[18:19], off offset:32
	v_lshl_add_u64 v[16:17], v[16:17], 0, v[68:69]
	v_mov_b64_e32 v[18:19], s[10:11]
	s_movk_i32 s1, 0x300
	v_mad_u64_u32 v[18:19], s[10:11], v16, s1, v[18:19]
	v_mov_b32_e32 v16, v19
	v_mad_u64_u32 v[16:17], s[10:11], v17, s1, v[16:17]
	v_mov_b32_e32 v19, v16
	v_lshl_add_u64 v[16:17], v[18:19], 0, s[4:5]
	s_movk_i32 s16, 0x3000
	v_lshl_add_u64 v[16:17], v[16:17], 0, v[192:193]
	v_add_co_u32_e32 v18, vcc, s16, v16
	s_lshl_b32 s1, s0, 8
	s_nop 0
	v_addc_co_u32_e32 v19, vcc, 0, v17, vcc
	global_load_dwordx4 v[138:141], v[18:19], off offset:64
	global_load_dwordx4 v[150:153], v[18:19], off
	global_load_dwordx4 v[142:145], v[16:17], off offset:64
	global_load_dwordx4 v[146:149], v[16:17], off
	v_lshl_add_u64 v[86:87], v[78:79], 0, s[4:5]
	s_ashr_i32 s4, s1, 31
	s_add_u32 s34, s1, 0x4000
	s_addc_u32 s35, s4, 0
	s_ashr_i32 s1, s0, 31
	v_add_u32_e32 v16, v83, v72
	s_lshl_b64 s[10:11], s[0:1], 13
	v_cmp_ge_u32_e32 vcc, v16, v81
	v_cmp_lt_u32_e64 s[0:1], v16, v93
	v_or_b32_e32 v17, 1, v16
	s_and_b64 s[12:13], vcc, s[0:1]
	v_cmp_ge_u32_e32 vcc, v17, v81
	v_cmp_lt_u32_e64 s[0:1], v17, v93
	v_or_b32_e32 v17, 2, v16
	v_readlane_b32 s17, v253, 1
	s_and_b64 s[14:15], vcc, s[0:1]
	v_cmp_ge_u32_e32 vcc, v17, v81
	v_cmp_lt_u32_e64 s[0:1], v17, v93
	v_or_b32_e32 v17, 3, v16
	v_readlane_b32 s18, v253, 2
	v_readlane_b32 s19, v253, 3
	s_and_b64 s[16:17], vcc, s[0:1]
	v_cmp_ge_u32_e32 vcc, v17, v81
	v_cmp_lt_u32_e64 s[0:1], v17, v93
	v_add_u32_e32 v17, 16, v16
	v_readlane_b32 s20, v253, 4
	v_readlane_b32 s21, v253, 5
	s_and_b64 s[18:19], vcc, s[0:1]
	v_cmp_ge_u32_e32 vcc, v17, v81
	v_cmp_lt_u32_e64 s[0:1], v17, v93
	v_add_u32_e32 v17, 17, v16
	s_and_b64 s[20:21], vcc, s[0:1]
	v_cmp_ge_u32_e32 vcc, v17, v81
	v_cmp_lt_u32_e64 s[0:1], v17, v93
	v_add_u32_e32 v17, 18, v16
	v_readlane_b32 s24, v253, 8
	v_readlane_b32 s25, v253, 9
	s_and_b64 s[22:23], vcc, s[0:1]
	v_cmp_ge_u32_e32 vcc, v17, v81
	v_cmp_lt_u32_e64 s[0:1], v17, v93
	v_add_u32_e32 v16, 19, v16
	s_and_b64 s[24:25], vcc, s[0:1]
	v_cmp_ge_u32_e32 vcc, v16, v81
	v_cmp_lt_u32_e64 s[0:1], v16, v93
	v_add_u32_e32 v16, v71, v83
	v_med3_i32 v16, v16, -15, 15
	v_subrev_u32_e32 v94, s26, v16
	v_add_u32_e32 v16, 1, v71
	v_add_u32_e32 v16, v16, v83
	v_med3_i32 v16, v16, -15, 15
	v_subrev_u32_e32 v95, s26, v16
	v_add_u32_e32 v16, 2, v71
	v_add_u32_e32 v16, v16, v83
	v_med3_i32 v16, v16, -15, 15
	v_subrev_u32_e32 v96, s26, v16
	v_add_u32_e32 v16, 3, v71
	v_add_u32_e32 v16, v16, v83
	v_med3_i32 v16, v16, -15, 15
	v_subrev_u32_e32 v97, s26, v16
	v_add_u32_e32 v16, 16, v71
	v_add_u32_e32 v16, v16, v83
	v_med3_i32 v16, v16, -15, 15
	v_subrev_u32_e32 v98, s26, v16
	v_add_u32_e32 v16, 17, v71
	v_add_u32_e32 v16, v16, v83
	v_med3_i32 v16, v16, -15, 15
	v_subrev_u32_e32 v99, s26, v16
	v_add_u32_e32 v16, 18, v71
	v_add_u32_e32 v16, v16, v83
	v_med3_i32 v16, v16, -15, 15
	v_subrev_u32_e32 v100, s26, v16
	v_add_u32_e32 v16, 19, v71
	v_add_u32_e32 v16, v16, v83
	v_mov_b32_e32 v192, v193
	v_med3_i32 v16, v16, -15, 15
	v_mov_b32_e32 v194, v193
	v_mov_b32_e32 v195, v193
	v_accvgpr_write_b32 a16, v192
	v_accvgpr_write_b32 a20, v192
	v_accvgpr_write_b32 a24, v192
	v_accvgpr_write_b32 a28, v192
	v_accvgpr_write_b32 a0, v192
	v_accvgpr_write_b32 a4, v192
	v_accvgpr_write_b32 a8, v192
	v_accvgpr_write_b32 a12, v192
	v_mov_b32_e32 v88, 0
	s_mul_i32 s81, s83, 31
	s_movk_i32 s93, 0x3000
	s_and_b64 s[0:1], vcc, s[0:1]
	v_subrev_u32_e32 v101, s26, v16
	v_accvgpr_write_b32 a17, v193
	v_accvgpr_write_b32 a18, v194
	v_accvgpr_write_b32 a19, v195
	v_accvgpr_write_b32 a21, v193
	v_accvgpr_write_b32 a22, v194
	v_accvgpr_write_b32 a23, v195
	v_accvgpr_write_b32 a25, v193
	v_accvgpr_write_b32 a26, v194
	v_accvgpr_write_b32 a27, v195
	v_accvgpr_write_b32 a29, v193
	v_accvgpr_write_b32 a30, v194
	v_accvgpr_write_b32 a31, v195
	v_accvgpr_write_b32 a1, v193
	v_accvgpr_write_b32 a2, v194
	v_accvgpr_write_b32 a3, v195
	v_accvgpr_write_b32 a5, v193
	v_accvgpr_write_b32 a6, v194
	v_accvgpr_write_b32 a7, v195
	v_accvgpr_write_b32 a9, v193
	v_accvgpr_write_b32 a10, v194
	v_accvgpr_write_b32 a11, v195
	v_accvgpr_write_b32 a13, v193
	v_accvgpr_write_b32 a14, v194
	v_accvgpr_write_b32 a15, v195
	v_mov_b32_e32 v102, 0xf149f2ca
	v_mov_b32_e32 v104, 0xf149f2ca
	v_mov_b32_e32 v89, v88
	v_readlane_b32 s27, v253, 11
	v_readlane_b32 s28, v253, 12
	v_readlane_b32 s29, v253, 13
	v_readlane_b32 s30, v253, 14
	v_readlane_b32 s31, v253, 15
	v_lshlrev_b32_e32 v232, 11, v246
	v_add_u32_e32 v232, 0x10000, v232
	v_lshlrev_b32_e32 v233, 2, v247
	v_add_u32_e32 v234, v232, v233
	global_load_dword v180, v233, s[8:9] offset:0
	global_load_dword v181, v233, s[8:9] offset:256
	global_load_dword v182, v233, s[8:9] offset:512
	global_load_dword v183, v233, s[8:9] offset:768
	global_load_dword v184, v233, s[8:9] offset:1024
	global_load_dword v185, v233, s[8:9] offset:1280
	global_load_dword v186, v233, s[8:9] offset:1536
	v_cmp_gt_u32_e32 vcc, 17, v247
	s_and_saveexec_b64 s[98:99], vcc
	global_load_dword v187, v233, s[8:9] offset:1792
	s_mov_b64 exec, s[98:99]
	s_waitcnt vmcnt(0)
	ds_write_b32 v234, v180 offset:0
	ds_write_b32 v234, v181 offset:256
	ds_write_b32 v234, v182 offset:512
	ds_write_b32 v234, v183 offset:768
	ds_write_b32 v234, v184 offset:1024
	ds_write_b32 v234, v185 offset:1280
	ds_write_b32 v234, v186 offset:1536
	s_and_saveexec_b64 s[98:99], vcc
	ds_write_b32 v234, v187 offset:1792
	s_mov_b64 exec, s[98:99]
	s_waitcnt lgkmcnt(0)

.LBB0_416:
	s_andn2_b64 vcc, exec, s[28:29]
	s_cbranch_vccnz .LBB0_458
	s_cmp_gt_u32 s71, 7
	s_cbranch_scc1 .LBB0_437
	s_waitcnt vmcnt(12)
	v_mfma_f32_16x16x32_bf16 a[0:3], v[146:149], v[0:3], 0
	s_add_i32 s4, s73, s71
	s_cmp_lt_i32 s4, -7
	v_mfma_f32_16x16x32_bf16 a[4:7], v[150:153], v[0:3], 0
	v_mfma_f32_16x16x32_bf16 a[0:3], v[142:145], v[4:7], a[0:3]
	v_mfma_f32_16x16x32_bf16 a[4:7], v[138:141], v[4:7], a[4:7]
	s_cbranch_scc1 .LBB0_436
	s_nop 5
	s_add_i32 s98, s81, 0xe8
	v_add_u32_e32 v180, s98, v94
	v_add_u32_e32 v181, s98, v95
	v_add_u32_e32 v182, s98, v96
	v_add_u32_e32 v183, s98, v97
	v_add_u32_e32 v184, s98, v98
	v_add_u32_e32 v185, s98, v99
	v_add_u32_e32 v186, s98, v100
	v_add_u32_e32 v187, s98, v101
	v_lshl_add_u32 v180, v180, 2, v232
	v_lshl_add_u32 v181, v181, 2, v232
	v_lshl_add_u32 v182, v182, 2, v232
	v_lshl_add_u32 v183, v183, 2, v232
	v_lshl_add_u32 v184, v184, 2, v232
	v_lshl_add_u32 v185, v185, 2, v232
	v_lshl_add_u32 v186, v186, 2, v232
	v_lshl_add_u32 v187, v187, 2, v232
	ds_read_b32 v180, v180
	ds_read_b32 v181, v181
	ds_read_b32 v182, v182
	ds_read_b32 v183, v183
	ds_read_b32 v184, v184
	ds_read_b32 v185, v185
	ds_read_b32 v186, v186
	ds_read_b32 v187, v187
	v_accvgpr_read_b32 v240, a0
	v_accvgpr_read_b32 v241, a1
	v_accvgpr_read_b32 v242, a2
	v_accvgpr_read_b32 v243, a3
	v_accvgpr_read_b32 v188, a4
	v_accvgpr_read_b32 v189, a5
	v_accvgpr_read_b32 v190, a6
	v_accvgpr_read_b32 v191, a7
	v_mov_b32_e32 v231, 0xf149f2ca
	s_waitcnt lgkmcnt(0)
	v_add_f32_e32 v180, v240, v180
	v_add_f32_e32 v181, v241, v181
	v_add_f32_e32 v182, v242, v182
	v_add_f32_e32 v183, v243, v183
	v_add_f32_e32 v184, v188, v184
	v_add_f32_e32 v185, v189, v185
	v_add_f32_e32 v186, v190, v186
	v_add_f32_e32 v187, v191, v187
	v_cndmask_b32_e64 v180, v231, v180, s[12:13]
	v_cndmask_b32_e64 v181, v231, v181, s[14:15]
	v_cndmask_b32_e64 v182, v231, v182, s[16:17]
	v_cndmask_b32_e64 v183, v231, v183, s[18:19]
	v_cndmask_b32_e64 v184, v231, v184, s[20:21]
	v_cndmask_b32_e64 v185, v231, v185, s[22:23]
	v_cndmask_b32_e64 v186, v231, v186, s[24:25]
	v_cndmask_b32_e64 v187, v231, v187, s[0:1]
	v_accvgpr_write_b32 a0, v180
	v_accvgpr_write_b32 a1, v181
	v_accvgpr_write_b32 a2, v182
	v_accvgpr_write_b32 a3, v183
	v_accvgpr_write_b32 a4, v184
	v_accvgpr_write_b32 a5, v185
	v_accvgpr_write_b32 a6, v186
	v_accvgpr_write_b32 a7, v187

.LBB0_438:
	s_waitcnt vmcnt(12)
	v_mfma_f32_16x16x32_bf16 a[16:19], v[146:149], v[8:11], 0
	s_add_i32 s4, s73, s71
	s_add_i32 s4, s4, -1
	s_cmp_lt_i32 s4, -7
	v_mfma_f32_16x16x32_bf16 a[20:23], v[150:153], v[8:11], 0
	v_mfma_f32_16x16x32_bf16 a[16:19], v[142:145], v[12:15], a[16:19]
	v_mfma_f32_16x16x32_bf16 a[20:23], v[138:141], v[12:15], a[20:23]
	s_cbranch_scc1 .LBB0_456
	s_nop 5
	s_add_i32 s98, s81, 0xc9
	v_add_u32_e32 v180, s98, v94
	v_add_u32_e32 v181, s98, v95
	v_add_u32_e32 v182, s98, v96
	v_add_u32_e32 v183, s98, v97
	v_add_u32_e32 v184, s98, v98
	v_add_u32_e32 v185, s98, v99
	v_add_u32_e32 v186, s98, v100
	v_add_u32_e32 v187, s98, v101
	v_lshl_add_u32 v180, v180, 2, v232
	v_lshl_add_u32 v181, v181, 2, v232
	v_lshl_add_u32 v182, v182, 2, v232
	v_lshl_add_u32 v183, v183, 2, v232
	v_lshl_add_u32 v184, v184, 2, v232
	v_lshl_add_u32 v185, v185, 2, v232
	v_lshl_add_u32 v186, v186, 2, v232
	v_lshl_add_u32 v187, v187, 2, v232
	ds_read_b32 v180, v180
	ds_read_b32 v181, v181
	ds_read_b32 v182, v182
	ds_read_b32 v183, v183
	ds_read_b32 v184, v184
	ds_read_b32 v185, v185
	ds_read_b32 v186, v186
	ds_read_b32 v187, v187
	v_accvgpr_read_b32 v240, a16
	v_accvgpr_read_b32 v241, a17
	v_accvgpr_read_b32 v242, a18
	v_accvgpr_read_b32 v243, a19
	v_accvgpr_read_b32 v188, a20
	v_accvgpr_read_b32 v189, a21
	v_accvgpr_read_b32 v190, a22
	v_accvgpr_read_b32 v191, a23
	v_mov_b32_e32 v231, 0xf149f2ca
	s_waitcnt lgkmcnt(0)
	v_add_f32_e32 v180, v240, v180
	v_add_f32_e32 v181, v241, v181
	v_add_f32_e32 v182, v242, v182
	v_add_f32_e32 v183, v243, v183
	v_add_f32_e32 v184, v188, v184
	v_add_f32_e32 v185, v189, v185
	v_add_f32_e32 v186, v190, v186
	v_add_f32_e32 v187, v191, v187
	v_cndmask_b32_e64 v180, v231, v180, s[12:13]
	v_cndmask_b32_e64 v181, v231, v181, s[14:15]
	v_cndmask_b32_e64 v182, v231, v182, s[16:17]
	v_cndmask_b32_e64 v183, v231, v183, s[18:19]
	v_cndmask_b32_e64 v184, v231, v184, s[20:21]
	v_cndmask_b32_e64 v185, v231, v185, s[22:23]
	v_cndmask_b32_e64 v186, v231, v186, s[24:25]
	v_cndmask_b32_e64 v187, v231, v187, s[0:1]
	v_accvgpr_write_b32 a16, v180
	v_accvgpr_write_b32 a17, v181
	v_accvgpr_write_b32 a18, v182
	v_accvgpr_write_b32 a19, v183
	v_accvgpr_write_b32 a20, v184
	v_accvgpr_write_b32 a21, v185
	v_accvgpr_write_b32 a22, v186
	v_accvgpr_write_b32 a23, v187

.LBB0_466:
	s_andn2_b64 vcc, exec, s[28:29]
	s_cbranch_vccnz .LBB0_509
	s_cmp_gt_u32 s71, 7
	s_cbranch_scc1 .LBB0_488
	s_waitcnt vmcnt(23)
	v_mfma_f32_16x16x32_bf16 a[0:3], v[16:19], v[0:3], 0
	s_add_i32 s4, s73, s71
	s_add_i32 s4, s4, 1
	s_cmp_lt_i32 s4, -7
	s_waitcnt vmcnt(21)
	v_mfma_f32_16x16x32_bf16 a[4:7], v[28:31], v[0:3], 0
	v_mfma_f32_16x16x32_bf16 a[0:3], v[20:23], v[4:7], a[0:3]
	s_waitcnt vmcnt(20)
	v_mfma_f32_16x16x32_bf16 a[4:7], v[24:27], v[4:7], a[4:7]
	s_cbranch_scc1 .LBB0_486
	s_nop 4
	s_add_i32 s98, s81, 0x107
	v_add_u32_e32 v180, s98, v94
	v_add_u32_e32 v181, s98, v95
	v_add_u32_e32 v182, s98, v96
	v_add_u32_e32 v183, s98, v97
	v_add_u32_e32 v184, s98, v98
	v_add_u32_e32 v185, s98, v99
	v_add_u32_e32 v186, s98, v100
	v_add_u32_e32 v187, s98, v101
	v_lshl_add_u32 v180, v180, 2, v232
	v_lshl_add_u32 v181, v181, 2, v232
	v_lshl_add_u32 v182, v182, 2, v232
	v_lshl_add_u32 v183, v183, 2, v232
	v_lshl_add_u32 v184, v184, 2, v232
	v_lshl_add_u32 v185, v185, 2, v232
	v_lshl_add_u32 v186, v186, 2, v232
	v_lshl_add_u32 v187, v187, 2, v232
	ds_read_b32 v180, v180
	ds_read_b32 v181, v181
	ds_read_b32 v182, v182
	ds_read_b32 v183, v183
	ds_read_b32 v184, v184
	ds_read_b32 v185, v185
	ds_read_b32 v186, v186
	ds_read_b32 v187, v187
	v_accvgpr_read_b32 v240, a0
	v_accvgpr_read_b32 v241, a1
	v_accvgpr_read_b32 v242, a2
	v_accvgpr_read_b32 v243, a3
	v_accvgpr_read_b32 v188, a4
	v_accvgpr_read_b32 v189, a5
	v_accvgpr_read_b32 v190, a6
	v_accvgpr_read_b32 v191, a7
	v_mov_b32_e32 v231, 0xf149f2ca
	s_waitcnt lgkmcnt(0)
	v_add_f32_e32 v180, v240, v180
	v_add_f32_e32 v181, v241, v181
	v_add_f32_e32 v182, v242, v182
	v_add_f32_e32 v183, v243, v183
	v_add_f32_e32 v184, v188, v184
	v_add_f32_e32 v185, v189, v185
	v_add_f32_e32 v186, v190, v186
	v_add_f32_e32 v187, v191, v187
	v_cndmask_b32_e64 v180, v231, v180, s[12:13]
	v_cndmask_b32_e64 v181, v231, v181, s[14:15]
	v_cndmask_b32_e64 v182, v231, v182, s[16:17]
	v_cndmask_b32_e64 v183, v231, v183, s[18:19]
	v_cndmask_b32_e64 v184, v231, v184, s[20:21]
	v_cndmask_b32_e64 v185, v231, v185, s[22:23]
	v_cndmask_b32_e64 v186, v231, v186, s[24:25]
	v_cndmask_b32_e64 v187, v231, v187, s[0:1]
	v_accvgpr_write_b32 a0, v180
	v_accvgpr_write_b32 a1, v181
	v_accvgpr_write_b32 a2, v182
	v_accvgpr_write_b32 a3, v183
	v_accvgpr_write_b32 a4, v184
	v_accvgpr_write_b32 a5, v185
	v_accvgpr_write_b32 a6, v186
	v_accvgpr_write_b32 a7, v187

.LBB0_489:
	s_waitcnt vmcnt(23)
	v_mfma_f32_16x16x32_bf16 a[0:3], v[16:19], v[8:11], 0
	s_add_i32 s4, s73, s71
	s_cmp_lt_i32 s4, -7
	s_waitcnt vmcnt(21)
	v_mfma_f32_16x16x32_bf16 a[4:7], v[28:31], v[8:11], 0
	v_mfma_f32_16x16x32_bf16 a[0:3], v[20:23], v[12:15], a[0:3]
	s_waitcnt vmcnt(20)
	v_mfma_f32_16x16x32_bf16 a[4:7], v[24:27], v[12:15], a[4:7]
	s_cbranch_scc1 .LBB0_507
	s_nop 4
	s_add_i32 s98, s81, 0xe8
	v_add_u32_e32 v180, s98, v94
	v_add_u32_e32 v181, s98, v95
	v_add_u32_e32 v182, s98, v96
	v_add_u32_e32 v183, s98, v97
	v_add_u32_e32 v184, s98, v98
	v_add_u32_e32 v185, s98, v99
	v_add_u32_e32 v186, s98, v100
	v_add_u32_e32 v187, s98, v101
	v_lshl_add_u32 v180, v180, 2, v232
	v_lshl_add_u32 v181, v181, 2, v232
	v_lshl_add_u32 v182, v182, 2, v232
	v_lshl_add_u32 v183, v183, 2, v232
	v_lshl_add_u32 v184, v184, 2, v232
	v_lshl_add_u32 v185, v185, 2, v232
	v_lshl_add_u32 v186, v186, 2, v232
	v_lshl_add_u32 v187, v187, 2, v232
	ds_read_b32 v180, v180
	ds_read_b32 v181, v181
	ds_read_b32 v182, v182
	ds_read_b32 v183, v183
	ds_read_b32 v184, v184
	ds_read_b32 v185, v185
	ds_read_b32 v186, v186
	ds_read_b32 v187, v187
	v_accvgpr_read_b32 v240, a0
	v_accvgpr_read_b32 v241, a1
	v_accvgpr_read_b32 v242, a2
	v_accvgpr_read_b32 v243, a3
	v_accvgpr_read_b32 v188, a4
	v_accvgpr_read_b32 v189, a5
	v_accvgpr_read_b32 v190, a6
	v_accvgpr_read_b32 v191, a7
	v_mov_b32_e32 v231, 0xf149f2ca
	s_waitcnt lgkmcnt(0)
	v_add_f32_e32 v180, v240, v180
	v_add_f32_e32 v181, v241, v181
	v_add_f32_e32 v182, v242, v182
	v_add_f32_e32 v183, v243, v183
	v_add_f32_e32 v184, v188, v184
	v_add_f32_e32 v185, v189, v185
	v_add_f32_e32 v186, v190, v186
	v_add_f32_e32 v187, v191, v187
	v_cndmask_b32_e64 v180, v231, v180, s[12:13]
	v_cndmask_b32_e64 v181, v231, v181, s[14:15]
	v_cndmask_b32_e64 v182, v231, v182, s[16:17]
	v_cndmask_b32_e64 v183, v231, v183, s[18:19]
	v_cndmask_b32_e64 v184, v231, v184, s[20:21]
	v_cndmask_b32_e64 v185, v231, v185, s[22:23]
	v_cndmask_b32_e64 v186, v231, v186, s[24:25]
	v_cndmask_b32_e64 v187, v231, v187, s[0:1]
	v_accvgpr_write_b32 a0, v180
	v_accvgpr_write_b32 a1, v181
	v_accvgpr_write_b32 a2, v182
	v_accvgpr_write_b32 a3, v183
	v_accvgpr_write_b32 a4, v184
	v_accvgpr_write_b32 a5, v185
	v_accvgpr_write_b32 a6, v186
	v_accvgpr_write_b32 a7, v187

	.amdhsa_kernel _Z14fwd_megakernel6ParamsPj
		.amdhsa_group_segment_fixed_size 73728
		.amdhsa_private_segment_fixed_size 0
		.amdhsa_kernarg_size 488
		.amdhsa_user_sgpr_count 2
		.amdhsa_user_sgpr_dispatch_ptr 0
		.amdhsa_user_sgpr_queue_ptr 0
		.amdhsa_user_sgpr_kernarg_segment_ptr 1
		.amdhsa_user_sgpr_dispatch_id 0
		.amdhsa_user_sgpr_kernarg_preload_length 0
		.amdhsa_user_sgpr_kernarg_preload_offset 0
		.amdhsa_user_sgpr_private_segment_size 0
		.amdhsa_uses_dynamic_stack 0
		.amdhsa_enable_private_segment 0
		.amdhsa_system_sgpr_workgroup_id_x 1
		.amdhsa_system_sgpr_workgroup_id_y 0
		.amdhsa_system_sgpr_workgroup_id_z 0
		.amdhsa_system_sgpr_workgroup_info 0
		.amdhsa_system_vgpr_workitem_id 2
		.amdhsa_next_free_vgpr 467
		.amdhsa_next_free_sgpr 100
		.amdhsa_accum_offset 256
		.amdhsa_reserve_vcc 1
		.amdhsa_float_round_mode_32 0
		.amdhsa_float_round_mode_16_64 0
		.amdhsa_float_denorm_mode_32 3
		.amdhsa_float_denorm_mode_16_64 3
		.amdhsa_dx10_clamp 1
		.amdhsa_ieee_mode 1
		.amdhsa_fp16_overflow 0
		.amdhsa_tg_split 0
		.amdhsa_exception_fp_ieee_invalid_op 0
		.amdhsa_exception_fp_denorm_src 0
		.amdhsa_exception_fp_ieee_div_zero 0
		.amdhsa_exception_fp_ieee_overflow 0
		.amdhsa_exception_fp_ieee_underflow 0
		.amdhsa_exception_fp_ieee_inexact 0
		.amdhsa_exception_int_div_zero 0
	.end_amdhsa_kernel

amdhsa.kernels:
  - .agpr_count:     211
    .args:
      - .offset:         0
        .size:           224
        .value_kind:     by_value
      - .address_space:  global
        .offset:         224
        .size:           8
        .value_kind:     global_buffer
      - .offset:         232
        .size:           4
        .value_kind:     hidden_block_count_x
      - .offset:         236
        .size:           4
        .value_kind:     hidden_block_count_y
      - .offset:         240
        .size:           4
        .value_kind:     hidden_block_count_z
      - .offset:         244
        .size:           2
        .value_kind:     hidden_group_size_x
      - .offset:         246
        .size:           2
        .value_kind:     hidden_group_size_y
      - .offset:         248
        .size:           2
        .value_kind:     hidden_group_size_z
      - .offset:         250
        .size:           2
        .value_kind:     hidden_remainder_x
      - .offset:         252
        .size:           2
        .value_kind:     hidden_remainder_y
      - .offset:         254
        .size:           2
        .value_kind:     hidden_remainder_z
      - .offset:         272
        .size:           8
        .value_kind:     hidden_global_offset_x
      - .offset:         280
        .size:           8
        .value_kind:     hidden_global_offset_y
      - .offset:         288
        .size:           8
        .value_kind:     hidden_global_offset_z
      - .offset:         296
        .size:           2
        .value_kind:     hidden_grid_dims
      - .offset:         320
        .size:           8
        .value_kind:     hidden_multigrid_sync_arg
    .group_segment_fixed_size: 73728
    .kernarg_segment_align: 8
    .kernarg_segment_size: 488
    .language:       OpenCL C
    .language_version:
      - 2
      - 0
    .max_flat_workgroup_size: 256
    .name:           _Z14fwd_megakernel6ParamsPj
    .private_segment_fixed_size: 0
    .sgpr_count:     106
    .sgpr_spill_count: 156
    .symbol:         _Z14fwd_megakernel6ParamsPj.kd
    .uniform_work_group_size: 1
    .uses_dynamic_stack: false
    .vgpr_count:     467
    .vgpr_spill_count: 0
    .wavefront_size: 64
